# baseline (speedup 1.0000x reference)
; #define LAS __attribute__((address_space(3)))
; __device__ __forceinline__ unsigned xb_ld(unsigned* p)              { return __hip_atomic_load(p, __ATOMIC_RELAXED, __HIP_MEMORY_SCOPE_AGENT); }
; __device__ __forceinline__ void xcd_barrier_complete(unsigned* bar, unsigned x, unsigned& nloc, unsigned& nx) {
;     const unsigned G = gridDim.x * gridDim.y * gridDim.z;
;     unsigned sum, cnt, mine, sp = 0u;
;     for (;;) {
;         sum = 0u; cnt = 0u; mine = 0u;
; #pragma unroll
;         for (unsigned j = 0; j < 16; ++j) { const unsigned c = xb_ld(&bar[XB_XCNT(j)]); sum += c; cnt += (c > 0u) ? 1u : 0u; mine = (j == x) ? c : mine; }
; __global__ void __launch_bounds__(512, 2) fwd_megakernel(Params p) {
;     ...
;     XcdBarrier xbar = xcd_barrier_post((unsigned*)(p.ws + WS_BAR), (volatile LAS unsigned*)(lds + LDS_BARST));
;     unsigned char* ws = p.ws;
;     bf16_t* H = (bf16_t*)(ws + WS_H); bf16_t* PROJ = (bf16_t*)(ws + WS_PROJ); bf16_t* AP = (bf16_t*)(ws + WS_AP); float* LSE = (float*)(ws + WS_LSE);
;     bf16_t* ST = (bf16_t*)(ws + WS_ST); f32x2* TA = (f32x2*)(ws + WS_TA); f32x2* TR = (f32x2*)(ws + WS_TR);
;     bf16_t* WGU = (bf16_t*)(ws + WS_WF + WF_GU); bf16_t* WDN = (bf16_t*)(ws + WS_WF + WF_DN); bf16_t* WIN = (bf16_t*)(ws + WS_WM + WM_IN); bf16_t* WOUT = (bf16_t*)(ws + WS_WM + WM_OUT);
;     float* SS = (float*)(ws + WS_SS);
.LBB0_15:
	s_add_u32 s76, s98, 0x6480000
	s_addc_u32 s77, s99, 0
	s_add_u32 s78, s98, 0xc480000
	s_addc_u32 s79, s99, 0
	s_add_u32 s80, s98, 0x21480000
	s_addc_u32 s81, s99, 0
	s_add_u32 s82, s98, 0x2a480000
	s_addc_u32 s83, s99, 0
	s_add_u32 s84, s98, 0x2a6c0000
	s_addc_u32 s85, s99, 0
	s_add_u32 s86, s98, 0x2b00000
	s_addc_u32 s87, s99, 0
	s_add_u32 s88, s98, 0x4080000
	s_addc_u32 s89, s99, 0
	s_add_u32 s4, s98, 0x5c80000
	s_addc_u32 s5, s99, 0
	v_writelane_b32 v253, s4, 2
	v_lshrrev_b32_e32 v1, 20, v0
	v_lshrrev_b32_e32 v0, 10, v0
	v_writelane_b32 v253, s5, 3
	s_add_u32 s4, s98, 0x312c3600
	s_addc_u32 s5, s99, 0
	s_lshl_b32 s67, s10, 9
	s_lshl_b32 s90, s10, 3
	v_writelane_b32 v253, s4, 4
	s_add_u32 s6, s98, 0x31383600
	s_addc_u32 s7, s99, 0
	v_writelane_b32 v253, s5, 5
	s_load_dword s5, s[0:1], 0xb0
	v_writelane_b32 v253, s6, 6
	s_mul_i32 s4, s11, s10
	v_or_b32_e32 v0, v0, v1
	v_writelane_b32 v253, s7, 7
	s_add_u32 s6, s98, 0x31443600
	s_addc_u32 s7, s99, 0
	v_writelane_b32 v253, s6, 8
	s_waitcnt lgkmcnt(0)
	s_mul_i32 s4, s4, s5
	s_load_dwordx16 s[36:51], s[0:1], 0x0
	v_writelane_b32 v253, s7, 9
	v_writelane_b32 v253, s4, 10
	s_add_u32 s4, s98, 0x312c0200
	s_addc_u32 s5, s99, 0
	v_writelane_b32 v253, s4, 11
	v_mbcnt_lo_u32_b32 v2, -1, 0
	v_mov_b32_e32 v204, 0x358637bd
	v_writelane_b32 v253, s5, 12
	s_add_u32 s4, s98, 0x312c0400
	s_addc_u32 s5, s99, 0
	v_writelane_b32 v253, s4, 13
	v_mbcnt_hi_u32_b32 v229, -1, v2
	v_mov_b32_e32 v230, 0xf149f2ca
	v_writelane_b32 v253, s5, 14
	s_add_u32 s4, s98, 0x312c0500
	s_addc_u32 s5, s99, 0
	v_writelane_b32 v253, s4, 15
	s_mov_b32 s11, 0xefa18f08
	s_mov_b32 s19, s8
	v_writelane_b32 v253, s5, 16
	s_add_u32 s4, s98, 0x312c0600
	s_addc_u32 s5, s99, 0
	v_writelane_b32 v253, s4, 17
	s_mov_b32 s61, 0
	s_mov_b64 s[30:31], 0x80
	v_writelane_b32 v253, s5, 18
	s_add_u32 s4, s98, 0x312c0700
	s_addc_u32 s5, s99, 0
	v_writelane_b32 v253, s4, 19
	s_mov_b64 s[56:57], 0x100
	s_mov_b64 s[26:27], 0x4800000
	v_writelane_b32 v253, s5, 20
	s_add_u32 s4, s98, 0x312c0800
	s_addc_u32 s5, s99, 0
	v_writelane_b32 v253, s4, 21
	s_nop 1
	v_writelane_b32 v253, s5, 22
	s_add_u32 s4, s98, 0x312c0900
	s_addc_u32 s5, s99, 0
	v_writelane_b32 v253, s4, 23
	s_nop 1
	v_writelane_b32 v253, s5, 24
	s_add_u32 s4, s98, 0x312c0a00
	s_addc_u32 s5, s99, 0
	v_writelane_b32 v253, s4, 25
	s_nop 1
	v_writelane_b32 v253, s5, 26
	s_add_u32 s4, s98, 0x312c0b00
	s_addc_u32 s5, s99, 0
	v_writelane_b32 v253, s4, 27
	s_nop 1
	v_writelane_b32 v253, s5, 28
	s_add_u32 s4, s98, 0x312c0c00
	s_addc_u32 s5, s99, 0
	v_writelane_b32 v253, s4, 29
	s_nop 1
	v_writelane_b32 v253, s5, 30
	s_add_u32 s4, s98, 0x312c0d00
	s_addc_u32 s5, s99, 0
	v_writelane_b32 v253, s4, 31
	s_nop 1
	v_writelane_b32 v253, s5, 32
	s_add_u32 s4, s98, 0x312c0e00
	s_addc_u32 s5, s99, 0
	v_writelane_b32 v253, s4, 33
	s_nop 1
	v_writelane_b32 v253, s5, 34
	s_add_u32 s4, s98, 0x312c0f00
	s_addc_u32 s5, s99, 0
	v_writelane_b32 v253, s4, 35
	s_nop 1
	v_writelane_b32 v253, s5, 36
	s_add_u32 s4, s98, 0x312c1000
	s_addc_u32 s5, s99, 0
	v_writelane_b32 v253, s4, 37
	s_nop 1
	v_writelane_b32 v253, s5, 38
	s_add_u32 s4, s98, 0x312c1100
	s_addc_u32 s5, s99, 0
	v_writelane_b32 v253, s4, 39
	s_nop 1
	v_writelane_b32 v253, s5, 40
	s_add_u32 s4, s98, 0x312c1200
	s_addc_u32 s5, s99, 0
	v_writelane_b32 v253, s4, 41
	s_nop 1
	v_writelane_b32 v253, s5, 42
	s_add_u32 s4, s98, 0x312c1300
	s_addc_u32 s5, s99, 0
	v_writelane_b32 v253, s4, 43
	s_cmp_eq_u32 s33, 15
	s_nop 0
	v_writelane_b32 v253, s5, 44
	s_cselect_b64 s[4:5], -1, 0
	v_writelane_b32 v253, s4, 45
	s_cmp_eq_u32 s33, 14
	s_nop 0
	v_writelane_b32 v253, s5, 46
	s_cselect_b64 s[4:5], -1, 0
	v_writelane_b32 v253, s4, 47
	s_cmp_eq_u32 s33, 13
	s_nop 0
	v_writelane_b32 v253, s5, 48
	s_cselect_b64 s[4:5], -1, 0
	v_writelane_b32 v253, s4, 49
	s_cmp_eq_u32 s33, 12
	s_nop 0
	v_writelane_b32 v253, s5, 50
	s_cselect_b64 s[4:5], -1, 0
	v_writelane_b32 v253, s4, 51
	s_cmp_eq_u32 s33, 11
	s_nop 0
	v_writelane_b32 v253, s5, 52
	s_cselect_b64 s[4:5], -1, 0
	v_writelane_b32 v253, s4, 53
	s_cmp_eq_u32 s33, 10
	s_nop 0
	v_writelane_b32 v253, s5, 54
	s_cselect_b64 s[4:5], -1, 0
	v_writelane_b32 v253, s4, 55
	s_cmp_eq_u32 s33, 9
	s_nop 0
	v_writelane_b32 v253, s5, 56
	s_cselect_b64 s[4:5], -1, 0
	v_writelane_b32 v253, s4, 57
	s_cmp_eq_u32 s33, 8
	s_nop 0
	v_writelane_b32 v253, s5, 58
	s_cselect_b64 s[4:5], -1, 0
	v_writelane_b32 v253, s4, 59
	s_cmp_eq_u32 s33, 7
	s_nop 0
	v_writelane_b32 v253, s5, 60
	s_cselect_b64 s[4:5], -1, 0
	v_writelane_b32 v253, s4, 61
	s_cmp_eq_u32 s33, 6
	s_nop 0
	v_writelane_b32 v253, s5, 62
	s_cselect_b64 s[4:5], -1, 0
	v_writelane_b32 v253, s4, 63
	s_cmp_eq_u32 s33, 5
	s_nop 0
	v_writelane_b32 v254, s5, 0
	s_cselect_b64 s[4:5], -1, 0
	v_writelane_b32 v254, s4, 1
; #define LAS __attribute__((address_space(3)))
; __device__ void ret_out_phase(LAS unsigned char* lds, const bf16_t* PROJ, const bf16_t* ST, bf16_t* MIX, const float* lgf, const float* lgb, const float* ogain) {
;     ...
;     constexpr int RP = 528, BUFB = 128 * RP;
; __global__ void __launch_bounds__(512, 2) fwd_megakernel(Params p) {
;     ...
;     XcdBarrier xbar = xcd_barrier_post((unsigned*)(p.ws + WS_BAR), (volatile LAS unsigned*)(lds + LDS_BARST));
;     unsigned char* ws = p.ws;
;     bf16_t* H = (bf16_t*)(ws + WS_H); bf16_t* PROJ = (bf16_t*)(ws + WS_PROJ); bf16_t* AP = (bf16_t*)(ws + WS_AP); float* LSE = (float*)(ws + WS_LSE);
;     bf16_t* ST = (bf16_t*)(ws + WS_ST); f32x2* TA = (f32x2*)(ws + WS_TA); f32x2* TR = (f32x2*)(ws + WS_TR);
;     bf16_t* WGU = (bf16_t*)(ws + WS_WF + WF_GU); bf16_t* WDN = (bf16_t*)(ws + WS_WF + WF_DN); bf16_t* WIN = (bf16_t*)(ws + WS_WM + WM_IN); bf16_t* WOUT = (bf16_t*)(ws + WS_WM + WM_OUT);
;     float* SS = (float*)(ws + WS_SS);
	s_cmp_eq_u32 s33, 4
	s_nop 0
	v_writelane_b32 v254, s5, 2
	s_cselect_b64 s[4:5], -1, 0
	v_writelane_b32 v254, s4, 3
	s_cmp_eq_u32 s33, 3
	s_nop 0
	v_writelane_b32 v254, s5, 4
	s_cselect_b64 s[4:5], -1, 0
	v_writelane_b32 v254, s4, 5
	s_cmp_eq_u32 s33, 2
	s_nop 0
	v_writelane_b32 v254, s5, 6
	s_cselect_b64 s[4:5], -1, 0
	v_writelane_b32 v254, s4, 7
	s_cmp_eq_u32 s33, 1
	s_nop 0
	v_writelane_b32 v254, s5, 8
	s_cselect_b64 s[4:5], -1, 0
	v_writelane_b32 v254, s4, 9
	s_cmp_eq_u32 s33, 0
	s_nop 0
	v_writelane_b32 v254, s5, 10
	s_cselect_b64 s[4:5], -1, 0
	v_writelane_b32 v254, s4, 11
	s_nop 1
	v_writelane_b32 v254, s5, 12
	s_lshl_b32 s4, s33, 8
	s_add_u32 s2, s2, s4
	s_addc_u32 s3, s3, 0
	s_add_u32 s4, s2, 0x1400
	s_addc_u32 s5, s3, 0
	v_writelane_b32 v254, s4, 13
	s_add_u32 s2, s2, 0x2400
	s_addc_u32 s3, s3, 0
	v_writelane_b32 v254, s5, 14
	v_writelane_b32 v254, s2, 15
	s_mov_b32 s33, 0x9000000
	s_nop 0
	v_writelane_b32 v254, s3, 16
	s_movk_i32 s2, 0x3ff
	v_and_or_b32 v0, v0, s2, v226
	s_add_u32 s2, s98, 0x312c3400
	s_addc_u32 s3, s99, 0
	v_writelane_b32 v254, s2, 17
	s_nop 1
	v_writelane_b32 v254, s3, 18
	s_add_u32 s2, s98, 0x312c3500
	s_addc_u32 s3, s99, 0
	v_writelane_b32 v254, s2, 19
	s_nop 1
	v_writelane_b32 v254, s3, 20
	s_abs_i32 s2, s10
	v_cvt_f32_u32_e32 v1, s2
	v_writelane_b32 v254, s2, 21
	s_sub_i32 s2, 0, s2
	v_rcp_iflag_f32_e32 v1, v1
	s_nop 0
	v_mul_f32_e32 v1, 0x4f7ffffe, v1
	v_cvt_u32_f32_e32 v1, v1
	s_nop 0
	v_readfirstlane_b32 s3, v1
	s_mul_i32 s2, s2, s3
	s_mul_hi_u32 s2, s3, s2
	s_add_i32 s2, s3, s2
	v_writelane_b32 v254, s2, 22
	s_lshl_b32 s2, s10, 4
	v_writelane_b32 v254, s2, 23
	s_add_u32 s2, s98, 0x10c80000
	s_addc_u32 s3, s99, 0
	v_writelane_b32 v254, s2, 24
	s_ashr_i32 s91, s90, 31
	v_mov_b32_e32 v1, 0
	v_writelane_b32 v254, s3, 25
	s_lshl_b64 s[2:3], s[90:91], 8
	v_writelane_b32 v254, s2, 26
	s_nop 1
	v_writelane_b32 v254, s3, 27
	s_lshl_b64 s[2:3], s[90:91], 2
	v_writelane_b32 v254, s2, 28
	s_nop 1
	v_writelane_b32 v254, s3, 29
	s_add_u32 s2, s96, 0x1000
	s_addc_u32 s3, s97, 0
	v_writelane_b32 v254, s2, 30
	s_nop 1
	v_writelane_b32 v254, s3, 31
	s_lshl_b64 s[2:3], s[90:91], 13
	v_writelane_b32 v254, s2, 32
	s_nop 1
	v_writelane_b32 v254, s3, 33
	s_add_u32 s2, s98, 0x6480800
	s_addc_u32 s3, s99, 0
	v_writelane_b32 v254, s2, 34
	s_nop 1
	v_writelane_b32 v254, s3, 35
	s_add_i32 s2, 0, 0x11000
	v_writelane_b32 v254, s2, 36
	s_add_i32 s2, 0, 0x21000
	v_writelane_b32 v254, s2, 37
	s_add_i32 s2, 0, 0x20000
	v_writelane_b32 v254, s2, 38
	s_add_i32 s2, 0, 0x25ff0
	v_writelane_b32 v254, s2, 39
	s_add_i32 s2, 0, 0x25ff4
	v_writelane_b32 v254, s2, 40
	v_cmp_eq_u32_e64 s[2:3], 0, v0
	s_nop 1
	v_writelane_b32 v254, s2, 41
	s_nop 1
	v_writelane_b32 v254, s3, 42
	s_lshl_b64 s[2:3], s[90:91], 12
	v_writelane_b32 v254, s2, 43
	s_nop 1
	v_writelane_b32 v254, s3, 44
	s_waitcnt lgkmcnt(0)
	v_writelane_b32 v254, s36, 45
	s_nop 1
	v_writelane_b32 v254, s37, 46
	v_writelane_b32 v254, s38, 47
	v_writelane_b32 v254, s39, 48
	v_writelane_b32 v254, s40, 49
	v_writelane_b32 v254, s41, 50
	v_writelane_b32 v254, s42, 51
	v_writelane_b32 v254, s43, 52
	v_writelane_b32 v254, s44, 53
	v_writelane_b32 v254, s45, 54
	v_writelane_b32 v254, s46, 55
	v_writelane_b32 v254, s47, 56
	v_writelane_b32 v254, s48, 57
	v_writelane_b32 v254, s49, 58
	v_writelane_b32 v254, s50, 59
	v_writelane_b32 v254, s51, 60
	s_load_dwordx16 s[36:51], s[0:1], 0x40
	s_waitcnt lgkmcnt(0)
	v_writelane_b32 v254, s36, 61
	s_nop 1
	v_writelane_b32 v255, s39, 0
	v_writelane_b32 v255, s40, 1
	v_writelane_b32 v255, s41, 2
	v_writelane_b32 v255, s42, 3
	v_writelane_b32 v255, s43, 4
	v_writelane_b32 v255, s44, 5
	v_writelane_b32 v255, s45, 6
	v_writelane_b32 v255, s46, 7
	v_writelane_b32 v255, s47, 8
	v_writelane_b32 v255, s48, 9
	v_writelane_b32 v255, s49, 10
	v_writelane_b32 v255, s50, 11
	v_writelane_b32 v255, s51, 12
	v_writelane_b32 v255, s66, 13
	v_writelane_b32 v255, s68, 14
	v_writelane_b32 v254, s37, 62
	v_writelane_b32 v254, s38, 63
	v_writelane_b32 v255, s69, 15
	v_writelane_b32 v255, s70, 16
	s_nop 1
	v_writelane_b32 v255, s71, 17
	v_writelane_b32 v255, s74, 18
	v_writelane_b32 v255, s75, 19
	v_writelane_b32 v255, s76, 20
	s_nop 1
	v_writelane_b32 v255, s77, 21
	v_writelane_b32 v255, s78, 22
	s_nop 1
	v_writelane_b32 v255, s79, 23
	v_writelane_b32 v255, s80, 24
	s_nop 1
	v_writelane_b32 v255, s81, 25
	v_writelane_b32 v255, s82, 26
	s_nop 1
	v_writelane_b32 v255, s83, 27
	v_writelane_b32 v255, s84, 28
	s_nop 1
	v_writelane_b32 v255, s85, 29
	v_writelane_b32 v255, s86, 30
	s_nop 1
	v_writelane_b32 v255, s87, 31
	v_writelane_b32 v255, s88, 32
	s_nop 1
	v_writelane_b32 v255, s89, 33
	v_writelane_b32 v255, s67, 34
	v_writelane_b32 v255, s90, 35
	s_nop 1
	v_writelane_b32 v255, s91, 36
	s_branch .LBB0_20

; #define LAS __attribute__((address_space(3)))
; __device__ __forceinline__ int otid() { int t = threadIdx.x; asm volatile("" : "+v"(t)); return t; }
; __device__ __forceinline__ int obid() { int b = blockIdx.x; asm volatile("" : "+s"(b)); return b; }
; #define MFMA16(a, b, c) __builtin_amdgcn_mfma_f32_16x16x32_bf16((a), (b), (c), 0, 0, 0)
; #define RET_ISSUE(s_, it_) do { const bf16_t* bp_; int pt_; RET_SRC(s_, it_, bp_, pt_); const int tv_ = otid(); const char* sb_ = (const char*)bp_ + (size_t)(((tv_ >> 5) * pt_ + (tv_ & 31) * 8) * 2); const size_t step_ = (size_t)pt_ * 32; \
;         _Pragma("unroll") for (int i_ = 0; i_ < 8; ++i_) stg[i_] = *(const u32x4*)(sb_ + i_ * step_); } while (0)
; __device__ void ret_out_phase(LAS unsigned char* lds, const bf16_t* PROJ, const bf16_t* ST, bf16_t* MIX, const float* lgf, const float* lgb, const float* ogain) {
;     const int tid = otid(), wave = __builtin_amdgcn_readfirstlane(tid >> 6), lane = tid & 63, fr = lane & 15, g = lane >> 4, q4 = (lane & 15) >> 2, p4 = lane & 3;
;     constexpr int RP = 528, BUFB = 128 * RP;
;     u32x4 stg[8];
;     int item = obid();
;     if (item < 768) { const RetItem r0 = ret_decode(item); RET_ISSUE(0, r0); }
;     for (; item < 768; item += gridDim.x) {
;         const RetItem ri = ret_decode(item);
;         const int h = ri.h, half = ri.half, qt = ri.qt;
;         const float lf = lgf[h], lb = lgb[h];
;         const size_t qtok = (size_t)qt * 128 + 16 * wave + fr;
;     ...
;                 for (int kk = 0; kk < 4; ++kk) { const bf16x8 pa = pack8(st[2 * kk], st[2 * kk + 1]);
;                     LAS unsigned char* vb = buf + (32 * kk + 4 * g + q4) * RP + 8 * p4;
; #pragma unroll
;                     for (int cc = 0; cc < 16; ++cc) { const bf16x8 bfrag = tr_pair(vb + 32 * cc, vb + 16 * RP + 32 * cc); o[cc] = MFMA16(pa, bfrag, o[cc]); } }
.LBB0_32:
	s_andn2_b64 vcc, exec, s[0:1]
	s_mov_b64 s[16:17], 0x9000000
	s_cbranch_vccnz .LBB0_293
	v_readlane_b32 s4, v255, 37
	s_lshl_b32 s0, s4, 2
	s_ashr_i32 s1, s0, 31
	v_readlane_b32 s36, v254, 61
	s_lshl_b64 s[0:1], s[0:1], 2
	v_readlane_b32 s38, v254, 63
	v_readlane_b32 s40, v255, 1
	v_readlane_b32 s39, v255, 0
	v_readlane_b32 s41, v255, 2
	s_add_u32 s38, s40, s0
	v_readlane_b32 s42, v255, 3
	s_addc_u32 s39, s41, s1
	v_readlane_b32 s43, v255, 4
	s_add_u32 s40, s42, s0
	s_addc_u32 s41, s43, s1
	s_lshl_b32 s0, s4, 10
	s_ashr_i32 s1, s0, 31
	v_readlane_b32 s44, v255, 5
	s_lshl_b64 s[0:1], s[0:1], 2
	v_readlane_b32 s45, v255, 6
	s_add_u32 s0, s44, s0
	s_addc_u32 s1, s45, s1
	s_ashr_i32 s2, s2, 6
	v_bfe_u32 v35, v34, 4, 2
	v_and_b32_e32 v165, 15, v34
	v_bfe_u32 v0, v34, 2, 2
	s_lshl_b32 s6, s2, 4
	v_lshlrev_b32_e32 v190, 2, v35
	s_mulk_i32 s2, 0x2200
	v_or_b32_e32 v41, v190, v0
	s_add_i32 s2, s2, 0
	v_lshlrev_b32_e32 v0, 2, v165
	v_ashrrev_i32_e32 v39, 5, v34
	v_lshl_add_u64 v[162:163], s[0:1], 0, v[0:1]
	v_bfe_u32 v164, v34, 2, 4
	v_mov_b32_e32 v0, s2
	s_movk_i32 s0, 0x220
	v_lshlrev_b32_e32 v38, 4, v34
	v_and_b32_e32 v42, 48, v34
	v_mad_u32_u24 v43, v164, s0, v0
	v_mul_lo_u32 v39, v39, s0
	v_mul_u32_u24_e32 v0, 0x220, v165
	v_readlane_b32 s0, v254, 36
	v_and_b32_e32 v37, 3, v34
	v_and_b32_e32 v40, 0x1f0, v38
	v_add3_u32 v191, 0, v42, v0
	v_add3_u32 v192, s0, v42, v0
	v_mul_u32_u24_e32 v0, 0x880, v35
	v_lshlrev_b32_e32 v34, 1, v165
	v_lshlrev_b32_e32 v36, 3, v35
	v_lshlrev_b32_e32 v38, 3, v37
	v_add_u32_e32 v45, 0, v40
	v_add_u32_e32 v47, s0, v40
	v_add3_u32 v193, s2, v0, v34
	v_lshlrev_b32_e32 v35, 4, v37
	v_or_b32_e32 v0, 4, v37
	v_or_b32_e32 v34, 8, v37
	v_or_b32_e32 v40, 12, v37
	v_or_b32_e32 v42, 16, v37
	v_or_b32_e32 v44, 20, v37
	v_or_b32_e32 v46, 24, v37
	v_or_b32_e32 v37, 28, v37
	v_mul_u32_u24_e32 v41, 0x220, v41
	v_lshlrev_b32_e32 v49, 4, v0
	v_lshlrev_b32_e32 v0, 3, v0
	v_lshlrev_b32_e32 v50, 4, v34
	v_lshlrev_b32_e32 v34, 3, v34
	v_lshlrev_b32_e32 v51, 4, v40
	v_lshlrev_b32_e32 v40, 3, v40
	v_lshlrev_b32_e32 v52, 4, v42
	v_lshlrev_b32_e32 v42, 3, v42
	v_lshlrev_b32_e32 v53, 4, v44
	v_lshlrev_b32_e32 v44, 3, v44
	v_lshlrev_b32_e32 v54, 4, v46
	v_lshlrev_b32_e32 v46, 3, v46
	s_waitcnt lgkmcnt(0)
	v_lshlrev_b32_e32 v55, 4, v37
	v_lshlrev_b32_e32 v48, 3, v37
	s_ashr_i32 s7, s6, 31
	v_add3_u32 v225, s0, v38, v41
	v_or_b32_e32 v245, 0xb1, v190
	v_or_b32_e32 v246, 0xb2, v190
	v_or_b32_e32 v247, 0xb3, v190
	v_or_b32_e32 v248, 0xc0, v190
	v_or_b32_e32 v249, 0xc1, v190
	v_or_b32_e32 v250, 0xc2, v190
	v_or_b32_e32 v251, 0xc3, v190
	v_or_b32_e32 v252, 0xd0, v190
	v_or_b32_e32 v228, 0xd1, v190
	v_or_b32_e32 v227, 0xd2, v190
	v_or_b32_e32 v231, 0xd3, v190
	v_or_b32_e32 v194, 0xe0, v190
	v_or_b32_e32 v195, 0xe1, v190
	v_or_b32_e32 v196, 0xe2, v190
	v_or_b32_e32 v197, 0xe3, v190
	v_or_b32_e32 v198, 0xf0, v190
	v_or_b32_e32 v199, 0xf1, v190
	v_or_b32_e32 v200, 0xf2, v190
	v_or_b32_e32 v201, 0xf3, v190
	v_lshlrev_b32_e32 v166, 1, v36
	v_add_u32_e32 v202, v43, v35
	v_lshlrev_b32_e32 v168, 1, v38
	v_add_u32_e32 v203, v43, v49
	v_lshlrev_b32_e32 v170, 1, v0
	v_add_u32_e32 v204, v43, v50
	v_lshlrev_b32_e32 v172, 1, v34
	v_add_u32_e32 v205, v43, v51
	v_lshlrev_b32_e32 v174, 1, v40
	v_add_u32_e32 v206, v43, v52
	v_lshlrev_b32_e32 v176, 1, v42
	v_add_u32_e32 v207, v43, v53
	v_lshlrev_b32_e32 v178, 1, v44
	v_add_u32_e32 v208, v43, v54
	v_lshlrev_b32_e32 v180, 1, v46
	v_add_u32_e32 v209, v43, v55
	v_lshlrev_b32_e32 v182, 1, v48
	v_add_u32_e32 v210, v45, v39
	v_add_u32_e32 v211, v47, v39
	v_readlane_b32 s5, v255, 38
	v_readlane_b32 s37, v254, 62
	v_readlane_b32 s46, v255, 7
	v_readlane_b32 s47, v255, 8
	v_readlane_b32 s48, v255, 9
	v_readlane_b32 s49, v255, 10
	v_readlane_b32 s50, v255, 11
	v_readlane_b32 s51, v255, 12
	s_branch .LBB0_35
.LBB0_34:
	v_mul_f32_e32 v0, v36, v158
	v_mul_f32_e32 v158, v37, v161
	v_mul_f32_e32 v159, v34, v159
	v_mul_f32_e32 v160, v35, v160
	v_mul_f32_e32 v34, v136, v44
	v_mul_f32_e32 v35, v137, v45
	v_mul_f32_e32 v36, v134, v42
	v_mul_f32_e32 v37, v135, v43
	v_mul_f32_e32 v40, v132, v40
	v_mul_f32_e32 v41, v133, v41
	v_mul_f32_e32 v38, v130, v38
	v_mul_f32_e32 v39, v131, v39
	v_mul_f32_e32 v144, v144, v52
	v_mul_f32_e32 v145, v145, v53
	v_mul_f32_e32 v142, v142, v50
	v_mul_f32_e32 v143, v143, v51
	v_cvt_pk_bf16_f32 v50, v38, v39
	v_cvt_pk_bf16_f32 v51, v40, v41
	v_cvt_pk_bf16_f32 v52, v36, v37
	v_cvt_pk_bf16_f32 v53, v34, v35
	ds_read_b64_tr_b16 v[36:37], v225 offset:8704
	ds_read_b64_tr_b16 v[34:35], v225
	ds_read_b64_tr_b16 v[38:39], v225 offset:32
	ds_read_b64_tr_b16 v[40:41], v225 offset:8736
	v_mul_f32_e32 v148, v148, v56
	v_mul_f32_e32 v149, v149, v57
	v_mul_f32_e32 v146, v146, v54
	v_mul_f32_e32 v147, v147, v55
	s_waitcnt lgkmcnt(2)
	v_mfma_f32_16x16x32_bf16 v[54:57], v[50:53], v[34:37], v[122:125]
	v_mul_f32_e32 v152, v152, v60
	v_mul_f32_e32 v153, v153, v61
	v_mul_f32_e32 v150, v150, v58
	s_waitcnt lgkmcnt(0)
	v_mfma_f32_16x16x32_bf16 v[34:37], v[50:53], v[38:41], v[126:129]
	ds_read_b64_tr_b16 v[38:39], v225 offset:64
	ds_read_b64_tr_b16 v[40:41], v225 offset:8768
	v_mul_f32_e32 v151, v151, v59
	v_mul_f32_e32 v156, v156, v64
	s_waitcnt lgkmcnt(0)
	v_mfma_f32_16x16x32_bf16 v[58:61], v[50:53], v[38:41], v[114:117]
	ds_read_b64_tr_b16 v[38:39], v225 offset:96
	ds_read_b64_tr_b16 v[40:41], v225 offset:8800
	v_mul_f32_e32 v157, v157, v65
	v_mul_f32_e32 v154, v154, v62
	s_waitcnt lgkmcnt(0)
	v_mfma_f32_16x16x32_bf16 v[82:85], v[50:53], v[38:41], v[82:85]
	ds_read_b64_tr_b16 v[38:39], v225 offset:128
	ds_read_b64_tr_b16 v[40:41], v225 offset:8832
	v_mul_f32_e32 v155, v155, v63
	v_mul_f32_e32 v140, v140, v48
	s_waitcnt lgkmcnt(0)
; #define LAS __attribute__((address_space(3)))
; #define MFMA16(a, b, c) __builtin_amdgcn_mfma_f32_16x16x32_bf16((a), (b), (c), 0, 0, 0)
; __device__ void ret_out_phase(LAS unsigned char* lds, const bf16_t* PROJ, const bf16_t* ST, bf16_t* MIX, const float* lgf, const float* lgb, const float* ogain) {
;     ...
;                 for (int kk = 0; kk < 4; ++kk) { const bf16x8 pa = pack8(st[2 * kk], st[2 * kk + 1]);
;                     LAS unsigned char* vb = buf + (32 * kk + 4 * g + q4) * RP + 8 * p4;
; #pragma unroll
;                     for (int cc = 0; cc < 16; ++cc) { const bf16x8 bfrag = tr_pair(vb + 32 * cc, vb + 16 * RP + 32 * cc); o[cc] = MFMA16(pa, bfrag, o[cc]); } }
	v_mfma_f32_16x16x32_bf16 v[86:89], v[50:53], v[38:41], v[86:89]
	ds_read_b64_tr_b16 v[38:39], v225 offset:160
	ds_read_b64_tr_b16 v[40:41], v225 offset:8864
	v_mul_f32_e32 v141, v141, v49
	v_mul_f32_e32 v138, v138, v46
	s_waitcnt lgkmcnt(0)
	v_mfma_f32_16x16x32_bf16 v[110:113], v[50:53], v[38:41], v[110:113]
	ds_read_b64_tr_b16 v[38:39], v225 offset:192
	ds_read_b64_tr_b16 v[40:41], v225 offset:8896
	v_mul_f32_e32 v139, v139, v47
	s_lshl_b32 s60, s12, 10
	s_waitcnt lgkmcnt(0)
	v_mfma_f32_16x16x32_bf16 v[114:117], v[50:53], v[38:41], v[98:101]
	ds_read_b64_tr_b16 v[38:39], v225 offset:224
	ds_read_b64_tr_b16 v[40:41], v225 offset:8928
	s_mov_b32 s0, 0x358637bd
	s_add_i32 s4, s14, s10
	s_waitcnt lgkmcnt(0)
	v_mfma_f32_16x16x32_bf16 v[74:77], v[50:53], v[38:41], v[74:77]
	ds_read_b64_tr_b16 v[38:39], v225 offset:256
	ds_read_b64_tr_b16 v[40:41], v225 offset:8960
	s_mov_b32 s14, 0x3b800000
	s_mov_b32 s5, 0x800000
	s_waitcnt lgkmcnt(0)
	v_mfma_f32_16x16x32_bf16 v[78:81], v[50:53], v[38:41], v[78:81]
	ds_read_b64_tr_b16 v[38:39], v225 offset:288
	ds_read_b64_tr_b16 v[40:41], v225 offset:8992
	s_mov_b64 s[16:17], 0x9000000
	v_mov_b32_e32 v169, v1
	s_waitcnt lgkmcnt(0)
	v_mfma_f32_16x16x32_bf16 v[122:125], v[50:53], v[38:41], v[102:105]
	ds_read_b64_tr_b16 v[38:39], v225 offset:320
	ds_read_b64_tr_b16 v[40:41], v225 offset:9024
	v_mov_b32_e32 v171, v1
	v_mov_b32_e32 v173, v1
	s_waitcnt lgkmcnt(0)
	v_mfma_f32_16x16x32_bf16 v[126:129], v[50:53], v[38:41], v[94:97]
	ds_read_b64_tr_b16 v[38:39], v225 offset:352
	ds_read_b64_tr_b16 v[40:41], v225 offset:9056
	v_mov_b32_e32 v175, v1
	v_mov_b32_e32 v177, v1
	s_waitcnt lgkmcnt(0)
	v_mfma_f32_16x16x32_bf16 v[130:133], v[50:53], v[38:41], v[70:73]
	ds_read_b64_tr_b16 v[38:39], v225 offset:384
	ds_read_b64_tr_b16 v[40:41], v225 offset:9088
	v_mov_b32_e32 v179, v1
	v_mov_b32_e32 v181, v1
	s_waitcnt lgkmcnt(0)
	v_mfma_f32_16x16x32_bf16 v[46:49], v[50:53], v[38:41], v[66:69]
	ds_read_b64_tr_b16 v[38:39], v225 offset:416
	ds_read_b64_tr_b16 v[40:41], v225 offset:9120
	ds_read_b64_tr_b16 v[42:43], v225 offset:448
	ds_read_b64_tr_b16 v[44:45], v225 offset:9152
	ds_read_b64_tr_b16 v[62:63], v225 offset:480
	ds_read_b64_tr_b16 v[64:65], v225 offset:9184
	s_waitcnt lgkmcnt(4)
	v_mfma_f32_16x16x32_bf16 v[38:41], v[50:53], v[38:41], v[90:93]
	v_mov_b32_e32 v183, v1
	s_waitcnt lgkmcnt(2)
	v_mfma_f32_16x16x32_bf16 v[42:45], v[50:53], v[42:45], v[106:109]
	s_waitcnt lgkmcnt(0)
	v_mfma_f32_16x16x32_bf16 v[50:53], v[50:53], v[62:65], v[118:121]
	s_nop 0
	v_cvt_pk_bf16_f32 v106, v138, v139
	v_cvt_pk_bf16_f32 v107, v140, v141
	v_cvt_pk_bf16_f32 v108, v142, v143
	v_cvt_pk_bf16_f32 v109, v144, v145
	ds_read_b64_tr_b16 v[62:63], v225 offset:17408
	ds_read_b64_tr_b16 v[64:65], v225 offset:26112
	s_waitcnt lgkmcnt(0)
	v_mfma_f32_16x16x32_bf16 v[54:57], v[106:109], v[62:65], v[54:57]
	ds_read_b64_tr_b16 v[62:63], v225 offset:17440
	ds_read_b64_tr_b16 v[64:65], v225 offset:26144
	v_cvt_pk_bf16_f32 v118, v146, v147
	v_cvt_pk_bf16_f32 v119, v148, v149
	s_waitcnt lgkmcnt(0)
	v_mfma_f32_16x16x32_bf16 v[62:65], v[106:109], v[62:65], v[34:37]
	s_nop 2
	ds_read_b64_tr_b16 v[34:35], v225 offset:17472
	ds_read_b64_tr_b16 v[36:37], v225 offset:26176
	v_cvt_pk_bf16_f32 v120, v150, v151
	v_cvt_pk_bf16_f32 v121, v152, v153
	s_waitcnt lgkmcnt(0)
	v_mfma_f32_16x16x32_bf16 v[90:93], v[106:109], v[34:37], v[58:61]
	ds_read_b64_tr_b16 v[34:35], v225 offset:17504
	ds_read_b64_tr_b16 v[36:37], v225 offset:26208
	s_waitcnt lgkmcnt(0)
	v_mfma_f32_16x16x32_bf16 v[94:97], v[106:109], v[34:37], v[82:85]
	ds_read_b64_tr_b16 v[34:35], v225 offset:17536
	ds_read_b64_tr_b16 v[36:37], v225 offset:26240
	s_waitcnt lgkmcnt(0)
	v_mfma_f32_16x16x32_bf16 v[98:101], v[106:109], v[34:37], v[86:89]
	ds_read_b64_tr_b16 v[34:35], v225 offset:17568
	ds_read_b64_tr_b16 v[36:37], v225 offset:26272
	s_waitcnt lgkmcnt(0)
	v_mfma_f32_16x16x32_bf16 v[102:105], v[106:109], v[34:37], v[110:113]
	ds_read_b64_tr_b16 v[34:35], v225 offset:17600
	ds_read_b64_tr_b16 v[36:37], v225 offset:26304
	s_waitcnt lgkmcnt(0)
	v_mfma_f32_16x16x32_bf16 v[58:61], v[106:109], v[34:37], v[114:117]
	ds_read_b64_tr_b16 v[34:35], v225 offset:17632
	ds_read_b64_tr_b16 v[36:37], v225 offset:26336
	s_waitcnt lgkmcnt(0)
	v_mfma_f32_16x16x32_bf16 v[110:113], v[106:109], v[34:37], v[74:77]
	ds_read_b64_tr_b16 v[34:35], v225 offset:17664
	ds_read_b64_tr_b16 v[36:37], v225 offset:26368
	s_waitcnt lgkmcnt(0)
	v_mfma_f32_16x16x32_bf16 v[66:69], v[106:109], v[34:37], v[78:81]
	ds_read_b64_tr_b16 v[34:35], v225 offset:17696
	ds_read_b64_tr_b16 v[36:37], v225 offset:26400
	s_waitcnt lgkmcnt(0)
	v_mfma_f32_16x16x32_bf16 v[70:73], v[106:109], v[34:37], v[122:125]
	ds_read_b64_tr_b16 v[34:35], v225 offset:17728
	ds_read_b64_tr_b16 v[36:37], v225 offset:26432
	s_waitcnt lgkmcnt(0)
	v_mfma_f32_16x16x32_bf16 v[74:77], v[106:109], v[34:37], v[126:129]
	ds_read_b64_tr_b16 v[34:35], v225 offset:17760
	ds_read_b64_tr_b16 v[36:37], v225 offset:26464
	s_waitcnt lgkmcnt(0)
	v_mfma_f32_16x16x32_bf16 v[78:81], v[106:109], v[34:37], v[130:133]
	ds_read_b64_tr_b16 v[34:35], v225 offset:17792
	ds_read_b64_tr_b16 v[36:37], v225 offset:26496
	s_waitcnt lgkmcnt(0)
	v_mfma_f32_16x16x32_bf16 v[46:49], v[106:109], v[34:37], v[46:49]
	ds_read_b64_tr_b16 v[34:35], v225 offset:17824
	ds_read_b64_tr_b16 v[36:37], v225 offset:26528
	s_waitcnt lgkmcnt(0)
	v_mfma_f32_16x16x32_bf16 v[82:85], v[106:109], v[34:37], v[38:41]
	ds_read_b64_tr_b16 v[34:35], v225 offset:17856
	ds_read_b64_tr_b16 v[36:37], v225 offset:26560
	s_waitcnt lgkmcnt(0)
	v_mfma_f32_16x16x32_bf16 v[86:89], v[106:109], v[34:37], v[42:45]
	ds_read_b64_tr_b16 v[34:35], v225 offset:17888
	ds_read_b64_tr_b16 v[36:37], v225 offset:26592
	s_waitcnt lgkmcnt(0)
; #define LAS __attribute__((address_space(3)))
; #define MFMA16(a, b, c) __builtin_amdgcn_mfma_f32_16x16x32_bf16((a), (b), (c), 0, 0, 0)
; __device__ void ret_out_phase(LAS unsigned char* lds, const bf16_t* PROJ, const bf16_t* ST, bf16_t* MIX, const float* lgf, const float* lgb, const float* ogain) {
;     ...
;                 for (int kk = 0; kk < 4; ++kk) { const bf16x8 pa = pack8(st[2 * kk], st[2 * kk + 1]);
;                     LAS unsigned char* vb = buf + (32 * kk + 4 * g + q4) * RP + 8 * p4;
; #pragma unroll
;                     for (int cc = 0; cc < 16; ++cc) { const bf16x8 bfrag = tr_pair(vb + 32 * cc, vb + 16 * RP + 32 * cc); o[cc] = MFMA16(pa, bfrag, o[cc]); } }
;             }
;         }
;         {
;             LAS unsigned char* sl = lds + wave * (16 * RP);
; #pragma unroll
;             for (int j = 0; j < 4; ++j) { float ss = 0.f;
; #pragma unroll
;                 for (int cc = 0; cc < 16; ++cc) ss += o[cc][j] * o[cc][j];
	v_mfma_f32_16x16x32_bf16 v[114:117], v[106:109], v[34:37], v[50:53]
	ds_read_b64_tr_b16 v[34:35], v225 offset:34816
	ds_read_b64_tr_b16 v[36:37], v225 offset:43520
	ds_read_b64_tr_b16 v[38:39], v225 offset:34848
	ds_read_b64_tr_b16 v[40:41], v225 offset:43552
	ds_read_b64_tr_b16 v[42:43], v225 offset:34880
	ds_read_b64_tr_b16 v[44:45], v225 offset:43584
	ds_read_b64_tr_b16 v[50:51], v225 offset:34912
	ds_read_b64_tr_b16 v[52:53], v225 offset:43616
	s_waitcnt lgkmcnt(6)
	v_mfma_f32_16x16x32_bf16 v[34:37], v[118:121], v[34:37], v[54:57]
	s_waitcnt lgkmcnt(4)
	v_mfma_f32_16x16x32_bf16 v[38:41], v[118:121], v[38:41], v[62:65]
	s_waitcnt lgkmcnt(0)
	v_mfma_f32_16x16x32_bf16 v[106:109], v[118:121], v[50:53], v[94:97]
	ds_read_b64_tr_b16 v[50:51], v225 offset:34944
	ds_read_b64_tr_b16 v[52:53], v225 offset:43648
	ds_read_b64_tr_b16 v[54:55], v225 offset:34976
	ds_read_b64_tr_b16 v[56:57], v225 offset:43680
	ds_read_b64_tr_b16 v[62:63], v225 offset:35008
	ds_read_b64_tr_b16 v[64:65], v225 offset:43712
	v_mfma_f32_16x16x32_bf16 v[42:45], v[118:121], v[42:45], v[90:93]
	s_waitcnt lgkmcnt(0)
	v_mfma_f32_16x16x32_bf16 v[58:61], v[118:121], v[62:65], v[58:61]
	ds_read_b64_tr_b16 v[62:63], v225 offset:35040
	ds_read_b64_tr_b16 v[64:65], v225 offset:43744
	ds_read_b64_tr_b16 v[90:91], v225 offset:35072
	ds_read_b64_tr_b16 v[92:93], v225 offset:43776
	s_waitcnt lgkmcnt(0)
	v_mfma_f32_16x16x32_bf16 v[66:69], v[118:121], v[90:93], v[66:69]
	ds_read_b64_tr_b16 v[90:91], v225 offset:35104
	ds_read_b64_tr_b16 v[92:93], v225 offset:43808
	s_waitcnt lgkmcnt(0)
	v_mfma_f32_16x16x32_bf16 v[70:73], v[118:121], v[90:93], v[70:73]
	ds_read_b64_tr_b16 v[90:91], v225 offset:35136
	ds_read_b64_tr_b16 v[92:93], v225 offset:43840
	s_waitcnt lgkmcnt(0)
	v_mfma_f32_16x16x32_bf16 v[74:77], v[118:121], v[90:93], v[74:77]
	ds_read_b64_tr_b16 v[90:91], v225 offset:35168
	ds_read_b64_tr_b16 v[92:93], v225 offset:43872
	s_waitcnt lgkmcnt(0)
	v_mfma_f32_16x16x32_bf16 v[78:81], v[118:121], v[90:93], v[78:81]
	ds_read_b64_tr_b16 v[90:91], v225 offset:35200
	ds_read_b64_tr_b16 v[92:93], v225 offset:43904
	s_waitcnt lgkmcnt(0)
	v_mfma_f32_16x16x32_bf16 v[90:93], v[118:121], v[90:93], v[46:49]
	s_nop 2
	ds_read_b64_tr_b16 v[46:47], v225 offset:35232
	ds_read_b64_tr_b16 v[48:49], v225 offset:43936
	s_waitcnt lgkmcnt(0)
	v_mfma_f32_16x16x32_bf16 v[94:97], v[118:121], v[46:49], v[82:85]
	ds_read_b64_tr_b16 v[46:47], v225 offset:35264
	ds_read_b64_tr_b16 v[48:49], v225 offset:43968
	v_mfma_f32_16x16x32_bf16 v[54:57], v[118:121], v[54:57], v[102:105]
	s_waitcnt lgkmcnt(0)
	v_mfma_f32_16x16x32_bf16 v[102:105], v[118:121], v[46:49], v[86:89]
	ds_read_b64_tr_b16 v[46:47], v225 offset:35296
	ds_read_b64_tr_b16 v[48:49], v225 offset:44000
	v_mfma_f32_16x16x32_bf16 v[50:53], v[118:121], v[50:53], v[98:101]
	v_mfma_f32_16x16x32_bf16 v[62:65], v[118:121], v[62:65], v[110:113]
	s_waitcnt lgkmcnt(0)
	v_mfma_f32_16x16x32_bf16 v[98:101], v[118:121], v[46:49], v[114:117]
	s_nop 0
	v_cvt_pk_bf16_f32 v110, v154, v155
	v_cvt_pk_bf16_f32 v111, v156, v157
	v_cvt_pk_bf16_f32 v112, v159, v160
	v_cvt_pk_bf16_f32 v113, v0, v158
	ds_read_b64_tr_b16 v[46:47], v225 offset:52224
	ds_read_b64_tr_b16 v[48:49], v225 offset:60928
	s_waitcnt lgkmcnt(0)
	v_mfma_f32_16x16x32_bf16 v[34:37], v[110:113], v[46:49], v[34:37]
	ds_read_b64_tr_b16 v[46:47], v225 offset:52256
	ds_read_b64_tr_b16 v[48:49], v225 offset:60960
	v_xor_b32_e32 v0, 1, v229
	s_waitcnt lgkmcnt(0)
	v_mfma_f32_16x16x32_bf16 v[38:41], v[110:113], v[46:49], v[38:41]
	ds_read_b64_tr_b16 v[46:47], v225 offset:52288
	ds_read_b64_tr_b16 v[48:49], v225 offset:60992
	s_waitcnt lgkmcnt(0)
	v_mfma_f32_16x16x32_bf16 v[42:45], v[110:113], v[46:49], v[42:45]
	ds_read_b64_tr_b16 v[46:47], v225 offset:52320
	ds_read_b64_tr_b16 v[48:49], v225 offset:61024
	ds_read_b64_tr_b16 v[82:83], v225 offset:52352
	ds_read_b64_tr_b16 v[84:85], v225 offset:61056
	v_pk_mul_f32 v[128:129], v[38:39], v[38:39]
	s_waitcnt lgkmcnt(0)
	v_mfma_f32_16x16x32_bf16 v[50:53], v[110:113], v[82:85], v[50:53]
	ds_read_b64_tr_b16 v[82:83], v225 offset:52384
	ds_read_b64_tr_b16 v[84:85], v225 offset:61088
	v_pk_fma_f32 v[128:129], v[34:35], v[34:35], v[128:129]
	s_waitcnt lgkmcnt(0)
	v_mfma_f32_16x16x32_bf16 v[54:57], v[110:113], v[82:85], v[54:57]
	ds_read_b64_tr_b16 v[82:83], v225 offset:52416
	ds_read_b64_tr_b16 v[84:85], v225 offset:61120
	v_pk_fma_f32 v[128:129], v[42:43], v[42:43], v[128:129]
	s_waitcnt lgkmcnt(0)
	v_mfma_f32_16x16x32_bf16 v[58:61], v[110:113], v[82:85], v[58:61]
	ds_read_b64_tr_b16 v[82:83], v225 offset:52448
	ds_read_b64_tr_b16 v[84:85], v225 offset:61152
	s_waitcnt lgkmcnt(0)
	v_mfma_f32_16x16x32_bf16 v[62:65], v[110:113], v[82:85], v[62:65]
	ds_read_b64_tr_b16 v[82:83], v225 offset:52480
	ds_read_b64_tr_b16 v[84:85], v225 offset:61184
	s_waitcnt lgkmcnt(0)
	v_mfma_f32_16x16x32_bf16 v[66:69], v[110:113], v[82:85], v[66:69]
	ds_read_b64_tr_b16 v[82:83], v225 offset:52512
	ds_read_b64_tr_b16 v[84:85], v225 offset:61216
	s_waitcnt lgkmcnt(0)
	v_mfma_f32_16x16x32_bf16 v[70:73], v[110:113], v[82:85], v[70:73]
	ds_read_b64_tr_b16 v[82:83], v225 offset:52544
	ds_read_b64_tr_b16 v[84:85], v225 offset:61248
	s_waitcnt lgkmcnt(0)
	v_mfma_f32_16x16x32_bf16 v[74:77], v[110:113], v[82:85], v[74:77]
	ds_read_b64_tr_b16 v[82:83], v225 offset:52576
	ds_read_b64_tr_b16 v[84:85], v225 offset:61280
	s_waitcnt lgkmcnt(0)
	v_mfma_f32_16x16x32_bf16 v[78:81], v[110:113], v[82:85], v[78:81]
	ds_read_b64_tr_b16 v[82:83], v225 offset:52608
	ds_read_b64_tr_b16 v[84:85], v225 offset:61312
	ds_read_b64_tr_b16 v[86:87], v225 offset:52640
	ds_read_b64_tr_b16 v[88:89], v225 offset:61344
	s_waitcnt lgkmcnt(2)
; #define LAS __attribute__((address_space(3)))
; __device__ __forceinline__ unsigned cvt_pk_bf16(float lo, float hi) { const f32x2 v = {lo, hi}; const bf16v2 r = __builtin_convertvector(v, bf16v2); return __builtin_bit_cast(unsigned, r); }
; __device__ void ret_out_phase(LAS unsigned char* lds, const bf16_t* PROJ, const bf16_t* ST, bf16_t* MIX, const float* lgf, const float* lgb, const float* ogain) {
;     ...
;             LAS unsigned char* sl = lds + wave * (16 * RP);
; #pragma unroll
;             for (int j = 0; j < 4; ++j) { float ss = 0.f;
; #pragma unroll
;                 for (int cc = 0; cc < 16; ++cc) ss += o[cc][j] * o[cc][j];
;                 ss += __shfl_xor(ss, 1); ss += __shfl_xor(ss, 2); ss += __shfl_xor(ss, 4); ss += __shfl_xor(ss, 8);
;                 const float rstd = rsqrtf(ss * (1.0f / 256.f) + EPS); const float* og = ogain + h * 256 + fr;
; #pragma unroll
;                 for (int cc = 0; cc < 16; ++cc) *(LAS bf16_t*)(sl + (4 * g + j) * RP + (16 * cc + fr) * 2) = (bf16_t)(cvt_pk_bf16(o[cc][j] * rstd * og[16 * cc], 0.f) & 0xffffu); }
	v_mfma_f32_16x16x32_bf16 v[82:85], v[110:113], v[82:85], v[90:93]
	s_nop 2
	ds_read_b64_tr_b16 v[90:91], v225 offset:52672
	ds_read_b64_tr_b16 v[92:93], v225 offset:61376
	s_nop 2
	v_mov_b32_e32 v130, v83
	s_waitcnt lgkmcnt(2)
	v_mfma_f32_16x16x32_bf16 v[86:89], v[110:113], v[86:89], v[94:97]
	s_nop 2
	ds_read_b64_tr_b16 v[94:95], v225 offset:52704
	ds_read_b64_tr_b16 v[96:97], v225 offset:61408
	s_nop 2
	v_mov_b32_e32 v131, v87
	s_waitcnt lgkmcnt(0)
	v_mfma_f32_16x16x32_bf16 v[94:97], v[110:113], v[94:97], v[98:101]
	v_mul_f32_e64 v130, v130, v130
	v_mul_f32_e64 v131, v131, v131
	s_nop 0
	v_and_b32_e32 v98, 64, v229
	v_add_u32_e32 v98, 64, v98
	v_cmp_lt_i32_e32 vcc, v0, v98
	v_mfma_f32_16x16x32_bf16 v[90:93], v[110:113], v[90:93], v[102:105]
	v_mov_b32_e32 v100, v74
	v_cndmask_b32_e32 v0, v229, v0, vcc
	v_lshlrev_b32_e32 v120, 2, v0
	v_xor_b32_e32 v0, 2, v229
	v_cmp_lt_i32_e32 vcc, v0, v98
	v_mov_b32_e32 v102, v82
	v_mov_b32_e32 v103, v86
	v_cndmask_b32_e32 v0, v229, v0, vcc
	v_lshlrev_b32_e32 v119, 2, v0
	v_xor_b32_e32 v0, 4, v229
	v_cmp_lt_i32_e32 vcc, v0, v98
	v_pk_mul_f32 v[122:123], v[102:103], v[102:103]
	v_mov_b32_e32 v102, v90
	v_cndmask_b32_e32 v0, v229, v0, vcc
	v_lshlrev_b32_e32 v118, 2, v0
	v_xor_b32_e32 v0, 8, v229
	v_cmp_lt_i32_e32 vcc, v0, v98
	v_lshl_add_u64 v[98:99], v[162:163], 0, s[60:61]
	v_mov_b32_e32 v103, v94
	v_cndmask_b32_e32 v0, v229, v0, vcc
	v_mfma_f32_16x16x32_bf16 v[46:49], v[110:113], v[46:49], v[106:109]
	v_lshlrev_b32_e32 v117, 2, v0
	v_pk_mul_f32 v[124:125], v[102:103], v[102:103]
	global_load_dword v116, v[98:99], off
	global_load_dword v115, v[98:99], off offset:64
	global_load_dword v114, v[98:99], off offset:128
	global_load_dword v113, v[98:99], off offset:192
	global_load_dword v112, v[98:99], off offset:256
	global_load_dword v111, v[98:99], off offset:320
	global_load_dword v110, v[98:99], off offset:384
	global_load_dword v109, v[98:99], off offset:448
	global_load_dword v108, v[98:99], off offset:512
	global_load_dword v107, v[98:99], off offset:576
	global_load_dword v106, v[98:99], off offset:640
	global_load_dword v105, v[98:99], off offset:704
	global_load_dword v104, v[98:99], off offset:768
	global_load_dword v103, v[98:99], off offset:832
	global_load_dword v102, v[98:99], off offset:896
	global_load_dword v0, v[98:99], off offset:960
	v_pk_fma_f32 v[128:129], v[46:47], v[46:47], v[128:129]
	v_mov_b32_e32 v101, v78
	v_pk_fma_f32 v[128:129], v[50:51], v[50:51], v[128:129]
	v_mov_b32_e32 v98, v75
	v_pk_fma_f32 v[128:129], v[54:55], v[54:55], v[128:129]
	v_mov_b32_e32 v99, v79
	v_pk_fma_f32 v[128:129], v[58:59], v[58:59], v[128:129]
	v_pk_mul_f32 v[100:101], v[100:101], v[100:101]
	v_pk_fma_f32 v[128:129], v[62:63], v[62:63], v[128:129]
	v_pk_mul_f32 v[126:127], v[98:99], v[98:99]
	v_pk_fma_f32 v[128:129], v[66:67], v[66:67], v[128:129]
	v_mov_b32_e32 v134, v126
	v_pk_fma_f32 v[128:129], v[70:71], v[70:71], v[128:129]
	v_mov_b32_e32 v135, v100
	v_pk_add_f32 v[128:129], v[128:129], v[134:135] op_sel:[1,0] op_sel_hi:[0,1]
	v_mov_b32_e32 v100, v127
	v_mov_b32_e32 v132, v91
	v_mov_b32_e32 v133, v95
	v_pk_add_f32 v[100:101], v[128:129], v[100:101]
	v_mov_b32_e32 v126, v130
	v_mov_b32_e32 v127, v122
	v_pk_mul_f32 v[132:133], v[132:133], v[132:133]
	v_pk_add_f32 v[100:101], v[100:101], v[126:127]
	v_mov_b32_e32 v122, v131
	v_pk_add_f32 v[100:101], v[100:101], v[122:123]
	v_mov_b32_e32 v122, v132
	v_mov_b32_e32 v123, v124
	v_pk_add_f32 v[100:101], v[100:101], v[122:123]
	v_mov_b32_e32 v124, v133
	v_pk_add_f32 v[100:101], v[100:101], v[124:125]
	ds_bpermute_b32 v123, v120, v101
	ds_bpermute_b32 v122, v120, v100
	v_pk_mul_f32 v[98:99], v[40:41], v[40:41]
	s_add_i32 s60, s13, 0x48000
	v_pk_fma_f32 v[98:99], v[36:37], v[36:37], v[98:99]
	s_waitcnt lgkmcnt(0)
	v_pk_add_f32 v[100:101], v[100:101], v[122:123]
	ds_bpermute_b32 v123, v119, v101
	ds_bpermute_b32 v122, v119, v100
	v_pk_fma_f32 v[98:99], v[44:45], v[44:45], v[98:99]
	s_waitcnt lgkmcnt(0)
	v_pk_add_f32 v[100:101], v[100:101], v[122:123]
	ds_bpermute_b32 v123, v118, v101
	ds_bpermute_b32 v122, v118, v100
	v_pk_fma_f32 v[98:99], v[48:49], v[48:49], v[98:99]
	s_waitcnt lgkmcnt(0)
	v_pk_add_f32 v[100:101], v[100:101], v[122:123]
	ds_bpermute_b32 v123, v117, v101
	ds_bpermute_b32 v122, v117, v100
	v_pk_fma_f32 v[98:99], v[52:53], v[52:53], v[98:99]
	s_waitcnt lgkmcnt(0)
	v_pk_add_f32 v[122:123], v[100:101], v[122:123]
	v_mov_b64_e32 v[100:101], s[0:1]
	v_pk_fma_f32 v[122:123], v[122:123], s[14:15], v[100:101] op_sel_hi:[1,0,0]
	v_pk_fma_f32 v[98:99], v[56:57], v[56:57], v[98:99]
	v_mul_f32_e32 v121, 0x4b800000, v123
	v_cmp_gt_f32_e64 s[0:1], s5, v123
	v_cmp_gt_f32_e32 vcc, s5, v122
	v_pk_fma_f32 v[98:99], v[60:61], v[60:61], v[98:99]
	v_cndmask_b32_e64 v121, v123, v121, s[0:1]
	v_rsq_f32_e32 v121, v121
	v_pk_fma_f32 v[98:99], v[64:65], v[64:65], v[98:99]
	v_mul_f32_e32 v123, 0x45800000, v121
	v_cndmask_b32_e64 v121, v121, v123, s[0:1]
	v_mul_f32_e32 v34, v34, v121
	s_waitcnt vmcnt(15)
	v_mul_f32_e32 v34, v116, v34
	v_cvt_pk_bf16_f32 v34, v34, s0
	ds_write_b16 v193, v34
	v_mul_f32_e32 v34, v38, v121
	s_waitcnt vmcnt(14)
	v_mul_f32_e32 v34, v115, v34
	v_cvt_pk_bf16_f32 v34, v34, s0
	ds_write_b16 v193, v34 offset:32
	v_mul_f32_e32 v34, v42, v121
	s_waitcnt vmcnt(13)
	v_mul_f32_e32 v34, v114, v34
	v_cvt_pk_bf16_f32 v34, v34, s0
	ds_write_b16 v193, v34 offset:64
	v_mul_f32_e32 v34, v46, v121
	s_waitcnt vmcnt(12)
	v_mul_f32_e32 v34, v113, v34
	v_cvt_pk_bf16_f32 v34, v34, s0
	ds_write_b16 v193, v34 offset:96
	v_mul_f32_e32 v34, v50, v121
	s_waitcnt vmcnt(11)
	v_mul_f32_e32 v34, v112, v34
	v_cvt_pk_bf16_f32 v34, v34, s0
	ds_write_b16 v193, v34 offset:128
	v_mul_f32_e32 v34, v54, v121
	s_waitcnt vmcnt(10)
; #define LAS __attribute__((address_space(3)))
; __device__ __forceinline__ unsigned cvt_pk_bf16(float lo, float hi) { const f32x2 v = {lo, hi}; const bf16v2 r = __builtin_convertvector(v, bf16v2); return __builtin_bit_cast(unsigned, r); }
; __device__ void ret_out_phase(LAS unsigned char* lds, const bf16_t* PROJ, const bf16_t* ST, bf16_t* MIX, const float* lgf, const float* lgb, const float* ogain) {
;     ...
;             for (int j = 0; j < 4; ++j) { float ss = 0.f;
; #pragma unroll
;                 for (int cc = 0; cc < 16; ++cc) ss += o[cc][j] * o[cc][j];
;                 ss += __shfl_xor(ss, 1); ss += __shfl_xor(ss, 2); ss += __shfl_xor(ss, 4); ss += __shfl_xor(ss, 8);
;                 const float rstd = rsqrtf(ss * (1.0f / 256.f) + EPS); const float* og = ogain + h * 256 + fr;
; #pragma unroll
;                 for (int cc = 0; cc < 16; ++cc) *(LAS bf16_t*)(sl + (4 * g + j) * RP + (16 * cc + fr) * 2) = (bf16_t)(cvt_pk_bf16(o[cc][j] * rstd * og[16 * cc], 0.f) & 0xffffu); }
	v_mul_f32_e32 v34, v34, v111
	v_cvt_pk_bf16_f32 v34, v34, s0
	ds_write_b16 v193, v34 offset:160
	v_mul_f32_e32 v34, v58, v121
	s_waitcnt vmcnt(9)
	v_mul_f32_e32 v34, v34, v110
	v_cvt_pk_bf16_f32 v34, v34, s0
	ds_write_b16 v193, v34 offset:192
	v_mul_f32_e32 v34, v62, v121
	s_waitcnt vmcnt(8)
	v_mul_f32_e32 v34, v34, v109
	v_cvt_pk_bf16_f32 v34, v34, s0
	ds_write_b16 v193, v34 offset:224
	v_mul_f32_e32 v34, v66, v121
	s_waitcnt vmcnt(7)
	v_mul_f32_e32 v34, v34, v108
	v_cvt_pk_bf16_f32 v34, v34, s0
	ds_write_b16 v193, v34 offset:256
	v_mul_f32_e32 v34, v70, v121
	s_waitcnt vmcnt(6)
	v_mul_f32_e32 v34, v34, v107
	v_cvt_pk_bf16_f32 v34, v34, s0
	ds_write_b16 v193, v34 offset:288
	v_mul_f32_e32 v34, v74, v121
	s_waitcnt vmcnt(5)
	v_mul_f32_e32 v34, v34, v106
	v_cvt_pk_bf16_f32 v34, v34, s0
	ds_write_b16 v193, v34 offset:320
	v_mul_f32_e32 v34, v78, v121
	s_waitcnt vmcnt(4)
	v_mul_f32_e32 v34, v34, v105
	v_cvt_pk_bf16_f32 v34, v34, s0
	ds_write_b16 v193, v34 offset:352
	v_mul_f32_e32 v34, v82, v121
	s_waitcnt vmcnt(3)
	v_mul_f32_e32 v34, v34, v104
	v_cvt_pk_bf16_f32 v34, v34, s0
	ds_write_b16 v193, v34 offset:384
	v_mul_f32_e32 v34, v86, v121
	s_waitcnt vmcnt(2)
	v_mul_f32_e32 v34, v34, v103
	v_cvt_pk_bf16_f32 v34, v34, s0
	ds_write_b16 v193, v34 offset:416
	v_mul_f32_e32 v34, v90, v121
	s_waitcnt vmcnt(1)
	v_mul_f32_e32 v34, v34, v102
	v_cvt_pk_bf16_f32 v34, v34, s0
	ds_write_b16 v193, v34 offset:448
	v_mul_f32_e32 v34, v94, v121
	s_waitcnt vmcnt(0)
	v_mul_f32_e32 v34, v34, v0
	v_cvt_pk_bf16_f32 v34, v34, s0
	ds_write_b16 v193, v34 offset:480
	v_mul_f32_e32 v34, 0x4b800000, v122
	v_cndmask_b32_e32 v34, v122, v34, vcc
	v_rsq_f32_e32 v34, v34
	v_mov_b32_e32 v46, v77
	v_pk_fma_f32 v[98:99], v[68:69], v[68:69], v[98:99]
	v_mov_b32_e32 v50, v85
	v_mul_f32_e32 v38, 0x45800000, v34
	v_cndmask_b32_e32 v34, v34, v38, vcc
	v_mul_f32_e32 v35, v35, v34
	v_mul_f32_e32 v35, v116, v35
	v_cvt_pk_bf16_f32 v35, v35, s0
	ds_write_b16 v193, v35 offset:544
	v_mul_f32_e32 v35, v39, v34
	v_mul_f32_e32 v35, v115, v35
	v_cvt_pk_bf16_f32 v35, v35, s0
	ds_write_b16 v193, v35 offset:576
	v_mul_f32_e32 v35, v43, v34
	v_mul_f32_e32 v35, v114, v35
	v_cvt_pk_bf16_f32 v35, v35, s0
	ds_write_b16 v193, v35 offset:608
	v_mul_f32_e32 v35, v47, v34
	v_mul_f32_e32 v35, v113, v35
	v_cvt_pk_bf16_f32 v35, v35, s0
	ds_write_b16 v193, v35 offset:640
	v_mul_f32_e32 v35, v51, v34
	v_mul_f32_e32 v35, v112, v35
	v_cvt_pk_bf16_f32 v35, v35, s0
	ds_write_b16 v193, v35 offset:672
	v_mul_f32_e32 v35, v55, v34
	v_mul_f32_e32 v35, v111, v35
	v_cvt_pk_bf16_f32 v35, v35, s0
	ds_write_b16 v193, v35 offset:704
	v_mul_f32_e32 v35, v59, v34
	v_mul_f32_e32 v35, v110, v35
	v_cvt_pk_bf16_f32 v35, v35, s0
	ds_write_b16 v193, v35 offset:736
	v_mul_f32_e32 v35, v63, v34
	v_mul_f32_e32 v35, v109, v35
	v_cvt_pk_bf16_f32 v35, v35, s0
	ds_write_b16 v193, v35 offset:768
	v_mul_f32_e32 v35, v67, v34
	v_mul_f32_e32 v35, v108, v35
	v_cvt_pk_bf16_f32 v35, v35, s0
	ds_write_b16 v193, v35 offset:800
	v_mul_f32_e32 v35, v71, v34
	v_mul_f32_e32 v35, v107, v35
	v_cvt_pk_bf16_f32 v35, v35, s0
	ds_write_b16 v193, v35 offset:832
	v_mul_f32_e32 v35, v75, v34
	v_mul_f32_e32 v35, v106, v35
	v_cvt_pk_bf16_f32 v35, v35, s0
	ds_write_b16 v193, v35 offset:864
	v_mul_f32_e32 v35, v79, v34
	v_mul_f32_e32 v35, v105, v35
	v_cvt_pk_bf16_f32 v35, v35, s0
	ds_write_b16 v193, v35 offset:896
	v_mul_f32_e32 v35, v83, v34
	v_mul_f32_e32 v35, v104, v35
	v_cvt_pk_bf16_f32 v35, v35, s0
	ds_write_b16 v193, v35 offset:928
	v_mul_f32_e32 v35, v87, v34
	v_mul_f32_e32 v35, v103, v35
	v_cvt_pk_bf16_f32 v35, v35, s0
	ds_write_b16 v193, v35 offset:960
	v_mul_f32_e32 v35, v91, v34
	v_mul_f32_e32 v34, v95, v34
	v_mul_f32_e32 v35, v102, v35
	v_mul_f32_e32 v34, v0, v34
	v_cvt_pk_bf16_f32 v35, v35, s0
	v_cvt_pk_bf16_f32 v34, v34, s0
	ds_write_b16 v193, v35 offset:992
	ds_write_b16 v193, v34 offset:1024
	v_mov_b32_e32 v34, v76
	v_mov_b32_e32 v35, v80
	v_mov_b32_e32 v47, v81
	v_pk_mul_f32 v[34:35], v[34:35], v[34:35]
	v_pk_mul_f32 v[46:47], v[46:47], v[46:47]
	v_pk_fma_f32 v[98:99], v[72:73], v[72:73], v[98:99]
	v_mov_b32_e32 v38, v84
	v_mov_b32_e32 v39, v88
	v_mov_b32_e32 v51, v89
	v_mov_b32_e32 v58, v46
	v_mov_b32_e32 v59, v34
	v_pk_mul_f32 v[38:39], v[38:39], v[38:39]
	v_pk_mul_f32 v[50:51], v[50:51], v[50:51]
	v_pk_add_f32 v[58:59], v[98:99], v[58:59] op_sel:[1,0] op_sel_hi:[0,1]
	v_mov_b32_e32 v34, v47
	v_mov_b32_e32 v42, v92
	v_mov_b32_e32 v43, v96
	v_mov_b32_e32 v54, v93
	v_mov_b32_e32 v55, v97
	v_pk_add_f32 v[34:35], v[58:59], v[34:35]
	v_mov_b32_e32 v46, v50
	v_mov_b32_e32 v47, v38
	v_pk_mul_f32 v[42:43], v[42:43], v[42:43]
	v_pk_mul_f32 v[54:55], v[54:55], v[54:55]
	v_pk_add_f32 v[34:35], v[34:35], v[46:47]
	v_mov_b32_e32 v38, v51
	v_pk_add_f32 v[34:35], v[34:35], v[38:39]
	v_mov_b32_e32 v38, v54
	v_mov_b32_e32 v39, v42
	v_pk_add_f32 v[34:35], v[34:35], v[38:39]
	v_mov_b32_e32 v42, v55
	v_pk_add_f32 v[34:35], v[34:35], v[42:43]
	ds_bpermute_b32 v39, v120, v35
	ds_bpermute_b32 v38, v120, v34
	s_waitcnt lgkmcnt(0)
	v_pk_add_f32 v[34:35], v[34:35], v[38:39]
	ds_bpermute_b32 v39, v119, v35
	ds_bpermute_b32 v38, v119, v34
	s_waitcnt lgkmcnt(0)
	v_pk_add_f32 v[34:35], v[34:35], v[38:39]
	ds_bpermute_b32 v39, v118, v35
	ds_bpermute_b32 v38, v118, v34
	s_waitcnt lgkmcnt(0)
	v_pk_add_f32 v[34:35], v[34:35], v[38:39]
	ds_bpermute_b32 v39, v117, v35
	ds_bpermute_b32 v38, v117, v34
	s_waitcnt lgkmcnt(0)
; #define LAS __attribute__((address_space(3)))
; __device__ __forceinline__ unsigned cvt_pk_bf16(float lo, float hi) { const f32x2 v = {lo, hi}; const bf16v2 r = __builtin_convertvector(v, bf16v2); return __builtin_bit_cast(unsigned, r); }
; __device__ void ret_out_phase(LAS unsigned char* lds, const bf16_t* PROJ, const bf16_t* ST, bf16_t* MIX, const float* lgf, const float* lgb, const float* ogain) {
;     ...
;             for (int j = 0; j < 4; ++j) { float ss = 0.f;
; #pragma unroll
;                 for (int cc = 0; cc < 16; ++cc) ss += o[cc][j] * o[cc][j];
;                 ss += __shfl_xor(ss, 1); ss += __shfl_xor(ss, 2); ss += __shfl_xor(ss, 4); ss += __shfl_xor(ss, 8);
;                 const float rstd = rsqrtf(ss * (1.0f / 256.f) + EPS); const float* og = ogain + h * 256 + fr;
; #pragma unroll
;                 for (int cc = 0; cc < 16; ++cc) *(LAS bf16_t*)(sl + (4 * g + j) * RP + (16 * cc + fr) * 2) = (bf16_t)(cvt_pk_bf16(o[cc][j] * rstd * og[16 * cc], 0.f) & 0xffffu); }
;             asm volatile("s_waitcnt lgkmcnt(0)" ::: "memory");
;             const int rw = lane >> 2; const size_t tok = (size_t)qt * 128 + 16 * wave + rw;
;             const bf16_t* gp = PROJ + pj(tok, 6144 + h * 256); bf16_t* mp = MIX + tok * DM + 1024 + h * 256;
; #pragma unroll
;             for (int i = 0; i < 8; ++i) { const int ch = (lane & 3) + 4 * i; const u32x4 y = *(const LAS u32x4*)(sl + rw * RP + 16 * ch); const u32x4 gt = *(const u32x4*)(gp + 8 * ch); u32x4 w;
	v_pk_add_f32 v[34:35], v[34:35], v[38:39]
	s_nop 0
	v_pk_fma_f32 v[34:35], v[34:35], s[14:15], v[100:101] op_sel_hi:[1,0,0]
	s_nop 0
	v_mul_f32_e32 v38, 0x4b800000, v35
	v_cmp_gt_f32_e64 s[0:1], s5, v35
	v_cmp_gt_f32_e32 vcc, s5, v34
	s_nop 0
	v_cndmask_b32_e64 v35, v35, v38, s[0:1]
	v_rsq_f32_e32 v35, v35
	s_nop 0
	v_mul_f32_e32 v38, 0x45800000, v35
	v_cndmask_b32_e64 v35, v35, v38, s[0:1]
	v_mul_f32_e32 v36, v36, v35
	v_mul_f32_e32 v36, v116, v36
	v_cvt_pk_bf16_f32 v36, v36, s0
	ds_write_b16 v193, v36 offset:1088
	v_mul_f32_e32 v36, v40, v35
	v_mul_f32_e32 v36, v115, v36
	v_cvt_pk_bf16_f32 v36, v36, s0
	ds_write_b16 v193, v36 offset:1120
	v_mul_f32_e32 v36, v44, v35
	v_mul_f32_e32 v36, v114, v36
	v_cvt_pk_bf16_f32 v36, v36, s0
	ds_write_b16 v193, v36 offset:1152
	v_mul_f32_e32 v36, v48, v35
	v_mul_f32_e32 v36, v113, v36
	v_cvt_pk_bf16_f32 v36, v36, s0
	ds_write_b16 v193, v36 offset:1184
	v_mul_f32_e32 v36, v52, v35
	v_mul_f32_e32 v36, v112, v36
	v_cvt_pk_bf16_f32 v36, v36, s0
	ds_write_b16 v193, v36 offset:1216
	v_mul_f32_e32 v36, v56, v35
	v_mul_f32_e32 v36, v111, v36
	v_cvt_pk_bf16_f32 v36, v36, s0
	ds_write_b16 v193, v36 offset:1248
	v_mul_f32_e32 v36, v60, v35
	v_mul_f32_e32 v36, v110, v36
	v_cvt_pk_bf16_f32 v36, v36, s0
	ds_write_b16 v193, v36 offset:1280
	v_mul_f32_e32 v36, v64, v35
	v_mul_f32_e32 v36, v109, v36
	v_cvt_pk_bf16_f32 v36, v36, s0
	ds_write_b16 v193, v36 offset:1312
	v_mul_f32_e32 v36, v68, v35
	v_mul_f32_e32 v36, v108, v36
	v_cvt_pk_bf16_f32 v36, v36, s0
	ds_write_b16 v193, v36 offset:1344
	v_mul_f32_e32 v36, v72, v35
	v_mul_f32_e32 v36, v107, v36
	v_cvt_pk_bf16_f32 v36, v36, s0
	ds_write_b16 v193, v36 offset:1376
	v_mul_f32_e32 v36, v76, v35
	v_mul_f32_e32 v36, v106, v36
	v_cvt_pk_bf16_f32 v36, v36, s0
	ds_write_b16 v193, v36 offset:1408
	v_mul_f32_e32 v36, v80, v35
	v_mul_f32_e32 v36, v105, v36
	v_cvt_pk_bf16_f32 v36, v36, s0
	ds_write_b16 v193, v36 offset:1440
	v_mul_f32_e32 v36, v84, v35
	v_mul_f32_e32 v36, v104, v36
	v_cvt_pk_bf16_f32 v36, v36, s0
	ds_write_b16 v193, v36 offset:1472
	v_mul_f32_e32 v36, v88, v35
	v_mul_f32_e32 v36, v103, v36
	v_cvt_pk_bf16_f32 v36, v36, s0
	ds_write_b16 v193, v36 offset:1504
	v_mul_f32_e32 v36, v92, v35
	v_mul_f32_e32 v35, v96, v35
	v_mul_f32_e32 v35, v0, v35
	v_cvt_pk_bf16_f32 v35, v35, s0
	ds_write_b16 v193, v35 offset:1568
	v_mul_f32_e32 v35, 0x4b800000, v34
	v_cndmask_b32_e32 v34, v34, v35, vcc
	v_rsq_f32_e32 v34, v34
	v_mul_f32_e32 v36, v102, v36
	v_cvt_pk_bf16_f32 v36, v36, s0
	ds_write_b16 v193, v36 offset:1536
	v_mul_f32_e32 v35, 0x45800000, v34
	v_cndmask_b32_e32 v34, v34, v35, vcc
	v_mul_f32_e32 v35, v37, v34
	v_mul_f32_e32 v35, v116, v35
	v_cvt_pk_bf16_f32 v35, v35, s0
	ds_write_b16 v193, v35 offset:1632
	v_mul_f32_e32 v35, v41, v34
	v_mul_f32_e32 v35, v115, v35
	v_cvt_pk_bf16_f32 v35, v35, s0
	ds_write_b16 v193, v35 offset:1664
	v_mul_f32_e32 v35, v45, v34
	v_mul_f32_e32 v35, v114, v35
	v_cvt_pk_bf16_f32 v35, v35, s0
	ds_write_b16 v193, v35 offset:1696
	v_mul_f32_e32 v35, v49, v34
	v_mul_f32_e32 v35, v113, v35
	v_cvt_pk_bf16_f32 v35, v35, s0
	ds_write_b16 v193, v35 offset:1728
	v_mul_f32_e32 v35, v53, v34
	v_mul_f32_e32 v35, v112, v35
	v_cvt_pk_bf16_f32 v35, v35, s0
	ds_write_b16 v193, v35 offset:1760
	v_mul_f32_e32 v35, v57, v34
	v_mul_f32_e32 v35, v111, v35
	v_cvt_pk_bf16_f32 v35, v35, s0
	ds_write_b16 v193, v35 offset:1792
	v_mul_f32_e32 v35, v61, v34
	v_mul_f32_e32 v35, v110, v35
	v_cvt_pk_bf16_f32 v35, v35, s0
	ds_write_b16 v193, v35 offset:1824
	v_mul_f32_e32 v35, v65, v34
	v_mul_f32_e32 v35, v109, v35
	v_cvt_pk_bf16_f32 v35, v35, s0
	ds_write_b16 v193, v35 offset:1856
	v_mul_f32_e32 v35, v69, v34
	v_mul_f32_e32 v35, v108, v35
	v_cvt_pk_bf16_f32 v35, v35, s0
	ds_write_b16 v193, v35 offset:1888
	v_mul_f32_e32 v35, v73, v34
	v_mul_f32_e32 v35, v107, v35
	v_cvt_pk_bf16_f32 v35, v35, s0
	ds_write_b16 v193, v35 offset:1920
	v_mul_f32_e32 v35, v77, v34
	v_mul_f32_e32 v35, v106, v35
	v_cvt_pk_bf16_f32 v35, v35, s0
	ds_write_b16 v193, v35 offset:1952
	v_mul_f32_e32 v35, v81, v34
	v_mul_f32_e32 v35, v105, v35
	v_cvt_pk_bf16_f32 v35, v35, s0
	ds_write_b16 v193, v35 offset:1984
	v_mul_f32_e32 v35, v85, v34
	v_mul_f32_e32 v35, v104, v35
	v_cvt_pk_bf16_f32 v35, v35, s0
	ds_write_b16 v193, v35 offset:2016
	v_mul_f32_e32 v35, v89, v34
	v_mul_f32_e32 v35, v103, v35
	v_cvt_pk_bf16_f32 v35, v35, s0
	ds_write_b16 v193, v35 offset:2048
	v_mul_f32_e32 v35, v93, v34
	v_mul_f32_e32 v35, v102, v35
	v_cvt_pk_bf16_f32 v35, v35, s0
	v_mul_f32_e32 v34, v97, v34
	ds_write_b16 v193, v35 offset:2080
	v_mul_f32_e32 v0, v0, v34
	v_mov_b32_e32 v35, s3
	v_or_b32_e32 v34, s2, v164
	v_lshl_add_u64 v[36:37], v[34:35], 0, s[60:61]
	v_lshlrev_b64 v[36:37], 9, v[36:37]
	v_cvt_pk_bf16_f32 v0, v0, s0
	v_lshl_add_u64 v[36:37], s[78:79], 0, v[36:37]
	ds_write_b16 v193, v0 offset:2112
	v_lshl_add_u64 v[38:39], v[36:37], 0, s[16:17]
	s_waitcnt lgkmcnt(0)
	v_lshl_add_u64 v[40:41], v[38:39], 0, v[168:169]
	global_load_dwordx4 v[44:47], v[40:41], off
	v_lshl_add_u64 v[124:125], v[38:39], 0, v[170:171]
	global_load_dwordx4 v[100:103], v[124:125], off
	v_lshl_add_u64 v[126:127], v[38:39], 0, v[172:173]
	global_load_dwordx4 v[104:107], v[126:127], off
	v_lshl_add_u64 v[128:129], v[38:39], 0, v[174:175]
	global_load_dwordx4 v[108:111], v[128:129], off
	v_lshl_add_u64 v[130:131], v[38:39], 0, v[176:177]
	global_load_dwordx4 v[112:115], v[130:131], off
	v_lshl_add_u64 v[132:133], v[38:39], 0, v[178:179]
	global_load_dwordx4 v[116:119], v[132:133], off
	v_lshl_add_u64 v[134:135], v[38:39], 0, v[180:181]
	global_load_dwordx4 v[120:123], v[134:135], off
	v_lshlrev_b64 v[34:35], 12, v[34:35]
	v_lshl_add_u64 v[34:35], s[76:77], 0, v[34:35]
	s_lshl_b32 s60, s12, 9
	v_lshl_add_u64 v[42:43], v[34:35], 0, s[60:61]
	ds_read_b128 v[34:37], v202
	s_waitcnt lgkmcnt(0)
; #define LAS __attribute__((address_space(3)))
; __device__ __forceinline__ unsigned cvt_pk_bf16(float lo, float hi) { const f32x2 v = {lo, hi}; const bf16v2 r = __builtin_convertvector(v, bf16v2); return __builtin_bit_cast(unsigned, r); }
; __device__ __forceinline__ float bf_lo(unsigned u) { return __uint_as_float(u << 16); }
; __device__ __forceinline__ float bf_hi(unsigned u) { return __uint_as_float(u & 0xffff0000u); }
; __device__ __forceinline__ float silu_f(float g) { return g * __builtin_amdgcn_rcpf(1.0f + __expf(-g)); }
; __device__ void ret_out_phase(LAS unsigned char* lds, const bf16_t* PROJ, const bf16_t* ST, bf16_t* MIX, const float* lgf, const float* lgb, const float* ogain) {
;     ...
;             const int rw = lane >> 2; const size_t tok = (size_t)qt * 128 + 16 * wave + rw;
;             const bf16_t* gp = PROJ + pj(tok, 6144 + h * 256); bf16_t* mp = MIX + tok * DM + 1024 + h * 256;
; #pragma unroll
;             for (int i = 0; i < 8; ++i) { const int ch = (lane & 3) + 4 * i; const u32x4 y = *(const LAS u32x4*)(sl + rw * RP + 16 * ch); const u32x4 gt = *(const u32x4*)(gp + 8 * ch); u32x4 w;
; #pragma unroll
;                 for (int e = 0; e < 4; ++e) w[e] = cvt_pk_bf16(bf_lo(y[e]) * silu_f(bf_lo(gt[e])), bf_hi(y[e]) * silu_f(bf_hi(gt[e])));
;                 *(u32x4*)(mp + 8 * ch) = w; }
	v_lshlrev_b32_e32 v50, 16, v34
	v_and_b32_e32 v51, 0xffff0000, v34
	s_waitcnt vmcnt(6)
	v_lshlrev_b32_e32 v40, 16, v44
	v_mul_f32_e32 v0, 0xbfb8aa3b, v40
	v_exp_f32_e32 v0, v0
	v_and_b32_e32 v41, 0xffff0000, v44
	v_add_f32_e32 v0, 1.0, v0
	v_rcp_f32_e32 v48, v0
	v_mul_f32_e32 v0, 0xbfb8aa3b, v41
	v_exp_f32_e32 v0, v0
	s_nop 0
	v_add_f32_e32 v0, 1.0, v0
	v_rcp_f32_e32 v49, v0
	s_nop 0
	v_pk_mul_f32 v[40:41], v[48:49], v[40:41]
	s_nop 0
	v_pk_mul_f32 v[40:41], v[40:41], v[50:51]
	v_lshlrev_b32_e32 v48, 16, v35
	v_cvt_pk_bf16_f32 v34, v40, v41
	v_lshlrev_b32_e32 v40, 16, v45
	v_mul_f32_e32 v0, 0xbfb8aa3b, v40
	v_exp_f32_e32 v0, v0
	v_and_b32_e32 v41, 0xffff0000, v45
	v_and_b32_e32 v49, 0xffff0000, v35
	v_add_f32_e32 v0, 1.0, v0
	v_rcp_f32_e32 v44, v0
	v_mul_f32_e32 v0, 0xbfb8aa3b, v41
	v_exp_f32_e32 v0, v0
	s_nop 0
	v_add_f32_e32 v0, 1.0, v0
	v_rcp_f32_e32 v45, v0
	s_nop 0
	v_pk_mul_f32 v[40:41], v[44:45], v[40:41]
	s_nop 0
	v_pk_mul_f32 v[40:41], v[40:41], v[48:49]
	v_lshlrev_b32_e32 v48, 16, v36
	v_cvt_pk_bf16_f32 v35, v40, v41
	v_lshlrev_b32_e32 v40, 16, v46
	v_mul_f32_e32 v0, 0xbfb8aa3b, v40
	v_exp_f32_e32 v0, v0
	v_and_b32_e32 v41, 0xffff0000, v46
	v_and_b32_e32 v49, 0xffff0000, v36
	v_lshlrev_b32_e32 v46, 16, v37
	v_add_f32_e32 v0, 1.0, v0
	v_rcp_f32_e32 v44, v0
	v_mul_f32_e32 v0, 0xbfb8aa3b, v41
	v_exp_f32_e32 v0, v0
	s_nop 0
	v_add_f32_e32 v0, 1.0, v0
	v_rcp_f32_e32 v45, v0
	s_nop 0
	v_pk_mul_f32 v[40:41], v[44:45], v[40:41]
	s_nop 0
	v_pk_mul_f32 v[40:41], v[40:41], v[48:49]
	s_nop 0
	v_cvt_pk_bf16_f32 v36, v40, v41
	v_lshlrev_b32_e32 v40, 16, v47
	v_mul_f32_e32 v0, 0xbfb8aa3b, v40
	v_exp_f32_e32 v0, v0
	v_and_b32_e32 v41, 0xffff0000, v47
	v_and_b32_e32 v47, 0xffff0000, v37
	v_add_f32_e32 v0, 1.0, v0
	v_rcp_f32_e32 v44, v0
	v_mul_f32_e32 v0, 0xbfb8aa3b, v41
	v_exp_f32_e32 v0, v0
	s_nop 0
	v_add_f32_e32 v0, 1.0, v0
	v_rcp_f32_e32 v45, v0
	s_nop 0
	v_pk_mul_f32 v[40:41], v[44:45], v[40:41]
	s_nop 0
	v_pk_mul_f32 v[40:41], v[40:41], v[46:47]
	s_nop 0
	v_cvt_pk_bf16_f32 v37, v40, v41
	v_lshl_add_u64 v[40:41], v[42:43], 0, v[168:169]
	global_store_dwordx4 v[40:41], v[34:37], off offset:2048
	s_nop 0
	s_nop 0
	ds_read_b128 v[34:37], v203
	s_waitcnt lgkmcnt(0)
	v_lshlrev_b32_e32 v50, 16, v34
	v_and_b32_e32 v51, 0xffff0000, v34
	s_waitcnt vmcnt(6)
	v_lshlrev_b32_e32 v40, 16, v100
	v_mul_f32_e32 v0, 0xbfb8aa3b, v40
	v_exp_f32_e32 v0, v0
	v_and_b32_e32 v41, 0xffff0000, v100
	v_add_f32_e32 v0, 1.0, v0
	v_rcp_f32_e32 v48, v0
	v_mul_f32_e32 v0, 0xbfb8aa3b, v41
	v_exp_f32_e32 v0, v0
	s_nop 0
	v_add_f32_e32 v0, 1.0, v0
	v_rcp_f32_e32 v49, v0
	s_nop 0
	v_pk_mul_f32 v[40:41], v[48:49], v[40:41]
	s_nop 0
	v_pk_mul_f32 v[40:41], v[40:41], v[50:51]
	v_lshlrev_b32_e32 v48, 16, v35
	v_cvt_pk_bf16_f32 v34, v40, v41
	v_lshlrev_b32_e32 v40, 16, v101
	v_mul_f32_e32 v0, 0xbfb8aa3b, v40
	v_exp_f32_e32 v0, v0
	v_and_b32_e32 v41, 0xffff0000, v101
	v_and_b32_e32 v49, 0xffff0000, v35
	v_add_f32_e32 v0, 1.0, v0
	v_rcp_f32_e32 v100, v0
	v_mul_f32_e32 v0, 0xbfb8aa3b, v41
	v_exp_f32_e32 v0, v0
	s_nop 0
	v_add_f32_e32 v0, 1.0, v0
	v_rcp_f32_e32 v101, v0
	s_nop 0
	v_pk_mul_f32 v[40:41], v[100:101], v[40:41]
	s_nop 0
	v_pk_mul_f32 v[40:41], v[40:41], v[48:49]
	v_lshlrev_b32_e32 v48, 16, v36
	v_cvt_pk_bf16_f32 v35, v40, v41
	v_lshlrev_b32_e32 v40, 16, v102
	v_mul_f32_e32 v0, 0xbfb8aa3b, v40
	v_exp_f32_e32 v0, v0
	v_and_b32_e32 v41, 0xffff0000, v102
	v_and_b32_e32 v49, 0xffff0000, v36
	v_lshlrev_b32_e32 v102, 16, v37
	v_add_f32_e32 v0, 1.0, v0
	v_rcp_f32_e32 v100, v0
	v_mul_f32_e32 v0, 0xbfb8aa3b, v41
	v_exp_f32_e32 v0, v0
	s_nop 0
	v_add_f32_e32 v0, 1.0, v0
	v_rcp_f32_e32 v101, v0
	s_nop 0
	v_pk_mul_f32 v[40:41], v[100:101], v[40:41]
	s_nop 0
	v_pk_mul_f32 v[40:41], v[40:41], v[48:49]
	s_nop 0
	v_cvt_pk_bf16_f32 v36, v40, v41
	v_lshlrev_b32_e32 v40, 16, v103
	v_mul_f32_e32 v0, 0xbfb8aa3b, v40
	v_exp_f32_e32 v0, v0
	v_and_b32_e32 v41, 0xffff0000, v103
	v_and_b32_e32 v103, 0xffff0000, v37
	v_add_f32_e32 v0, 1.0, v0
	v_rcp_f32_e32 v100, v0
	v_mul_f32_e32 v0, 0xbfb8aa3b, v41
	v_exp_f32_e32 v0, v0
	s_nop 0
	v_add_f32_e32 v0, 1.0, v0
	v_rcp_f32_e32 v101, v0
	s_nop 0
	v_pk_mul_f32 v[40:41], v[100:101], v[40:41]
	s_nop 0
	v_pk_mul_f32 v[40:41], v[40:41], v[102:103]
	s_nop 0
	v_cvt_pk_bf16_f32 v37, v40, v41
	v_lshl_add_u64 v[40:41], v[42:43], 0, v[170:171]
	global_store_dwordx4 v[40:41], v[34:37], off offset:2048
	s_nop 0
	s_nop 0
	ds_read_b128 v[34:37], v204
	s_waitcnt lgkmcnt(0)
	v_lshlrev_b32_e32 v50, 16, v34
	v_and_b32_e32 v51, 0xffff0000, v34
	s_waitcnt vmcnt(6)
	v_lshlrev_b32_e32 v40, 16, v104
	v_mul_f32_e32 v0, 0xbfb8aa3b, v40
	v_exp_f32_e32 v0, v0
	v_and_b32_e32 v41, 0xffff0000, v104
	v_add_f32_e32 v0, 1.0, v0
	v_rcp_f32_e32 v48, v0
	v_mul_f32_e32 v0, 0xbfb8aa3b, v41
	v_exp_f32_e32 v0, v0
	s_nop 0
	v_add_f32_e32 v0, 1.0, v0
	v_rcp_f32_e32 v49, v0
	s_nop 0
	v_pk_mul_f32 v[40:41], v[48:49], v[40:41]
	s_nop 0
	v_pk_mul_f32 v[40:41], v[40:41], v[50:51]
	v_lshlrev_b32_e32 v48, 16, v35
	v_cvt_pk_bf16_f32 v34, v40, v41
	v_lshlrev_b32_e32 v40, 16, v105
	v_mul_f32_e32 v0, 0xbfb8aa3b, v40
	v_exp_f32_e32 v0, v0
	v_and_b32_e32 v41, 0xffff0000, v105
	v_and_b32_e32 v49, 0xffff0000, v35
	v_add_f32_e32 v0, 1.0, v0
	v_rcp_f32_e32 v104, v0
	v_mul_f32_e32 v0, 0xbfb8aa3b, v41
	v_exp_f32_e32 v0, v0
	s_nop 0
	v_add_f32_e32 v0, 1.0, v0
	v_rcp_f32_e32 v105, v0
	s_nop 0
	v_pk_mul_f32 v[40:41], v[104:105], v[40:41]
	s_nop 0
	v_pk_mul_f32 v[40:41], v[40:41], v[48:49]
	v_lshlrev_b32_e32 v48, 16, v36
	v_cvt_pk_bf16_f32 v35, v40, v41
	v_lshlrev_b32_e32 v40, 16, v106
	v_mul_f32_e32 v0, 0xbfb8aa3b, v40
	v_exp_f32_e32 v0, v0
	v_and_b32_e32 v41, 0xffff0000, v106
	v_and_b32_e32 v49, 0xffff0000, v36
	v_lshlrev_b32_e32 v106, 16, v37
	v_add_f32_e32 v0, 1.0, v0
	v_rcp_f32_e32 v104, v0
	v_mul_f32_e32 v0, 0xbfb8aa3b, v41
	v_exp_f32_e32 v0, v0
	s_nop 0
	v_add_f32_e32 v0, 1.0, v0
	v_rcp_f32_e32 v105, v0
	s_nop 0
	v_pk_mul_f32 v[40:41], v[104:105], v[40:41]
	s_nop 0
	v_pk_mul_f32 v[40:41], v[40:41], v[48:49]
	s_nop 0
	v_cvt_pk_bf16_f32 v36, v40, v41
	v_lshlrev_b32_e32 v40, 16, v107
	v_mul_f32_e32 v0, 0xbfb8aa3b, v40
	v_exp_f32_e32 v0, v0
	v_and_b32_e32 v41, 0xffff0000, v107
	v_and_b32_e32 v107, 0xffff0000, v37
	v_add_f32_e32 v0, 1.0, v0
	v_rcp_f32_e32 v104, v0
	v_mul_f32_e32 v0, 0xbfb8aa3b, v41
	v_exp_f32_e32 v0, v0
	s_nop 0
	v_add_f32_e32 v0, 1.0, v0
	v_rcp_f32_e32 v105, v0
	s_nop 0
	v_pk_mul_f32 v[40:41], v[104:105], v[40:41]
	s_nop 0
	v_pk_mul_f32 v[40:41], v[40:41], v[106:107]
	s_nop 0
	v_cvt_pk_bf16_f32 v37, v40, v41
	v_lshl_add_u64 v[40:41], v[42:43], 0, v[172:173]
	global_store_dwordx4 v[40:41], v[34:37], off offset:2048
	s_nop 0
	s_nop 0
	ds_read_b128 v[34:37], v205
	s_waitcnt lgkmcnt(0)
; #define LAS __attribute__((address_space(3)))
; __device__ __forceinline__ unsigned cvt_pk_bf16(float lo, float hi) { const f32x2 v = {lo, hi}; const bf16v2 r = __builtin_convertvector(v, bf16v2); return __builtin_bit_cast(unsigned, r); }
; __device__ __forceinline__ float bf_lo(unsigned u) { return __uint_as_float(u << 16); }
; __device__ __forceinline__ float bf_hi(unsigned u) { return __uint_as_float(u & 0xffff0000u); }
; __device__ __forceinline__ float silu_f(float g) { return g * __builtin_amdgcn_rcpf(1.0f + __expf(-g)); }
; __device__ void ret_out_phase(LAS unsigned char* lds, const bf16_t* PROJ, const bf16_t* ST, bf16_t* MIX, const float* lgf, const float* lgb, const float* ogain) {
;     ...
;             const int rw = lane >> 2; const size_t tok = (size_t)qt * 128 + 16 * wave + rw;
;             const bf16_t* gp = PROJ + pj(tok, 6144 + h * 256); bf16_t* mp = MIX + tok * DM + 1024 + h * 256;
; #pragma unroll
;             for (int i = 0; i < 8; ++i) { const int ch = (lane & 3) + 4 * i; const u32x4 y = *(const LAS u32x4*)(sl + rw * RP + 16 * ch); const u32x4 gt = *(const u32x4*)(gp + 8 * ch); u32x4 w;
; #pragma unroll
;                 for (int e = 0; e < 4; ++e) w[e] = cvt_pk_bf16(bf_lo(y[e]) * silu_f(bf_lo(gt[e])), bf_hi(y[e]) * silu_f(bf_hi(gt[e])));
;                 *(u32x4*)(mp + 8 * ch) = w; }
	v_lshlrev_b32_e32 v50, 16, v34
	v_and_b32_e32 v51, 0xffff0000, v34
	s_waitcnt vmcnt(6)
	v_lshlrev_b32_e32 v40, 16, v108
	v_mul_f32_e32 v0, 0xbfb8aa3b, v40
	v_exp_f32_e32 v0, v0
	v_and_b32_e32 v41, 0xffff0000, v108
	v_add_f32_e32 v0, 1.0, v0
	v_rcp_f32_e32 v48, v0
	v_mul_f32_e32 v0, 0xbfb8aa3b, v41
	v_exp_f32_e32 v0, v0
	s_nop 0
	v_add_f32_e32 v0, 1.0, v0
	v_rcp_f32_e32 v49, v0
	s_nop 0
	v_pk_mul_f32 v[40:41], v[48:49], v[40:41]
	s_nop 0
	v_pk_mul_f32 v[40:41], v[40:41], v[50:51]
	v_lshlrev_b32_e32 v48, 16, v35
	v_cvt_pk_bf16_f32 v34, v40, v41
	v_lshlrev_b32_e32 v40, 16, v109
	v_mul_f32_e32 v0, 0xbfb8aa3b, v40
	v_exp_f32_e32 v0, v0
	v_and_b32_e32 v41, 0xffff0000, v109
	v_and_b32_e32 v49, 0xffff0000, v35
	v_add_f32_e32 v0, 1.0, v0
	v_rcp_f32_e32 v108, v0
	v_mul_f32_e32 v0, 0xbfb8aa3b, v41
	v_exp_f32_e32 v0, v0
	s_nop 0
	v_add_f32_e32 v0, 1.0, v0
	v_rcp_f32_e32 v109, v0
	s_nop 0
	v_pk_mul_f32 v[40:41], v[108:109], v[40:41]
	s_nop 0
	v_pk_mul_f32 v[40:41], v[40:41], v[48:49]
	v_lshlrev_b32_e32 v48, 16, v36
	v_cvt_pk_bf16_f32 v35, v40, v41
	v_lshlrev_b32_e32 v40, 16, v110
	v_mul_f32_e32 v0, 0xbfb8aa3b, v40
	v_exp_f32_e32 v0, v0
	v_and_b32_e32 v41, 0xffff0000, v110
	v_and_b32_e32 v49, 0xffff0000, v36
	v_lshlrev_b32_e32 v110, 16, v37
	v_add_f32_e32 v0, 1.0, v0
	v_rcp_f32_e32 v108, v0
	v_mul_f32_e32 v0, 0xbfb8aa3b, v41
	v_exp_f32_e32 v0, v0
	s_nop 0
	v_add_f32_e32 v0, 1.0, v0
	v_rcp_f32_e32 v109, v0
	s_nop 0
	v_pk_mul_f32 v[40:41], v[108:109], v[40:41]
	s_nop 0
	v_pk_mul_f32 v[40:41], v[40:41], v[48:49]
	s_nop 0
	v_cvt_pk_bf16_f32 v36, v40, v41
	v_lshlrev_b32_e32 v40, 16, v111
	v_mul_f32_e32 v0, 0xbfb8aa3b, v40
	v_exp_f32_e32 v0, v0
	v_and_b32_e32 v41, 0xffff0000, v111
	v_and_b32_e32 v111, 0xffff0000, v37
	v_add_f32_e32 v0, 1.0, v0
	v_rcp_f32_e32 v108, v0
	v_mul_f32_e32 v0, 0xbfb8aa3b, v41
	v_exp_f32_e32 v0, v0
	s_nop 0
	v_add_f32_e32 v0, 1.0, v0
	v_rcp_f32_e32 v109, v0
	s_nop 0
	v_pk_mul_f32 v[40:41], v[108:109], v[40:41]
	s_nop 0
	v_pk_mul_f32 v[40:41], v[40:41], v[110:111]
	s_nop 0
	v_cvt_pk_bf16_f32 v37, v40, v41
	v_lshl_add_u64 v[40:41], v[42:43], 0, v[174:175]
	global_store_dwordx4 v[40:41], v[34:37], off offset:2048
	s_nop 0
	s_nop 0
	ds_read_b128 v[34:37], v206
	s_waitcnt lgkmcnt(0)
	v_lshlrev_b32_e32 v50, 16, v34
	v_and_b32_e32 v51, 0xffff0000, v34
	s_waitcnt vmcnt(6)
	v_lshlrev_b32_e32 v40, 16, v112
	v_mul_f32_e32 v0, 0xbfb8aa3b, v40
	v_exp_f32_e32 v0, v0
	v_and_b32_e32 v41, 0xffff0000, v112
	v_add_f32_e32 v0, 1.0, v0
	v_rcp_f32_e32 v48, v0
	v_mul_f32_e32 v0, 0xbfb8aa3b, v41
	v_exp_f32_e32 v0, v0
	s_nop 0
	v_add_f32_e32 v0, 1.0, v0
	v_rcp_f32_e32 v49, v0
	s_nop 0
	v_pk_mul_f32 v[40:41], v[48:49], v[40:41]
	s_nop 0
	v_pk_mul_f32 v[40:41], v[40:41], v[50:51]
	v_lshlrev_b32_e32 v48, 16, v35
	v_cvt_pk_bf16_f32 v34, v40, v41
	v_lshlrev_b32_e32 v40, 16, v113
	v_mul_f32_e32 v0, 0xbfb8aa3b, v40
	v_exp_f32_e32 v0, v0
	v_and_b32_e32 v41, 0xffff0000, v113
	v_and_b32_e32 v49, 0xffff0000, v35
	v_add_f32_e32 v0, 1.0, v0
	v_rcp_f32_e32 v112, v0
	v_mul_f32_e32 v0, 0xbfb8aa3b, v41
	v_exp_f32_e32 v0, v0
	s_nop 0
	v_add_f32_e32 v0, 1.0, v0
	v_rcp_f32_e32 v113, v0
	s_nop 0
	v_pk_mul_f32 v[40:41], v[112:113], v[40:41]
	s_nop 0
	v_pk_mul_f32 v[40:41], v[40:41], v[48:49]
	v_lshlrev_b32_e32 v48, 16, v36
	v_cvt_pk_bf16_f32 v35, v40, v41
	v_lshlrev_b32_e32 v40, 16, v114
	v_mul_f32_e32 v0, 0xbfb8aa3b, v40
	v_exp_f32_e32 v0, v0
	v_and_b32_e32 v41, 0xffff0000, v114
	v_and_b32_e32 v49, 0xffff0000, v36
	v_lshlrev_b32_e32 v114, 16, v37
	v_add_f32_e32 v0, 1.0, v0
	v_rcp_f32_e32 v112, v0
	v_mul_f32_e32 v0, 0xbfb8aa3b, v41
	v_exp_f32_e32 v0, v0
	s_nop 0
	v_add_f32_e32 v0, 1.0, v0
	v_rcp_f32_e32 v113, v0
	s_nop 0
	v_pk_mul_f32 v[40:41], v[112:113], v[40:41]
	s_nop 0
	v_pk_mul_f32 v[40:41], v[40:41], v[48:49]
	s_nop 0
	v_cvt_pk_bf16_f32 v36, v40, v41
	v_lshlrev_b32_e32 v40, 16, v115
	v_mul_f32_e32 v0, 0xbfb8aa3b, v40
	v_exp_f32_e32 v0, v0
	v_and_b32_e32 v41, 0xffff0000, v115
	v_and_b32_e32 v115, 0xffff0000, v37
	v_add_f32_e32 v0, 1.0, v0
	v_rcp_f32_e32 v112, v0
	v_mul_f32_e32 v0, 0xbfb8aa3b, v41
	v_exp_f32_e32 v0, v0
	s_nop 0
	v_add_f32_e32 v0, 1.0, v0
	v_rcp_f32_e32 v113, v0
	s_nop 0
	v_pk_mul_f32 v[40:41], v[112:113], v[40:41]
	s_nop 0
	v_pk_mul_f32 v[40:41], v[40:41], v[114:115]
	s_nop 0
	v_cvt_pk_bf16_f32 v37, v40, v41
	v_lshl_add_u64 v[40:41], v[42:43], 0, v[176:177]
	global_store_dwordx4 v[40:41], v[34:37], off offset:2048
	s_nop 0
	s_nop 0
	ds_read_b128 v[34:37], v207
	s_waitcnt lgkmcnt(0)
	v_lshlrev_b32_e32 v50, 16, v34
	v_and_b32_e32 v51, 0xffff0000, v34
	s_waitcnt vmcnt(6)
	v_lshlrev_b32_e32 v40, 16, v116
	v_mul_f32_e32 v0, 0xbfb8aa3b, v40
	v_exp_f32_e32 v0, v0
	v_and_b32_e32 v41, 0xffff0000, v116
	v_add_f32_e32 v0, 1.0, v0
	v_rcp_f32_e32 v48, v0
	v_mul_f32_e32 v0, 0xbfb8aa3b, v41
	v_exp_f32_e32 v0, v0
	s_nop 0
	v_add_f32_e32 v0, 1.0, v0
	v_rcp_f32_e32 v49, v0
	s_nop 0
	v_pk_mul_f32 v[40:41], v[48:49], v[40:41]
	s_nop 0
	v_pk_mul_f32 v[40:41], v[40:41], v[50:51]
	v_lshlrev_b32_e32 v48, 16, v35
	v_cvt_pk_bf16_f32 v34, v40, v41
	v_lshlrev_b32_e32 v40, 16, v117
	v_mul_f32_e32 v0, 0xbfb8aa3b, v40
	v_exp_f32_e32 v0, v0
	v_and_b32_e32 v41, 0xffff0000, v117
	v_and_b32_e32 v49, 0xffff0000, v35
	v_add_f32_e32 v0, 1.0, v0
	v_rcp_f32_e32 v116, v0
	v_mul_f32_e32 v0, 0xbfb8aa3b, v41
	v_exp_f32_e32 v0, v0
	s_nop 0
	v_add_f32_e32 v0, 1.0, v0
	v_rcp_f32_e32 v117, v0
	s_nop 0
	v_pk_mul_f32 v[40:41], v[116:117], v[40:41]
	s_nop 0
	v_pk_mul_f32 v[40:41], v[40:41], v[48:49]
	v_lshlrev_b32_e32 v48, 16, v36
	v_cvt_pk_bf16_f32 v35, v40, v41
	v_lshlrev_b32_e32 v40, 16, v118
	v_mul_f32_e32 v0, 0xbfb8aa3b, v40
	v_exp_f32_e32 v0, v0
	v_and_b32_e32 v41, 0xffff0000, v118
	v_and_b32_e32 v49, 0xffff0000, v36
	v_lshlrev_b32_e32 v118, 16, v37
	v_add_f32_e32 v0, 1.0, v0
	v_rcp_f32_e32 v116, v0
	v_mul_f32_e32 v0, 0xbfb8aa3b, v41
	v_exp_f32_e32 v0, v0
	s_nop 0
	v_add_f32_e32 v0, 1.0, v0
	v_rcp_f32_e32 v117, v0
	s_nop 0
	v_pk_mul_f32 v[40:41], v[116:117], v[40:41]
	s_nop 0
	v_pk_mul_f32 v[40:41], v[40:41], v[48:49]
	s_nop 0
	v_cvt_pk_bf16_f32 v36, v40, v41
	v_lshlrev_b32_e32 v40, 16, v119
	v_mul_f32_e32 v0, 0xbfb8aa3b, v40
	v_exp_f32_e32 v0, v0
	v_and_b32_e32 v41, 0xffff0000, v119
	v_and_b32_e32 v119, 0xffff0000, v37
	v_add_f32_e32 v0, 1.0, v0
	v_rcp_f32_e32 v116, v0
	v_mul_f32_e32 v0, 0xbfb8aa3b, v41
	v_exp_f32_e32 v0, v0
	s_nop 0
	v_add_f32_e32 v0, 1.0, v0
	v_rcp_f32_e32 v117, v0
	s_nop 0
	v_pk_mul_f32 v[40:41], v[116:117], v[40:41]
	s_nop 0
	v_pk_mul_f32 v[40:41], v[40:41], v[118:119]
	s_nop 0
	v_cvt_pk_bf16_f32 v37, v40, v41
	v_lshl_add_u64 v[40:41], v[42:43], 0, v[178:179]
	global_store_dwordx4 v[40:41], v[34:37], off offset:2048
	s_nop 0
	s_nop 0
	ds_read_b128 v[34:37], v208
	v_lshl_add_u64 v[38:39], v[38:39], 0, v[182:183]
	s_waitcnt lgkmcnt(0)
; #define LAS __attribute__((address_space(3)))
; __device__ __forceinline__ unsigned cvt_pk_bf16(float lo, float hi) { const f32x2 v = {lo, hi}; const bf16v2 r = __builtin_convertvector(v, bf16v2); return __builtin_bit_cast(unsigned, r); }
; __device__ __forceinline__ float bf_lo(unsigned u) { return __uint_as_float(u << 16); }
; __device__ __forceinline__ float bf_hi(unsigned u) { return __uint_as_float(u & 0xffff0000u); }
; __device__ __forceinline__ float silu_f(float g) { return g * __builtin_amdgcn_rcpf(1.0f + __expf(-g)); }
; __device__ void ret_out_phase(LAS unsigned char* lds, const bf16_t* PROJ, const bf16_t* ST, bf16_t* MIX, const float* lgf, const float* lgb, const float* ogain) {
;     ...
;             const int rw = lane >> 2; const size_t tok = (size_t)qt * 128 + 16 * wave + rw;
;             const bf16_t* gp = PROJ + pj(tok, 6144 + h * 256); bf16_t* mp = MIX + tok * DM + 1024 + h * 256;
; #pragma unroll
;             for (int i = 0; i < 8; ++i) { const int ch = (lane & 3) + 4 * i; const u32x4 y = *(const LAS u32x4*)(sl + rw * RP + 16 * ch); const u32x4 gt = *(const u32x4*)(gp + 8 * ch); u32x4 w;
; #pragma unroll
;                 for (int e = 0; e < 4; ++e) w[e] = cvt_pk_bf16(bf_lo(y[e]) * silu_f(bf_lo(gt[e])), bf_hi(y[e]) * silu_f(bf_hi(gt[e])));
;                 *(u32x4*)(mp + 8 * ch) = w; }
;         }
;         __syncthreads();
;     }
	v_lshlrev_b32_e32 v50, 16, v34
	v_and_b32_e32 v51, 0xffff0000, v34
	s_waitcnt vmcnt(6)
	v_lshlrev_b32_e32 v40, 16, v120
	v_mul_f32_e32 v0, 0xbfb8aa3b, v40
	v_exp_f32_e32 v0, v0
	v_and_b32_e32 v41, 0xffff0000, v120
	v_add_f32_e32 v0, 1.0, v0
	v_rcp_f32_e32 v48, v0
	v_mul_f32_e32 v0, 0xbfb8aa3b, v41
	v_exp_f32_e32 v0, v0
	s_nop 0
	v_add_f32_e32 v0, 1.0, v0
	v_rcp_f32_e32 v49, v0
	s_nop 0
	v_pk_mul_f32 v[40:41], v[48:49], v[40:41]
	s_nop 0
	v_pk_mul_f32 v[40:41], v[40:41], v[50:51]
	v_lshlrev_b32_e32 v48, 16, v35
	v_cvt_pk_bf16_f32 v34, v40, v41
	v_lshlrev_b32_e32 v40, 16, v121
	v_mul_f32_e32 v0, 0xbfb8aa3b, v40
	v_exp_f32_e32 v0, v0
	v_and_b32_e32 v41, 0xffff0000, v121
	v_and_b32_e32 v49, 0xffff0000, v35
	v_add_f32_e32 v0, 1.0, v0
	v_rcp_f32_e32 v120, v0
	v_mul_f32_e32 v0, 0xbfb8aa3b, v41
	v_exp_f32_e32 v0, v0
	s_nop 0
	v_add_f32_e32 v0, 1.0, v0
	v_rcp_f32_e32 v121, v0
	s_nop 0
	v_pk_mul_f32 v[40:41], v[120:121], v[40:41]
	s_nop 0
	v_pk_mul_f32 v[40:41], v[40:41], v[48:49]
	v_lshlrev_b32_e32 v48, 16, v36
	v_cvt_pk_bf16_f32 v35, v40, v41
	v_lshlrev_b32_e32 v40, 16, v122
	v_mul_f32_e32 v0, 0xbfb8aa3b, v40
	v_exp_f32_e32 v0, v0
	v_and_b32_e32 v41, 0xffff0000, v122
	v_and_b32_e32 v49, 0xffff0000, v36
	v_lshlrev_b32_e32 v122, 16, v37
	v_add_f32_e32 v0, 1.0, v0
	v_rcp_f32_e32 v120, v0
	v_mul_f32_e32 v0, 0xbfb8aa3b, v41
	v_exp_f32_e32 v0, v0
	s_nop 0
	v_add_f32_e32 v0, 1.0, v0
	v_rcp_f32_e32 v121, v0
	s_nop 0
	v_pk_mul_f32 v[40:41], v[120:121], v[40:41]
	s_nop 0
	v_pk_mul_f32 v[40:41], v[40:41], v[48:49]
	s_nop 0
	v_cvt_pk_bf16_f32 v36, v40, v41
	v_lshlrev_b32_e32 v40, 16, v123
	v_mul_f32_e32 v0, 0xbfb8aa3b, v40
	v_exp_f32_e32 v0, v0
	v_and_b32_e32 v41, 0xffff0000, v123
	v_and_b32_e32 v123, 0xffff0000, v37
	v_add_f32_e32 v0, 1.0, v0
	v_rcp_f32_e32 v120, v0
	v_mul_f32_e32 v0, 0xbfb8aa3b, v41
	v_exp_f32_e32 v0, v0
	s_nop 0
	v_add_f32_e32 v0, 1.0, v0
	v_rcp_f32_e32 v121, v0
	s_nop 0
	v_pk_mul_f32 v[40:41], v[120:121], v[40:41]
	s_nop 0
	v_pk_mul_f32 v[40:41], v[40:41], v[122:123]
	s_nop 0
	v_cvt_pk_bf16_f32 v37, v40, v41
	v_lshl_add_u64 v[40:41], v[42:43], 0, v[180:181]
	global_store_dwordx4 v[40:41], v[34:37], off offset:2048
	global_load_dwordx4 v[38:41], v[38:39], off
	ds_read_b128 v[34:37], v209
	s_waitcnt lgkmcnt(0)
	v_lshlrev_b32_e32 v48, 16, v34
	v_and_b32_e32 v49, 0xffff0000, v34
	s_waitcnt vmcnt(0)
	v_lshlrev_b32_e32 v44, 16, v38
	v_mul_f32_e32 v0, 0xbfb8aa3b, v44
	v_exp_f32_e32 v0, v0
	v_and_b32_e32 v45, 0xffff0000, v38
	v_lshlrev_b32_e32 v38, 16, v39
	v_and_b32_e32 v39, 0xffff0000, v39
	v_add_f32_e32 v0, 1.0, v0
	v_rcp_f32_e32 v46, v0
	v_mul_f32_e32 v0, 0xbfb8aa3b, v45
	v_exp_f32_e32 v0, v0
	s_nop 0
	v_add_f32_e32 v0, 1.0, v0
	v_rcp_f32_e32 v47, v0
	v_mul_f32_e32 v0, 0xbfb8aa3b, v38
	v_exp_f32_e32 v0, v0
	v_pk_mul_f32 v[44:45], v[46:47], v[44:45]
	s_nop 0
	v_pk_mul_f32 v[44:45], v[44:45], v[48:49]
	v_add_f32_e32 v0, 1.0, v0
	v_cvt_pk_bf16_f32 v34, v44, v45
	v_rcp_f32_e32 v44, v0
	v_mul_f32_e32 v0, 0xbfb8aa3b, v39
	v_exp_f32_e32 v0, v0
	v_lshlrev_b32_e32 v46, 16, v35
	v_and_b32_e32 v47, 0xffff0000, v35
	v_add_f32_e32 v0, 1.0, v0
	v_rcp_f32_e32 v45, v0
	s_nop 0
	v_pk_mul_f32 v[38:39], v[44:45], v[38:39]
	s_nop 0
	v_pk_mul_f32 v[38:39], v[38:39], v[46:47]
	v_lshlrev_b32_e32 v46, 16, v36
	v_cvt_pk_bf16_f32 v35, v38, v39
	v_lshlrev_b32_e32 v38, 16, v40
	v_mul_f32_e32 v0, 0xbfb8aa3b, v38
	v_exp_f32_e32 v0, v0
	v_and_b32_e32 v39, 0xffff0000, v40
	v_and_b32_e32 v47, 0xffff0000, v36
	v_add_f32_e32 v0, 1.0, v0
	v_rcp_f32_e32 v44, v0
	v_mul_f32_e32 v0, 0xbfb8aa3b, v39
	v_exp_f32_e32 v0, v0
	s_nop 0
	v_add_f32_e32 v0, 1.0, v0
	v_rcp_f32_e32 v45, v0
	s_nop 0
	v_pk_mul_f32 v[38:39], v[44:45], v[38:39]
	s_nop 0
	v_pk_mul_f32 v[38:39], v[38:39], v[46:47]
	v_lshlrev_b32_e32 v44, 16, v37
	v_cvt_pk_bf16_f32 v36, v38, v39
	v_lshlrev_b32_e32 v38, 16, v41
	v_mul_f32_e32 v0, 0xbfb8aa3b, v38
	v_exp_f32_e32 v0, v0
	v_and_b32_e32 v39, 0xffff0000, v41
	v_and_b32_e32 v45, 0xffff0000, v37
	v_add_f32_e32 v0, 1.0, v0
	v_rcp_f32_e32 v40, v0
	v_mul_f32_e32 v0, 0xbfb8aa3b, v39
	v_exp_f32_e32 v0, v0
	s_nop 0
	v_add_f32_e32 v0, 1.0, v0
	v_rcp_f32_e32 v41, v0
	s_nop 0
	v_pk_mul_f32 v[38:39], v[40:41], v[38:39]
	s_nop 0
	v_pk_mul_f32 v[38:39], v[38:39], v[44:45]
	s_nop 0
	v_cvt_pk_bf16_f32 v37, v38, v39
	v_lshl_add_u64 v[38:39], v[42:43], 0, v[182:183]
	global_store_dwordx4 v[38:39], v[34:37], off offset:2048
	s_barrier
	s_load_dword s0, s[68:69], 0x10
	s_waitcnt lgkmcnt(0)
	s_lshr_b32 s0, s0, 16
	s_cmp_lg_u32 s0, 0
	s_cselect_b64 s[0:1], -1, 0
	s_cmp_lg_u64 s[0:1], 0
	s_addc_u32 s14, s4, 0
	s_cmpk_lt_i32 s14, 0x300
	s_cbranch_scc0 .LBB0_293
; #define LAS __attribute__((address_space(3)))
; #define MFMA16(a, b, c) __builtin_amdgcn_mfma_f32_16x16x32_bf16((a), (b), (c), 0, 0, 0)
; #define RET_ISSUE(s_, it_) do { const bf16_t* bp_; int pt_; RET_SRC(s_, it_, bp_, pt_); const int tv_ = otid(); const char* sb_ = (const char*)bp_ + (size_t)(((tv_ >> 5) * pt_ + (tv_ & 31) * 8) * 2); const size_t step_ = (size_t)pt_ * 32; \
;         _Pragma("unroll") for (int i_ = 0; i_ < 8; ++i_) stg[i_] = *(const u32x4*)(sb_ + i_ * step_); } while (0)
; __device__ void ret_out_phase(LAS unsigned char* lds, const bf16_t* PROJ, const bf16_t* ST, bf16_t* MIX, const float* lgf, const float* lgb, const float* ogain) {
;     ...
;     for (; item < 768; item += gridDim.x) {
;         const RetItem ri = ret_decode(item);
;         const int h = ri.h, half = ri.half, qt = ri.qt;
;         const float lf = lgf[h], lb = lgb[h];
;         const size_t qtok = (size_t)qt * 128 + 16 * wave + fr;
;         bf16x8 qf[8];
; #pragma unroll
;         for (int ks = 0; ks < 8; ++ks) qf[ks] = *(const bf16x8*)(PROJ + pj(qtok, 3072 + h * 256 + 32 * ks + 8 * g));
;         f32x4 o[16];
; #pragma unroll
;         for (int cc = 0; cc < 16; ++cc) o[cc] = (f32x4){0.f, 0.f, 0.f, 0.f};
;         f32x4 st[8];
; #pragma unroll
;         for (int s = 0; s < 8; ++s) {
;             LAS unsigned char* buf = lds + (s & 1) * BUFB;
; #pragma unroll
;             for (int i = 0; i < 8; ++i) *(LAS u32x4*)(buf + ((tid >> 5) + 16 * i) * RP + (tid & 31) * 16) = stg[i];
;             __syncthreads();
;             if (s < 7) { RET_ISSUE(s + 1, ri); }
;             else if (item + (int)gridDim.x < 768) { const RetItem rn = ret_decode(item + gridDim.x); RET_ISSUE(0, rn); }
;             if (s < 4) {
; #pragma unroll
;                 for (int ccl = 0; ccl < 8; ++ccl)
; #pragma unroll
;                     for (int ks = 0; ks < 8; ++ks) { const bf16x8 bfrag = *(const LAS bf16x8*)(buf + (16 * ccl + fr) * RP + (32 * ks + 8 * g) * 2); o[(s & 1) * 8 + ccl] = MFMA16(qf[ks], bfrag, o[(s & 1) * 8 + ccl]); }
.LBB0_35:
	s_ashr_i32 s1, s14, 1
	s_and_b32 s0, s14, 4
	s_and_b32 s1, s1, -8
	s_or_b32 s4, s1, s0
	s_bfe_u32 s5, s14, 0x10003
	s_and_b32 s12, s14, 3
	s_ashr_i32 s0, s4, 1
	s_or_b32 s0, s0, s5
	s_lshl_b32 s1, s12, 2
	v_mov_b32_e32 v0, s1
	s_ashr_i32 s1, s0, 31
	s_lshl_b64 s[0:1], s[0:1], 7
	s_add_u32 s2, s0, s6
	s_mul_i32 s13, s12, 0x6000
	global_load_dword v184, v0, s[38:39]
	global_load_dword v185, v0, s[40:41]
	s_addc_u32 s3, s1, s7
	v_or_b32_e32 v0, s13, v165
	v_lshl_add_u64 v[34:35], s[2:3], 0, v[0:1]
	v_lshlrev_b64 v[34:35], 9, v[34:35]
	v_lshl_add_u64 v[34:35], s[78:79], 0, v[34:35]
	v_mov_b32_e32 v167, v1
	v_lshl_add_u64 v[34:35], v[34:35], 0, v[166:167]
	v_lshl_add_u64 v[36:37], v[34:35], 0, s[16:17]
	v_add_co_u32_e32 v34, vcc, s33, v34
	s_ashr_i32 s0, s4, 2
	s_nop 0
	v_addc_co_u32_e32 v35, vcc, 0, v35, vcc
	global_load_dwordx4 v[62:65], v[34:35], off
	global_load_dwordx4 v[58:61], v[36:37], off offset:64
	global_load_dwordx4 v[54:57], v[36:37], off offset:128
	global_load_dwordx4 v[50:53], v[36:37], off offset:192
	global_load_dwordx4 v[46:49], v[36:37], off offset:256
	global_load_dwordx4 v[42:45], v[36:37], off offset:320
	global_load_dwordx4 v[38:41], v[36:37], off offset:384
	s_nop 0
	global_load_dwordx4 v[34:37], v[36:37], off offset:448
	s_lshl_b32 s5, s5, 7
	v_or_b32_e32 v0, s6, v165
	v_or_b32_e32 v66, s6, v190
	s_or_b32 s4, s4, s12
	s_ashr_i32 s1, s0, 31
	v_add_u32_e32 v0, s5, v0
	v_add_u32_e32 v167, s5, v66
	s_waitcnt vmcnt(17)
	ds_write_b128 v210, v[2:5]
	s_waitcnt vmcnt(16)
	ds_write_b128 v210, v[6:9] offset:8704
	s_waitcnt vmcnt(15)
	ds_write_b128 v210, v[10:13] offset:17408
	s_waitcnt vmcnt(14)
	ds_write_b128 v210, v[14:17] offset:26112
	s_waitcnt vmcnt(13)
	ds_write_b128 v210, v[18:21] offset:34816
	s_waitcnt vmcnt(12)
	ds_write_b128 v210, v[22:25] offset:43520
	s_waitcnt vmcnt(11)
	ds_write_b128 v210, v[26:29] offset:52224
	s_waitcnt vmcnt(10)
	ds_write_b128 v210, v[30:33] offset:60928
	s_ashr_i32 s5, s4, 31
	v_mov_b32_e32 v2, v226
	s_lshl_b64 s[0:1], s[0:1], 8
	s_waitcnt lgkmcnt(0)
	s_barrier
	s_lshl_b64 s[16:17], s[4:5], 17
	s_add_u32 s16, s84, s16
	v_lshlrev_b32_e32 v2, 4, v2
	s_addc_u32 s17, s85, s17
	v_ashrrev_i32_e32 v3, 31, v2
	v_lshl_add_u64 v[2:3], s[16:17], 0, v[2:3]
	s_mov_b32 s16, 0x10000
	v_add_co_u32_e32 v4, vcc, s16, v2
	s_mov_b32 s17, 0x12000
	s_nop 0
	v_addc_co_u32_e32 v5, vcc, 0, v3, vcc
	global_load_dwordx4 v[26:29], v[4:5], off
	v_add_co_u32_e32 v4, vcc, s17, v2
	s_mov_b32 s18, 0x14000
	s_nop 0
	v_addc_co_u32_e32 v5, vcc, 0, v3, vcc
	global_load_dwordx4 v[30:33], v[4:5], off
	v_add_co_u32_e32 v4, vcc, s18, v2
	s_mov_b32 s20, 0x16000
	s_nop 0
	v_addc_co_u32_e32 v5, vcc, 0, v3, vcc
	global_load_dwordx4 v[70:73], v[4:5], off
	v_add_co_u32_e32 v4, vcc, s20, v2
	s_mov_b32 s21, 0x18000
	s_nop 0
	v_addc_co_u32_e32 v5, vcc, 0, v3, vcc
	global_load_dwordx4 v[74:77], v[4:5], off
	v_add_co_u32_e32 v4, vcc, s21, v2
	s_mov_b32 s22, 0x1a000
	s_nop 0
	v_addc_co_u32_e32 v5, vcc, 0, v3, vcc
	global_load_dwordx4 v[78:81], v[4:5], off
	v_add_co_u32_e32 v4, vcc, s22, v2
	s_mov_b32 s23, 0x1c000
	s_nop 0
	v_addc_co_u32_e32 v5, vcc, 0, v3, vcc
	global_load_dwordx4 v[82:85], v[4:5], off
	v_add_co_u32_e32 v4, vcc, s23, v2
	s_mov_b32 s24, 0x1e000
	s_nop 0
	v_addc_co_u32_e32 v5, vcc, 0, v3, vcc
	v_add_co_u32_e32 v2, vcc, s24, v2
	global_load_dwordx4 v[86:89], v[4:5], off
	s_nop 0
	v_addc_co_u32_e32 v3, vcc, 0, v3, vcc
	global_load_dwordx4 v[90:93], v[2:3], off
	ds_read_b128 v[2:5], v191
	ds_read_b128 v[6:9], v191 offset:64
	s_waitcnt vmcnt(15) lgkmcnt(1)
	v_mfma_f32_16x16x32_bf16 v[2:5], v[62:65], v[2:5], 0
	ds_read_b128 v[10:13], v191 offset:8768
	ds_read_b128 v[14:17], v191 offset:17472
	ds_read_b128 v[18:21], v191 offset:26176
	s_waitcnt vmcnt(14) lgkmcnt(3)
	v_mfma_f32_16x16x32_bf16 v[2:5], v[58:61], v[6:9], v[2:5]
	ds_read_b128 v[6:9], v191 offset:128
	s_addk_i32 s4, 0x180
	s_ashr_i32 s5, s4, 31
	s_waitcnt vmcnt(13) lgkmcnt(0)
	v_mfma_f32_16x16x32_bf16 v[2:5], v[54:57], v[6:9], v[2:5]
	ds_read_b128 v[6:9], v191 offset:192
	s_lshl_b64 s[4:5], s[4:5], 17
	s_add_u32 s4, s84, s4
	s_waitcnt vmcnt(12) lgkmcnt(0)
	v_mfma_f32_16x16x32_bf16 v[2:5], v[50:53], v[6:9], v[2:5]
	ds_read_b128 v[6:9], v191 offset:256
	s_addc_u32 s5, s85, s5
	s_movk_i32 s15, 0x2000
	s_waitcnt vmcnt(11) lgkmcnt(0)
	v_mfma_f32_16x16x32_bf16 v[2:5], v[46:49], v[6:9], v[2:5]
	ds_read_b128 v[6:9], v191 offset:320
	v_sub_u32_e32 v173, v0, v190
	ds_read_b128 v[22:25], v191 offset:34880
	s_waitcnt vmcnt(10) lgkmcnt(1)
	v_mfma_f32_16x16x32_bf16 v[2:5], v[42:45], v[6:9], v[2:5]
	ds_read_b128 v[6:9], v191 offset:384
	ds_read_b128 v[66:69], v191 offset:43584
	ds_read_b128 v[94:97], v191 offset:52288
	s_waitcnt vmcnt(9) lgkmcnt(2)
	v_mfma_f32_16x16x32_bf16 v[2:5], v[38:41], v[6:9], v[2:5]
	ds_read_b128 v[6:9], v191 offset:448
	ds_read_b128 v[98:101], v191 offset:60992
	s_waitcnt vmcnt(8) lgkmcnt(1)
	v_mfma_f32_16x16x32_bf16 v[2:5], v[34:37], v[6:9], v[2:5]
	ds_read_b128 v[6:9], v191 offset:8704
	s_waitcnt lgkmcnt(0)
	v_mfma_f32_16x16x32_bf16 v[6:9], v[62:65], v[6:9], 0
	v_mfma_f32_16x16x32_bf16 v[6:9], v[58:61], v[10:13], v[6:9]
	ds_read_b128 v[10:13], v191 offset:8832
	ds_read_b128 v[102:105], v191 offset:8896
	ds_read_b128 v[106:109], v191 offset:8960
	ds_read_b128 v[110:113], v191 offset:9024
	s_waitcnt lgkmcnt(3)
	v_mfma_f32_16x16x32_bf16 v[6:9], v[54:57], v[10:13], v[6:9]
	ds_read_b128 v[10:13], v191 offset:9088
	s_waitcnt lgkmcnt(3)
	v_mfma_f32_16x16x32_bf16 v[6:9], v[50:53], v[102:105], v[6:9]
	ds_read_b128 v[102:105], v191 offset:9152
	s_waitcnt lgkmcnt(3)
	v_mfma_f32_16x16x32_bf16 v[6:9], v[46:49], v[106:109], v[6:9]
	s_waitcnt lgkmcnt(2)
; #define LAS __attribute__((address_space(3)))
; #define MFMA16(a, b, c) __builtin_amdgcn_mfma_f32_16x16x32_bf16((a), (b), (c), 0, 0, 0)
; #define RET_ISSUE(s_, it_) do { const bf16_t* bp_; int pt_; RET_SRC(s_, it_, bp_, pt_); const int tv_ = otid(); const char* sb_ = (const char*)bp_ + (size_t)(((tv_ >> 5) * pt_ + (tv_ & 31) * 8) * 2); const size_t step_ = (size_t)pt_ * 32; \
;         _Pragma("unroll") for (int i_ = 0; i_ < 8; ++i_) stg[i_] = *(const u32x4*)(sb_ + i_ * step_); } while (0)
; __device__ void ret_out_phase(LAS unsigned char* lds, const bf16_t* PROJ, const bf16_t* ST, bf16_t* MIX, const float* lgf, const float* lgb, const float* ogain) {
;     ...
;         for (int s = 0; s < 8; ++s) {
;             LAS unsigned char* buf = lds + (s & 1) * BUFB;
; #pragma unroll
;             for (int i = 0; i < 8; ++i) *(LAS u32x4*)(buf + ((tid >> 5) + 16 * i) * RP + (tid & 31) * 16) = stg[i];
;             __syncthreads();
;             if (s < 7) { RET_ISSUE(s + 1, ri); }
;             else if (item + (int)gridDim.x < 768) { const RetItem rn = ret_decode(item + gridDim.x); RET_ISSUE(0, rn); }
;             if (s < 4) {
; #pragma unroll
;                 for (int ccl = 0; ccl < 8; ++ccl)
; #pragma unroll
;                     for (int ks = 0; ks < 8; ++ks) { const bf16x8 bfrag = *(const LAS bf16x8*)(buf + (16 * ccl + fr) * RP + (32 * ks + 8 * g) * 2); o[(s & 1) * 8 + ccl] = MFMA16(qf[ks], bfrag, o[(s & 1) * 8 + ccl]); }
	v_mfma_f32_16x16x32_bf16 v[6:9], v[42:45], v[110:113], v[6:9]
	s_waitcnt lgkmcnt(1)
	v_mfma_f32_16x16x32_bf16 v[6:9], v[38:41], v[10:13], v[6:9]
	s_waitcnt lgkmcnt(0)
	v_mfma_f32_16x16x32_bf16 v[6:9], v[34:37], v[102:105], v[6:9]
	ds_read_b128 v[10:13], v191 offset:17408
	s_waitcnt lgkmcnt(0)
	v_mfma_f32_16x16x32_bf16 v[10:13], v[62:65], v[10:13], 0
	v_mfma_f32_16x16x32_bf16 v[10:13], v[58:61], v[14:17], v[10:13]
	ds_read_b128 v[14:17], v191 offset:17536
	ds_read_b128 v[102:105], v191 offset:17600
	ds_read_b128 v[106:109], v191 offset:17664
	ds_read_b128 v[110:113], v191 offset:17728
	s_waitcnt lgkmcnt(3)
	v_mfma_f32_16x16x32_bf16 v[10:13], v[54:57], v[14:17], v[10:13]
	ds_read_b128 v[14:17], v191 offset:17792
	s_waitcnt lgkmcnt(3)
	v_mfma_f32_16x16x32_bf16 v[10:13], v[50:53], v[102:105], v[10:13]
	ds_read_b128 v[102:105], v191 offset:17856
	s_waitcnt lgkmcnt(3)
	v_mfma_f32_16x16x32_bf16 v[10:13], v[46:49], v[106:109], v[10:13]
	s_waitcnt lgkmcnt(2)
	v_mfma_f32_16x16x32_bf16 v[10:13], v[42:45], v[110:113], v[10:13]
	s_waitcnt lgkmcnt(1)
	v_mfma_f32_16x16x32_bf16 v[10:13], v[38:41], v[14:17], v[10:13]
	s_waitcnt lgkmcnt(0)
	v_mfma_f32_16x16x32_bf16 v[10:13], v[34:37], v[102:105], v[10:13]
	ds_read_b128 v[14:17], v191 offset:26112
	s_waitcnt lgkmcnt(0)
	v_mfma_f32_16x16x32_bf16 v[14:17], v[62:65], v[14:17], 0
	v_mfma_f32_16x16x32_bf16 v[14:17], v[58:61], v[18:21], v[14:17]
	ds_read_b128 v[18:21], v191 offset:26240
	ds_read_b128 v[102:105], v191 offset:26304
	ds_read_b128 v[106:109], v191 offset:26368
	ds_read_b128 v[110:113], v191 offset:26432
	s_waitcnt lgkmcnt(3)
	v_mfma_f32_16x16x32_bf16 v[14:17], v[54:57], v[18:21], v[14:17]
	ds_read_b128 v[18:21], v191 offset:26496
	s_waitcnt lgkmcnt(3)
	v_mfma_f32_16x16x32_bf16 v[14:17], v[50:53], v[102:105], v[14:17]
	ds_read_b128 v[102:105], v191 offset:26560
	s_waitcnt lgkmcnt(3)
	v_mfma_f32_16x16x32_bf16 v[14:17], v[46:49], v[106:109], v[14:17]
	s_waitcnt lgkmcnt(2)
	v_mfma_f32_16x16x32_bf16 v[14:17], v[42:45], v[110:113], v[14:17]
	s_waitcnt lgkmcnt(1)
	v_mfma_f32_16x16x32_bf16 v[14:17], v[38:41], v[18:21], v[14:17]
	s_waitcnt lgkmcnt(0)
	v_mfma_f32_16x16x32_bf16 v[14:17], v[34:37], v[102:105], v[14:17]
	ds_read_b128 v[18:21], v191 offset:34816
	s_waitcnt lgkmcnt(0)
	v_mfma_f32_16x16x32_bf16 v[18:21], v[62:65], v[18:21], 0
	v_mfma_f32_16x16x32_bf16 v[18:21], v[58:61], v[22:25], v[18:21]
	ds_read_b128 v[22:25], v191 offset:34944
	ds_read_b128 v[102:105], v191 offset:35008
	ds_read_b128 v[106:109], v191 offset:35072
	ds_read_b128 v[110:113], v191 offset:35136
	s_waitcnt lgkmcnt(3)
	v_mfma_f32_16x16x32_bf16 v[18:21], v[54:57], v[22:25], v[18:21]
	ds_read_b128 v[22:25], v191 offset:35200
	s_waitcnt lgkmcnt(3)
	v_mfma_f32_16x16x32_bf16 v[18:21], v[50:53], v[102:105], v[18:21]
	ds_read_b128 v[102:105], v191 offset:35264
	s_waitcnt lgkmcnt(3)
	v_mfma_f32_16x16x32_bf16 v[18:21], v[46:49], v[106:109], v[18:21]
	s_waitcnt lgkmcnt(2)
	v_mfma_f32_16x16x32_bf16 v[18:21], v[42:45], v[110:113], v[18:21]
	s_waitcnt lgkmcnt(1)
	v_mfma_f32_16x16x32_bf16 v[18:21], v[38:41], v[22:25], v[18:21]
	s_waitcnt lgkmcnt(0)
	v_mfma_f32_16x16x32_bf16 v[18:21], v[34:37], v[102:105], v[18:21]
	ds_read_b128 v[22:25], v191 offset:43520
	s_waitcnt lgkmcnt(0)
	v_mfma_f32_16x16x32_bf16 v[22:25], v[62:65], v[22:25], 0
	v_mfma_f32_16x16x32_bf16 v[22:25], v[58:61], v[66:69], v[22:25]
	ds_read_b128 v[66:69], v191 offset:43648
	ds_read_b128 v[102:105], v191 offset:43712
	ds_read_b128 v[106:109], v191 offset:43776
	ds_read_b128 v[110:113], v191 offset:43840
	s_waitcnt lgkmcnt(3)
	v_mfma_f32_16x16x32_bf16 v[22:25], v[54:57], v[66:69], v[22:25]
	ds_read_b128 v[66:69], v191 offset:43904
	s_waitcnt lgkmcnt(3)
	v_mfma_f32_16x16x32_bf16 v[22:25], v[50:53], v[102:105], v[22:25]
	ds_read_b128 v[102:105], v191 offset:43968
	s_waitcnt lgkmcnt(3)
	v_mfma_f32_16x16x32_bf16 v[22:25], v[46:49], v[106:109], v[22:25]
	s_waitcnt lgkmcnt(2)
	v_mfma_f32_16x16x32_bf16 v[22:25], v[42:45], v[110:113], v[22:25]
	s_waitcnt lgkmcnt(1)
	v_mfma_f32_16x16x32_bf16 v[22:25], v[38:41], v[66:69], v[22:25]
	s_waitcnt lgkmcnt(0)
	v_mfma_f32_16x16x32_bf16 v[22:25], v[34:37], v[102:105], v[22:25]
	ds_read_b128 v[66:69], v191 offset:52224
	s_waitcnt lgkmcnt(0)
	v_mfma_f32_16x16x32_bf16 v[66:69], v[62:65], v[66:69], 0
	v_mfma_f32_16x16x32_bf16 v[66:69], v[58:61], v[94:97], v[66:69]
	ds_read_b128 v[94:97], v191 offset:52352
	ds_read_b128 v[102:105], v191 offset:52416
	ds_read_b128 v[106:109], v191 offset:52480
	ds_read_b128 v[110:113], v191 offset:52544
	s_waitcnt lgkmcnt(3)
	v_mfma_f32_16x16x32_bf16 v[66:69], v[54:57], v[94:97], v[66:69]
	ds_read_b128 v[94:97], v191 offset:52608
	s_waitcnt lgkmcnt(3)
	v_mfma_f32_16x16x32_bf16 v[66:69], v[50:53], v[102:105], v[66:69]
	ds_read_b128 v[102:105], v191 offset:52672
	s_waitcnt lgkmcnt(3)
	v_mfma_f32_16x16x32_bf16 v[66:69], v[46:49], v[106:109], v[66:69]
	s_waitcnt lgkmcnt(2)
	v_mfma_f32_16x16x32_bf16 v[66:69], v[42:45], v[110:113], v[66:69]
	s_waitcnt lgkmcnt(1)
	v_mfma_f32_16x16x32_bf16 v[66:69], v[38:41], v[94:97], v[66:69]
	s_waitcnt lgkmcnt(0)
	v_mfma_f32_16x16x32_bf16 v[66:69], v[34:37], v[102:105], v[66:69]
	ds_read_b128 v[94:97], v191 offset:60928
	s_waitcnt lgkmcnt(0)
	v_mfma_f32_16x16x32_bf16 v[94:97], v[62:65], v[94:97], 0
	v_mfma_f32_16x16x32_bf16 v[94:97], v[58:61], v[98:101], v[94:97]
	ds_read_b128 v[98:101], v191 offset:61056
	ds_read_b128 v[102:105], v191 offset:61120
	ds_read_b128 v[106:109], v191 offset:61184
	ds_read_b128 v[110:113], v191 offset:61248
	s_waitcnt lgkmcnt(3)
	v_mfma_f32_16x16x32_bf16 v[94:97], v[54:57], v[98:101], v[94:97]
	ds_read_b128 v[98:101], v191 offset:61312
	s_waitcnt lgkmcnt(3)
	v_mfma_f32_16x16x32_bf16 v[94:97], v[50:53], v[102:105], v[94:97]
	s_waitcnt lgkmcnt(2)
	v_mfma_f32_16x16x32_bf16 v[94:97], v[46:49], v[106:109], v[94:97]
	s_waitcnt lgkmcnt(1)
	v_mfma_f32_16x16x32_bf16 v[94:97], v[42:45], v[110:113], v[94:97]
	s_waitcnt lgkmcnt(0)
	v_mfma_f32_16x16x32_bf16 v[94:97], v[38:41], v[98:101], v[94:97]
	ds_read_b128 v[98:101], v191 offset:61376
	s_waitcnt vmcnt(7)
	ds_write_b128 v211, v[26:29]
	s_waitcnt vmcnt(6)
	ds_write_b128 v211, v[30:33] offset:8704
	s_waitcnt vmcnt(5)
	ds_write_b128 v211, v[70:73] offset:17408
	s_waitcnt vmcnt(4)
	ds_write_b128 v211, v[74:77] offset:26112
	s_waitcnt vmcnt(3)
	ds_write_b128 v211, v[78:81] offset:34816
	s_waitcnt vmcnt(2)
	ds_write_b128 v211, v[82:85] offset:43520
	s_waitcnt vmcnt(1)
	ds_write_b128 v211, v[86:89] offset:52224
	s_waitcnt vmcnt(0)
	ds_write_b128 v211, v[90:93] offset:60928
	v_mov_b32_e32 v26, v226
	s_waitcnt lgkmcnt(0)
	s_barrier
; #define LAS __attribute__((address_space(3)))
; #define MFMA16(a, b, c) __builtin_amdgcn_mfma_f32_16x16x32_bf16((a), (b), (c), 0, 0, 0)
; #define RET_ISSUE(s_, it_) do { const bf16_t* bp_; int pt_; RET_SRC(s_, it_, bp_, pt_); const int tv_ = otid(); const char* sb_ = (const char*)bp_ + (size_t)(((tv_ >> 5) * pt_ + (tv_ & 31) * 8) * 2); const size_t step_ = (size_t)pt_ * 32; \
;         _Pragma("unroll") for (int i_ = 0; i_ < 8; ++i_) stg[i_] = *(const u32x4*)(sb_ + i_ * step_); } while (0)
; __device__ void ret_out_phase(LAS unsigned char* lds, const bf16_t* PROJ, const bf16_t* ST, bf16_t* MIX, const float* lgf, const float* lgb, const float* ogain) {
;     ...
;         for (int s = 0; s < 8; ++s) {
;             LAS unsigned char* buf = lds + (s & 1) * BUFB;
; #pragma unroll
;             for (int i = 0; i < 8; ++i) *(LAS u32x4*)(buf + ((tid >> 5) + 16 * i) * RP + (tid & 31) * 16) = stg[i];
;             __syncthreads();
;             if (s < 7) { RET_ISSUE(s + 1, ri); }
;             else if (item + (int)gridDim.x < 768) { const RetItem rn = ret_decode(item + gridDim.x); RET_ISSUE(0, rn); }
;             if (s < 4) {
; #pragma unroll
;                 for (int ccl = 0; ccl < 8; ++ccl)
; #pragma unroll
;                     for (int ks = 0; ks < 8; ++ks) { const bf16x8 bfrag = *(const LAS bf16x8*)(buf + (16 * ccl + fr) * RP + (32 * ks + 8 * g) * 2); o[(s & 1) * 8 + ccl] = MFMA16(qf[ks], bfrag, o[(s & 1) * 8 + ccl]); }
	v_mfma_f32_16x16x32_bf16 v[94:97], v[34:37], v[98:101], v[94:97]
	v_lshlrev_b32_e32 v26, 4, v26
	v_ashrrev_i32_e32 v27, 31, v26
	v_lshl_add_u64 v[70:71], s[4:5], 0, v[26:27]
	v_add_co_u32_e32 v30, vcc, s15, v70
	s_movk_i32 s15, 0x4000
	s_nop 0
	v_addc_co_u32_e32 v31, vcc, 0, v71, vcc
	v_add_co_u32_e32 v72, vcc, s15, v70
	s_movk_i32 s15, 0x6000
	s_nop 0
	v_addc_co_u32_e32 v73, vcc, 0, v71, vcc
	global_load_dwordx4 v[98:101], v[72:73], off
	v_add_co_u32_e32 v72, vcc, s15, v70
	s_mov_b32 s15, 0x8000
	s_nop 0
	v_addc_co_u32_e32 v73, vcc, 0, v71, vcc
	global_load_dwordx4 v[102:105], v[72:73], off
	v_add_co_u32_e32 v72, vcc, s15, v70
	s_mov_b32 s15, 0xa000
	s_nop 0
	v_addc_co_u32_e32 v73, vcc, 0, v71, vcc
	global_load_dwordx4 v[106:109], v[72:73], off
	v_add_co_u32_e32 v72, vcc, s15, v70
	s_mov_b32 s15, 0xc000
	s_nop 0
	v_addc_co_u32_e32 v73, vcc, 0, v71, vcc
	global_load_dwordx4 v[110:113], v[72:73], off
	v_add_co_u32_e32 v72, vcc, s15, v70
	s_mov_b32 s15, 0xe000
	s_nop 0
	v_addc_co_u32_e32 v73, vcc, 0, v71, vcc
	global_load_dwordx4 v[26:29], v[70:71], off
	global_load_dwordx4 v[114:117], v[72:73], off
	ds_read_b128 v[74:77], v192 offset:64
	global_load_dwordx4 v[30:33], v[30:31], off
	v_add_co_u32_e32 v70, vcc, s15, v70
	ds_read_b128 v[78:81], v192 offset:8768
	s_nop 0
	v_addc_co_u32_e32 v71, vcc, 0, v71, vcc
	global_load_dwordx4 v[118:121], v[70:71], off
	ds_read_b128 v[70:73], v192
	s_waitcnt lgkmcnt(0)
	v_mfma_f32_16x16x32_bf16 v[70:73], v[62:65], v[70:73], 0
	ds_read_b128 v[82:85], v192 offset:17472
	ds_read_b128 v[86:89], v192 offset:26176
	s_add_i32 s15, s13, 0x18000
	v_mfma_f32_16x16x32_bf16 v[70:73], v[58:61], v[74:77], v[70:73]
	ds_read_b128 v[74:77], v192 offset:128
	ds_read_b128 v[90:93], v192 offset:34880
	ds_read_b128 v[122:125], v192 offset:43584
	s_waitcnt lgkmcnt(2)
	v_mfma_f32_16x16x32_bf16 v[70:73], v[54:57], v[74:77], v[70:73]
	ds_read_b128 v[74:77], v192 offset:192
	ds_read_b128 v[126:129], v192 offset:52288
	s_waitcnt lgkmcnt(1)
	v_mfma_f32_16x16x32_bf16 v[70:73], v[50:53], v[74:77], v[70:73]
	ds_read_b128 v[74:77], v192 offset:256
	ds_read_b128 v[130:133], v192 offset:320
	ds_read_b128 v[134:137], v192 offset:384
	ds_read_b128 v[138:141], v192 offset:448
	s_waitcnt lgkmcnt(3)
	v_mfma_f32_16x16x32_bf16 v[70:73], v[46:49], v[74:77], v[70:73]
	s_waitcnt lgkmcnt(2)
	v_mfma_f32_16x16x32_bf16 v[70:73], v[42:45], v[130:133], v[70:73]
	s_waitcnt lgkmcnt(1)
	v_mfma_f32_16x16x32_bf16 v[70:73], v[38:41], v[134:137], v[70:73]
	s_waitcnt lgkmcnt(0)
	v_mfma_f32_16x16x32_bf16 v[70:73], v[34:37], v[138:141], v[70:73]
	ds_read_b128 v[74:77], v192 offset:8704
	s_waitcnt lgkmcnt(0)
	v_mfma_f32_16x16x32_bf16 v[74:77], v[62:65], v[74:77], 0
	v_mfma_f32_16x16x32_bf16 v[74:77], v[58:61], v[78:81], v[74:77]
	ds_read_b128 v[78:81], v192 offset:8832
	ds_read_b128 v[130:133], v192 offset:8896
	ds_read_b128 v[134:137], v192 offset:8960
	ds_read_b128 v[138:141], v192 offset:9024
	s_waitcnt lgkmcnt(3)
	v_mfma_f32_16x16x32_bf16 v[74:77], v[54:57], v[78:81], v[74:77]
	ds_read_b128 v[78:81], v192 offset:9088
	s_waitcnt lgkmcnt(3)
	v_mfma_f32_16x16x32_bf16 v[74:77], v[50:53], v[130:133], v[74:77]
	ds_read_b128 v[130:133], v192 offset:9152
	s_waitcnt lgkmcnt(3)
	v_mfma_f32_16x16x32_bf16 v[74:77], v[46:49], v[134:137], v[74:77]
	s_waitcnt lgkmcnt(2)
	v_mfma_f32_16x16x32_bf16 v[74:77], v[42:45], v[138:141], v[74:77]
	s_waitcnt lgkmcnt(1)
	v_mfma_f32_16x16x32_bf16 v[74:77], v[38:41], v[78:81], v[74:77]
	s_waitcnt lgkmcnt(0)
	v_mfma_f32_16x16x32_bf16 v[74:77], v[34:37], v[130:133], v[74:77]
	ds_read_b128 v[78:81], v192 offset:17408
	s_waitcnt lgkmcnt(0)
	v_mfma_f32_16x16x32_bf16 v[78:81], v[62:65], v[78:81], 0
	v_mfma_f32_16x16x32_bf16 v[78:81], v[58:61], v[82:85], v[78:81]
	ds_read_b128 v[82:85], v192 offset:17536
	ds_read_b128 v[130:133], v192 offset:17600
	ds_read_b128 v[134:137], v192 offset:17664
	ds_read_b128 v[138:141], v192 offset:17728
	s_waitcnt lgkmcnt(3)
	v_mfma_f32_16x16x32_bf16 v[78:81], v[54:57], v[82:85], v[78:81]
	ds_read_b128 v[82:85], v192 offset:17792
	s_waitcnt lgkmcnt(3)
	v_mfma_f32_16x16x32_bf16 v[78:81], v[50:53], v[130:133], v[78:81]
	ds_read_b128 v[130:133], v192 offset:17856
	s_waitcnt lgkmcnt(3)
	v_mfma_f32_16x16x32_bf16 v[78:81], v[46:49], v[134:137], v[78:81]
	s_waitcnt lgkmcnt(2)
	v_mfma_f32_16x16x32_bf16 v[78:81], v[42:45], v[138:141], v[78:81]
	s_waitcnt lgkmcnt(1)
	v_mfma_f32_16x16x32_bf16 v[78:81], v[38:41], v[82:85], v[78:81]
	s_waitcnt lgkmcnt(0)
	v_mfma_f32_16x16x32_bf16 v[78:81], v[34:37], v[130:133], v[78:81]
	ds_read_b128 v[82:85], v192 offset:26112
	s_waitcnt lgkmcnt(0)
	v_mfma_f32_16x16x32_bf16 v[82:85], v[62:65], v[82:85], 0
	v_mfma_f32_16x16x32_bf16 v[82:85], v[58:61], v[86:89], v[82:85]
	ds_read_b128 v[86:89], v192 offset:26240
	ds_read_b128 v[130:133], v192 offset:26304
	ds_read_b128 v[134:137], v192 offset:26368
	ds_read_b128 v[138:141], v192 offset:26432
	s_waitcnt lgkmcnt(3)
	v_mfma_f32_16x16x32_bf16 v[82:85], v[54:57], v[86:89], v[82:85]
	ds_read_b128 v[86:89], v192 offset:26496
	s_waitcnt lgkmcnt(3)
	v_mfma_f32_16x16x32_bf16 v[82:85], v[50:53], v[130:133], v[82:85]
	ds_read_b128 v[130:133], v192 offset:26560
	s_waitcnt lgkmcnt(3)
	v_mfma_f32_16x16x32_bf16 v[82:85], v[46:49], v[134:137], v[82:85]
	s_waitcnt lgkmcnt(2)
	v_mfma_f32_16x16x32_bf16 v[82:85], v[42:45], v[138:141], v[82:85]
	s_waitcnt lgkmcnt(1)
	v_mfma_f32_16x16x32_bf16 v[82:85], v[38:41], v[86:89], v[82:85]
	s_waitcnt lgkmcnt(0)
	v_mfma_f32_16x16x32_bf16 v[82:85], v[34:37], v[130:133], v[82:85]
	ds_read_b128 v[86:89], v192 offset:34816
	s_waitcnt lgkmcnt(0)
; #define LAS __attribute__((address_space(3)))
; #define MFMA16(a, b, c) __builtin_amdgcn_mfma_f32_16x16x32_bf16((a), (b), (c), 0, 0, 0)
; __device__ void ret_out_phase(LAS unsigned char* lds, const bf16_t* PROJ, const bf16_t* ST, bf16_t* MIX, const float* lgf, const float* lgb, const float* ogain) {
;     ...
;             for (int i = 0; i < 8; ++i) *(LAS u32x4*)(buf + ((tid >> 5) + 16 * i) * RP + (tid & 31) * 16) = stg[i];
;     ...
;                 for (int ccl = 0; ccl < 8; ++ccl)
; #pragma unroll
;                     for (int ks = 0; ks < 8; ++ks) { const bf16x8 bfrag = *(const LAS bf16x8*)(buf + (16 * ccl + fr) * RP + (32 * ks + 8 * g) * 2); o[(s & 1) * 8 + ccl] = MFMA16(qf[ks], bfrag, o[(s & 1) * 8 + ccl]); }
	v_mfma_f32_16x16x32_bf16 v[86:89], v[62:65], v[86:89], 0
	v_mfma_f32_16x16x32_bf16 v[86:89], v[58:61], v[90:93], v[86:89]
	ds_read_b128 v[90:93], v192 offset:34944
	ds_read_b128 v[130:133], v192 offset:35008
	ds_read_b128 v[134:137], v192 offset:35072
	ds_read_b128 v[138:141], v192 offset:35136
	s_waitcnt lgkmcnt(3)
	v_mfma_f32_16x16x32_bf16 v[86:89], v[54:57], v[90:93], v[86:89]
	ds_read_b128 v[90:93], v192 offset:35200
	s_waitcnt lgkmcnt(3)
	v_mfma_f32_16x16x32_bf16 v[86:89], v[50:53], v[130:133], v[86:89]
	ds_read_b128 v[130:133], v192 offset:35264
	s_waitcnt lgkmcnt(3)
	v_mfma_f32_16x16x32_bf16 v[86:89], v[46:49], v[134:137], v[86:89]
	s_waitcnt lgkmcnt(2)
	v_mfma_f32_16x16x32_bf16 v[86:89], v[42:45], v[138:141], v[86:89]
	s_waitcnt lgkmcnt(1)
	v_mfma_f32_16x16x32_bf16 v[86:89], v[38:41], v[90:93], v[86:89]
	s_waitcnt lgkmcnt(0)
	v_mfma_f32_16x16x32_bf16 v[86:89], v[34:37], v[130:133], v[86:89]
	ds_read_b128 v[90:93], v192 offset:43520
	s_waitcnt lgkmcnt(0)
	v_mfma_f32_16x16x32_bf16 v[90:93], v[62:65], v[90:93], 0
	v_mfma_f32_16x16x32_bf16 v[90:93], v[58:61], v[122:125], v[90:93]
	ds_read_b128 v[122:125], v192 offset:43648
	ds_read_b128 v[130:133], v192 offset:43712
	ds_read_b128 v[134:137], v192 offset:43776
	ds_read_b128 v[138:141], v192 offset:43840
	s_waitcnt lgkmcnt(3)
	v_mfma_f32_16x16x32_bf16 v[90:93], v[54:57], v[122:125], v[90:93]
	ds_read_b128 v[122:125], v192 offset:43904
	s_waitcnt lgkmcnt(3)
	v_mfma_f32_16x16x32_bf16 v[90:93], v[50:53], v[130:133], v[90:93]
	ds_read_b128 v[130:133], v192 offset:43968
	s_waitcnt lgkmcnt(3)
	v_mfma_f32_16x16x32_bf16 v[90:93], v[46:49], v[134:137], v[90:93]
	s_waitcnt lgkmcnt(2)
	v_mfma_f32_16x16x32_bf16 v[90:93], v[42:45], v[138:141], v[90:93]
	s_waitcnt lgkmcnt(1)
	v_mfma_f32_16x16x32_bf16 v[90:93], v[38:41], v[122:125], v[90:93]
	s_waitcnt lgkmcnt(0)
	v_mfma_f32_16x16x32_bf16 v[90:93], v[34:37], v[130:133], v[90:93]
	ds_read_b128 v[122:125], v192 offset:52224
	s_waitcnt lgkmcnt(0)
	v_mfma_f32_16x16x32_bf16 v[122:125], v[62:65], v[122:125], 0
	v_mfma_f32_16x16x32_bf16 v[122:125], v[58:61], v[126:129], v[122:125]
	ds_read_b128 v[126:129], v192 offset:52352
	ds_read_b128 v[134:137], v192 offset:52416
	ds_read_b128 v[138:141], v192 offset:52480
	ds_read_b128 v[142:145], v192 offset:52544
	s_waitcnt lgkmcnt(3)
	v_mfma_f32_16x16x32_bf16 v[122:125], v[54:57], v[126:129], v[122:125]
	ds_read_b128 v[126:129], v192 offset:52608
	s_waitcnt lgkmcnt(3)
	v_mfma_f32_16x16x32_bf16 v[122:125], v[50:53], v[134:137], v[122:125]
	ds_read_b128 v[134:137], v192 offset:52672
	s_waitcnt lgkmcnt(3)
	v_mfma_f32_16x16x32_bf16 v[122:125], v[46:49], v[138:141], v[122:125]
	s_waitcnt lgkmcnt(2)
	v_mfma_f32_16x16x32_bf16 v[122:125], v[42:45], v[142:145], v[122:125]
	s_waitcnt lgkmcnt(1)
	v_mfma_f32_16x16x32_bf16 v[122:125], v[38:41], v[126:129], v[122:125]
	s_waitcnt lgkmcnt(0)
	v_mfma_f32_16x16x32_bf16 v[130:133], v[34:37], v[134:137], v[122:125]
	ds_read_b128 v[126:129], v192 offset:60992
	s_nop 3
	ds_read_b128 v[122:125], v192 offset:60928
	s_waitcnt lgkmcnt(0)
	v_mfma_f32_16x16x32_bf16 v[122:125], v[62:65], v[122:125], 0
	v_mfma_f32_16x16x32_bf16 v[122:125], v[58:61], v[126:129], v[122:125]
	ds_read_b128 v[126:129], v192 offset:61056
	ds_read_b128 v[134:137], v192 offset:61120
	ds_read_b128 v[138:141], v192 offset:61184
	ds_read_b128 v[142:145], v192 offset:61248
	s_waitcnt lgkmcnt(3)
	v_mfma_f32_16x16x32_bf16 v[122:125], v[54:57], v[126:129], v[122:125]
	ds_read_b128 v[126:129], v192 offset:61312
	s_waitcnt lgkmcnt(3)
	v_mfma_f32_16x16x32_bf16 v[122:125], v[50:53], v[134:137], v[122:125]
	s_waitcnt lgkmcnt(2)
	v_mfma_f32_16x16x32_bf16 v[122:125], v[46:49], v[138:141], v[122:125]
	s_waitcnt lgkmcnt(1)
	v_mfma_f32_16x16x32_bf16 v[122:125], v[42:45], v[142:145], v[122:125]
	s_waitcnt lgkmcnt(0)
	v_mfma_f32_16x16x32_bf16 v[122:125], v[38:41], v[126:129], v[122:125]
	ds_read_b128 v[126:129], v192 offset:61376
	s_waitcnt vmcnt(3)
	ds_write_b128 v210, v[26:29]
	s_waitcnt vmcnt(1)
	ds_write_b128 v210, v[30:33] offset:8704
	ds_write_b128 v210, v[98:101] offset:17408
	ds_write_b128 v210, v[102:105] offset:26112
	ds_write_b128 v210, v[106:109] offset:34816
	ds_write_b128 v210, v[110:113] offset:43520
	ds_write_b128 v210, v[114:117] offset:52224
	s_waitcnt vmcnt(0)
	ds_write_b128 v210, v[118:121] offset:60928
	s_waitcnt lgkmcnt(0)
	v_mfma_f32_16x16x32_bf16 v[134:137], v[34:37], v[126:129], v[122:125]
	s_barrier
; #define LAS __attribute__((address_space(3)))
; #define MFMA16(a, b, c) __builtin_amdgcn_mfma_f32_16x16x32_bf16((a), (b), (c), 0, 0, 0)
; __device__ void ret_out_phase(LAS unsigned char* lds, const bf16_t* PROJ, const bf16_t* ST, bf16_t* MIX, const float* lgf, const float* lgb, const float* ogain) {
;     ...
;             if (s < 4) {
; #pragma unroll
;                 for (int ccl = 0; ccl < 8; ++ccl)
; #pragma unroll
;                     for (int ks = 0; ks < 8; ++ks) { const bf16x8 bfrag = *(const LAS bf16x8*)(buf + (16 * ccl + fr) * RP + (32 * ks + 8 * g) * 2); o[(s & 1) * 8 + ccl] = MFMA16(qf[ks], bfrag, o[(s & 1) * 8 + ccl]); }
;                 if (s & 1) {
; #pragma unroll
;                     for (int j = 0; j < 4; ++j) { const int il = half * 128 + 16 * wave + 4 * g + j;
;                         const float sc = s == 1 ? __expf(lf * (float)(il + 1) - lb * (float)(256 - il)) : __expf(lb * (float)(256 - il));
; #pragma unroll
;                         for (int cc = 0; cc < 16; ++cc) o[cc][j] *= sc; }
;                 }
	s_nop 1
	v_sub_u32_e32 v124, 0x100, v167
	v_or_b32_e32 v122, 1, v167
	v_cvt_f32_i32_e32 v124, v124
	v_cvt_f32_i32_e32 v123, v122
	v_sub_u32_e32 v122, 0x100, v122
	v_cvt_f32_i32_e32 v122, v122
	v_mul_f32_e32 v169, v185, v124
	v_fma_f32 v123, v184, v123, -v169
	v_mul_f32_e32 v123, 0x3fb8aa3b, v123
	v_exp_f32_e32 v142, v123
	v_or_b32_e32 v123, 2, v167
	v_cvt_f32_i32_e32 v124, v123
	v_mul_f32_e32 v122, v185, v122
	v_sub_u32_e32 v123, 0x100, v123
	v_cvt_f32_i32_e32 v123, v123
	v_fma_f32 v122, v184, v124, -v122
	v_mul_f32_e32 v122, 0x3fb8aa3b, v122
	v_exp_f32_e32 v143, v122
	v_or_b32_e32 v122, 3, v167
	v_cvt_f32_i32_e32 v124, v122
	v_mul_f32_e32 v171, v185, v123
	v_pk_mul_f32 v[138:139], v[142:143], v[2:3]
	v_pk_mul_f32 v[2:3], v[142:143], v[6:7]
	v_fma_f32 v123, v184, v124, -v171
	v_mul_f32_e32 v123, 0x3fb8aa3b, v123
	v_exp_f32_e32 v144, v123
	v_sub_u32_e32 v123, 0x100, v122
	v_add_u32_e32 v122, 4, v167
	v_cvt_f32_i32_e32 v122, v122
	v_cvt_f32_i32_e32 v123, v123
	v_pk_mul_f32 v[6:7], v[142:143], v[10:11]
	v_pk_mul_f32 v[10:11], v[142:143], v[14:15]
	v_mov_b32_e32 v14, v226
	v_pk_mul_f32 v[186:187], v[184:185], v[122:123]
	s_nop 0
	v_sub_f32_e32 v122, v186, v187
	v_mul_f32_e32 v122, 0x3fb8aa3b, v122
	v_exp_f32_e32 v145, v122
	v_pk_mul_f32 v[126:127], v[142:143], v[66:67]
	v_lshlrev_b32_e32 v14, 4, v14
	v_ashrrev_i32_e32 v15, 31, v14
	v_lshl_add_u64 v[14:15], s[4:5], 0, v[14:15]
	v_pk_mul_f32 v[140:141], v[144:145], v[4:5]
	v_pk_mul_f32 v[4:5], v[144:145], v[8:9]
	v_pk_mul_f32 v[8:9], v[144:145], v[12:13]
	v_pk_mul_f32 v[12:13], v[144:145], v[16:17]
	v_add_co_u32_e32 v16, vcc, s16, v14
	v_pk_mul_f32 v[128:129], v[144:145], v[68:69]
	s_nop 0
	v_addc_co_u32_e32 v17, vcc, 0, v15, vcc
	global_load_dwordx4 v[98:101], v[16:17], off
	v_add_co_u32_e32 v16, vcc, s17, v14
	v_pk_mul_f32 v[124:125], v[144:145], v[96:97]
	s_nop 0
	v_addc_co_u32_e32 v17, vcc, 0, v15, vcc
	global_load_dwordx4 v[102:105], v[16:17], off
	v_add_co_u32_e32 v16, vcc, s18, v14
	v_pk_mul_f32 v[122:123], v[142:143], v[94:95]
	s_nop 0
	v_addc_co_u32_e32 v17, vcc, 0, v15, vcc
	global_load_dwordx4 v[106:109], v[16:17], off
	v_add_co_u32_e32 v16, vcc, s20, v14
	v_pk_mul_f32 v[68:69], v[144:145], v[72:73]
	s_nop 0
	v_addc_co_u32_e32 v17, vcc, 0, v15, vcc
	global_load_dwordx4 v[110:113], v[16:17], off
	v_add_co_u32_e32 v16, vcc, s21, v14
	v_pk_mul_f32 v[66:67], v[142:143], v[70:71]
	s_nop 0
	v_addc_co_u32_e32 v17, vcc, 0, v15, vcc
	global_load_dwordx4 v[114:117], v[16:17], off
	v_add_co_u32_e32 v16, vcc, s22, v14
	v_pk_mul_f32 v[72:73], v[144:145], v[76:77]
	s_nop 0
	v_addc_co_u32_e32 v17, vcc, 0, v15, vcc
	global_load_dwordx4 v[118:121], v[16:17], off
	v_add_co_u32_e32 v16, vcc, s23, v14
	v_pk_mul_f32 v[70:71], v[142:143], v[74:75]
	s_nop 0
	v_addc_co_u32_e32 v17, vcc, 0, v15, vcc
	v_add_co_u32_e32 v14, vcc, s24, v14
	v_pk_mul_f32 v[76:77], v[144:145], v[80:81]
	s_nop 0
	v_addc_co_u32_e32 v15, vcc, 0, v15, vcc
	v_pk_mul_f32 v[74:75], v[142:143], v[78:79]
	v_pk_mul_f32 v[80:81], v[144:145], v[84:85]
	v_pk_mul_f32 v[78:79], v[142:143], v[82:83]
	v_pk_mul_f32 v[84:85], v[144:145], v[88:89]
	v_pk_mul_f32 v[82:83], v[142:143], v[86:87]
	v_pk_mul_f32 v[88:89], v[144:145], v[92:93]
	v_pk_mul_f32 v[86:87], v[142:143], v[90:91]
	v_pk_mul_f32 v[92:93], v[144:145], v[132:133]
	v_pk_mul_f32 v[90:91], v[142:143], v[130:131]
	v_pk_mul_f32 v[96:97], v[144:145], v[136:137]
	v_pk_mul_f32 v[94:95], v[142:143], v[134:135]
	global_load_dwordx4 v[130:133], v[16:17], off
	global_load_dwordx4 v[134:137], v[14:15], off
	ds_read_b128 v[14:17], v191
	ds_read_b128 v[26:29], v191 offset:64
	s_waitcnt lgkmcnt(1)
	v_mfma_f32_16x16x32_bf16 v[14:17], v[62:65], v[14:17], v[138:141]
	v_mul_f32_e64 v20, v144, v20
	v_mul_f32_e64 v21, v145, v21
	v_pk_mul_f32 v[18:19], v[142:143], v[18:19]
	ds_read_b128 v[30:33], v191 offset:52288
	s_waitcnt lgkmcnt(1)
	v_mfma_f32_16x16x32_bf16 v[14:17], v[58:61], v[26:29], v[14:17]
	ds_read_b128 v[26:29], v191 offset:128
	v_pk_mul_f32 v[24:25], v[144:145], v[24:25]
	v_pk_mul_f32 v[22:23], v[142:143], v[22:23]
	s_waitcnt lgkmcnt(0)
	v_mfma_f32_16x16x32_bf16 v[14:17], v[54:57], v[26:29], v[14:17]
	ds_read_b128 v[26:29], v191 offset:192
	s_add_u32 s4, s0, s15
	s_addc_u32 s5, s1, 0
	s_waitcnt lgkmcnt(0)
	v_mfma_f32_16x16x32_bf16 v[14:17], v[50:53], v[26:29], v[14:17]
	ds_read_b128 v[26:29], v191 offset:256
	s_lshl_b64 s[4:5], s[4:5], 9
	s_add_u32 s4, s78, s4
	s_waitcnt lgkmcnt(0)
	v_mfma_f32_16x16x32_bf16 v[14:17], v[46:49], v[26:29], v[14:17]
	ds_read_b128 v[26:29], v191 offset:320
	s_addc_u32 s5, s79, s5
	s_mov_b32 s17, 0x9002000
	s_waitcnt lgkmcnt(0)
	v_mfma_f32_16x16x32_bf16 v[14:17], v[42:45], v[26:29], v[14:17]
	ds_read_b128 v[26:29], v191 offset:384
	s_mov_b32 s18, 0x9004000
	s_mov_b32 s20, 0x9006000
	s_waitcnt lgkmcnt(0)
	v_mfma_f32_16x16x32_bf16 v[14:17], v[38:41], v[26:29], v[14:17]
	ds_read_b128 v[26:29], v191 offset:448
	s_mov_b32 s21, 0x9008000
	s_mov_b32 s22, 0x900a000
	s_waitcnt lgkmcnt(0)
	v_mfma_f32_16x16x32_bf16 v[14:17], v[34:37], v[26:29], v[14:17]
	ds_read_b128 v[26:29], v191 offset:8704
	s_mov_b32 s23, 0x900c000
	s_mov_b32 s24, 0x900e000
	s_waitcnt lgkmcnt(0)
	v_mfma_f32_16x16x32_bf16 v[2:5], v[62:65], v[26:29], v[2:5]
	ds_read_b128 v[26:29], v191 offset:8768
	s_add_i32 s16, s13, 0x30000
	s_waitcnt lgkmcnt(0)
	v_mfma_f32_16x16x32_bf16 v[2:5], v[58:61], v[26:29], v[2:5]
	ds_read_b128 v[26:29], v191 offset:8832
	ds_read_b128 v[138:141], v191 offset:8896
	ds_read_b128 v[142:145], v191 offset:8960
	ds_read_b128 v[146:149], v191 offset:9024
	s_waitcnt lgkmcnt(3)
	v_mfma_f32_16x16x32_bf16 v[2:5], v[54:57], v[26:29], v[2:5]
	ds_read_b128 v[26:29], v191 offset:9088
	s_waitcnt lgkmcnt(3)
; #define LAS __attribute__((address_space(3)))
; #define MFMA16(a, b, c) __builtin_amdgcn_mfma_f32_16x16x32_bf16((a), (b), (c), 0, 0, 0)
; __device__ void ret_out_phase(LAS unsigned char* lds, const bf16_t* PROJ, const bf16_t* ST, bf16_t* MIX, const float* lgf, const float* lgb, const float* ogain) {
;     ...
;                 for (int ccl = 0; ccl < 8; ++ccl)
; #pragma unroll
;                     for (int ks = 0; ks < 8; ++ks) { const bf16x8 bfrag = *(const LAS bf16x8*)(buf + (16 * ccl + fr) * RP + (32 * ks + 8 * g) * 2); o[(s & 1) * 8 + ccl] = MFMA16(qf[ks], bfrag, o[(s & 1) * 8 + ccl]); }
	v_mfma_f32_16x16x32_bf16 v[2:5], v[50:53], v[138:141], v[2:5]
	ds_read_b128 v[138:141], v191 offset:9152
	s_waitcnt lgkmcnt(3)
	v_mfma_f32_16x16x32_bf16 v[2:5], v[46:49], v[142:145], v[2:5]
	ds_read_b128 v[142:145], v191 offset:17408
	s_waitcnt lgkmcnt(3)
	v_mfma_f32_16x16x32_bf16 v[2:5], v[42:45], v[146:149], v[2:5]
	ds_read_b128 v[146:149], v191 offset:17472
	s_waitcnt lgkmcnt(3)
	v_mfma_f32_16x16x32_bf16 v[2:5], v[38:41], v[26:29], v[2:5]
	ds_read_b128 v[26:29], v191 offset:17536
	s_waitcnt lgkmcnt(3)
	v_mfma_f32_16x16x32_bf16 v[2:5], v[34:37], v[138:141], v[2:5]
	ds_read_b128 v[138:141], v191 offset:17600
	s_waitcnt lgkmcnt(3)
	v_mfma_f32_16x16x32_bf16 v[6:9], v[62:65], v[142:145], v[6:9]
	ds_read_b128 v[142:145], v191 offset:17664
	s_waitcnt lgkmcnt(3)
	v_mfma_f32_16x16x32_bf16 v[6:9], v[58:61], v[146:149], v[6:9]
	ds_read_b128 v[146:149], v191 offset:17728
	s_waitcnt lgkmcnt(3)
	v_mfma_f32_16x16x32_bf16 v[6:9], v[54:57], v[26:29], v[6:9]
	ds_read_b128 v[26:29], v191 offset:17792
	s_waitcnt lgkmcnt(3)
	v_mfma_f32_16x16x32_bf16 v[6:9], v[50:53], v[138:141], v[6:9]
	ds_read_b128 v[138:141], v191 offset:17856
	s_waitcnt lgkmcnt(3)
	v_mfma_f32_16x16x32_bf16 v[6:9], v[46:49], v[142:145], v[6:9]
	ds_read_b128 v[142:145], v191 offset:26112
	s_waitcnt lgkmcnt(3)
	v_mfma_f32_16x16x32_bf16 v[6:9], v[42:45], v[146:149], v[6:9]
	ds_read_b128 v[146:149], v191 offset:26176
	s_waitcnt lgkmcnt(3)
	v_mfma_f32_16x16x32_bf16 v[6:9], v[38:41], v[26:29], v[6:9]
	ds_read_b128 v[26:29], v191 offset:26240
	s_waitcnt lgkmcnt(3)
	v_mfma_f32_16x16x32_bf16 v[6:9], v[34:37], v[138:141], v[6:9]
	ds_read_b128 v[138:141], v191 offset:26304
	s_waitcnt lgkmcnt(3)
	v_mfma_f32_16x16x32_bf16 v[10:13], v[62:65], v[142:145], v[10:13]
	ds_read_b128 v[142:145], v191 offset:26368
	s_waitcnt lgkmcnt(3)
	v_mfma_f32_16x16x32_bf16 v[10:13], v[58:61], v[146:149], v[10:13]
	ds_read_b128 v[146:149], v191 offset:26432
	s_waitcnt lgkmcnt(3)
	v_mfma_f32_16x16x32_bf16 v[10:13], v[54:57], v[26:29], v[10:13]
	ds_read_b128 v[26:29], v191 offset:26496
	s_waitcnt lgkmcnt(3)
	v_mfma_f32_16x16x32_bf16 v[10:13], v[50:53], v[138:141], v[10:13]
	ds_read_b128 v[138:141], v191 offset:26560
	s_waitcnt lgkmcnt(3)
	v_mfma_f32_16x16x32_bf16 v[10:13], v[46:49], v[142:145], v[10:13]
	ds_read_b128 v[142:145], v191 offset:34816
	s_waitcnt lgkmcnt(3)
	v_mfma_f32_16x16x32_bf16 v[10:13], v[42:45], v[146:149], v[10:13]
	ds_read_b128 v[146:149], v191 offset:34880
	s_waitcnt lgkmcnt(3)
	v_mfma_f32_16x16x32_bf16 v[10:13], v[38:41], v[26:29], v[10:13]
	ds_read_b128 v[26:29], v191 offset:34944
	s_waitcnt lgkmcnt(3)
	v_mfma_f32_16x16x32_bf16 v[10:13], v[34:37], v[138:141], v[10:13]
	ds_read_b128 v[138:141], v191 offset:35008
	s_waitcnt lgkmcnt(3)
	v_mfma_f32_16x16x32_bf16 v[18:21], v[62:65], v[142:145], v[18:21]
	ds_read_b128 v[142:145], v191 offset:35072
	s_waitcnt lgkmcnt(3)
	v_mfma_f32_16x16x32_bf16 v[18:21], v[58:61], v[146:149], v[18:21]
	ds_read_b128 v[146:149], v191 offset:35136
	s_waitcnt lgkmcnt(3)
	v_mfma_f32_16x16x32_bf16 v[18:21], v[54:57], v[26:29], v[18:21]
	ds_read_b128 v[26:29], v191 offset:35200
	s_waitcnt lgkmcnt(3)
	v_mfma_f32_16x16x32_bf16 v[18:21], v[50:53], v[138:141], v[18:21]
	ds_read_b128 v[138:141], v191 offset:35264
	s_waitcnt lgkmcnt(3)
	v_mfma_f32_16x16x32_bf16 v[18:21], v[46:49], v[142:145], v[18:21]
	ds_read_b128 v[142:145], v191 offset:43520
	s_waitcnt lgkmcnt(3)
	v_mfma_f32_16x16x32_bf16 v[18:21], v[42:45], v[146:149], v[18:21]
	ds_read_b128 v[146:149], v191 offset:43584
	s_waitcnt lgkmcnt(3)
	v_mfma_f32_16x16x32_bf16 v[18:21], v[38:41], v[26:29], v[18:21]
	ds_read_b128 v[26:29], v191 offset:43648
	s_waitcnt lgkmcnt(3)
	v_mfma_f32_16x16x32_bf16 v[18:21], v[34:37], v[138:141], v[18:21]
	ds_read_b128 v[138:141], v191 offset:43712
	s_waitcnt lgkmcnt(3)
	v_mfma_f32_16x16x32_bf16 v[22:25], v[62:65], v[142:145], v[22:25]
	ds_read_b128 v[142:145], v191 offset:43776
	s_waitcnt lgkmcnt(3)
	v_mfma_f32_16x16x32_bf16 v[22:25], v[58:61], v[146:149], v[22:25]
	ds_read_b128 v[146:149], v191 offset:43840
	s_waitcnt lgkmcnt(3)
	v_mfma_f32_16x16x32_bf16 v[22:25], v[54:57], v[26:29], v[22:25]
	ds_read_b128 v[26:29], v191 offset:43904
	s_waitcnt lgkmcnt(3)
	v_mfma_f32_16x16x32_bf16 v[22:25], v[50:53], v[138:141], v[22:25]
	ds_read_b128 v[138:141], v191 offset:43968
	s_waitcnt lgkmcnt(3)
	v_mfma_f32_16x16x32_bf16 v[22:25], v[46:49], v[142:145], v[22:25]
	s_waitcnt lgkmcnt(2)
	v_mfma_f32_16x16x32_bf16 v[22:25], v[42:45], v[146:149], v[22:25]
	s_waitcnt lgkmcnt(1)
	v_mfma_f32_16x16x32_bf16 v[22:25], v[38:41], v[26:29], v[22:25]
	s_waitcnt lgkmcnt(0)
	v_mfma_f32_16x16x32_bf16 v[22:25], v[34:37], v[138:141], v[22:25]
	ds_read_b128 v[26:29], v191 offset:52224
	s_waitcnt lgkmcnt(0)
	v_mfma_f32_16x16x32_bf16 v[26:29], v[62:65], v[26:29], v[126:129]
	v_mfma_f32_16x16x32_bf16 v[26:29], v[58:61], v[30:33], v[26:29]
	ds_read_b128 v[30:33], v191 offset:52352
	ds_read_b128 v[126:129], v191 offset:52416
	ds_read_b128 v[138:141], v191 offset:52480
	ds_read_b128 v[142:145], v191 offset:52544
	s_waitcnt lgkmcnt(3)
	v_mfma_f32_16x16x32_bf16 v[26:29], v[54:57], v[30:33], v[26:29]
	ds_read_b128 v[30:33], v191 offset:52608
	s_waitcnt lgkmcnt(3)
	v_mfma_f32_16x16x32_bf16 v[26:29], v[50:53], v[126:129], v[26:29]
	ds_read_b128 v[126:129], v191 offset:52672
	s_waitcnt lgkmcnt(3)
	v_mfma_f32_16x16x32_bf16 v[26:29], v[46:49], v[138:141], v[26:29]
	s_waitcnt lgkmcnt(2)
	v_mfma_f32_16x16x32_bf16 v[26:29], v[42:45], v[142:145], v[26:29]
	s_waitcnt lgkmcnt(1)
	v_mfma_f32_16x16x32_bf16 v[26:29], v[38:41], v[30:33], v[26:29]
	s_waitcnt lgkmcnt(0)
	v_mfma_f32_16x16x32_bf16 v[26:29], v[34:37], v[126:129], v[26:29]
	ds_read_b128 v[30:33], v191 offset:60928
	s_waitcnt lgkmcnt(0)
; #define LAS __attribute__((address_space(3)))
; #define MFMA16(a, b, c) __builtin_amdgcn_mfma_f32_16x16x32_bf16((a), (b), (c), 0, 0, 0)
; #define RET_ISSUE(s_, it_) do { const bf16_t* bp_; int pt_; RET_SRC(s_, it_, bp_, pt_); const int tv_ = otid(); const char* sb_ = (const char*)bp_ + (size_t)(((tv_ >> 5) * pt_ + (tv_ & 31) * 8) * 2); const size_t step_ = (size_t)pt_ * 32; \
;         _Pragma("unroll") for (int i_ = 0; i_ < 8; ++i_) stg[i_] = *(const u32x4*)(sb_ + i_ * step_); } while (0)
; __device__ void ret_out_phase(LAS unsigned char* lds, const bf16_t* PROJ, const bf16_t* ST, bf16_t* MIX, const float* lgf, const float* lgb, const float* ogain) {
;     ...
;             for (int i = 0; i < 8; ++i) *(LAS u32x4*)(buf + ((tid >> 5) + 16 * i) * RP + (tid & 31) * 16) = stg[i];
;             __syncthreads();
;             if (s < 7) { RET_ISSUE(s + 1, ri); }
;             else if (item + (int)gridDim.x < 768) { const RetItem rn = ret_decode(item + gridDim.x); RET_ISSUE(0, rn); }
;     ...
;                 for (int ccl = 0; ccl < 8; ++ccl)
; #pragma unroll
;                     for (int ks = 0; ks < 8; ++ks) { const bf16x8 bfrag = *(const LAS bf16x8*)(buf + (16 * ccl + fr) * RP + (32 * ks + 8 * g) * 2); o[(s & 1) * 8 + ccl] = MFMA16(qf[ks], bfrag, o[(s & 1) * 8 + ccl]); }
	v_mfma_f32_16x16x32_bf16 v[30:33], v[62:65], v[30:33], v[122:125]
	s_nop 2
	ds_read_b128 v[122:125], v191 offset:60992
	ds_read_b128 v[126:129], v191 offset:61056
	ds_read_b128 v[138:141], v191 offset:61120
	ds_read_b128 v[142:145], v191 offset:61184
	s_waitcnt lgkmcnt(3)
	v_mfma_f32_16x16x32_bf16 v[30:33], v[58:61], v[122:125], v[30:33]
	ds_read_b128 v[122:125], v191 offset:61248
	s_waitcnt lgkmcnt(3)
	v_mfma_f32_16x16x32_bf16 v[30:33], v[54:57], v[126:129], v[30:33]
	ds_read_b128 v[126:129], v191 offset:61312
	s_waitcnt lgkmcnt(3)
	v_mfma_f32_16x16x32_bf16 v[30:33], v[50:53], v[138:141], v[30:33]
	s_waitcnt lgkmcnt(2)
	v_mfma_f32_16x16x32_bf16 v[30:33], v[46:49], v[142:145], v[30:33]
	s_waitcnt lgkmcnt(1)
	v_mfma_f32_16x16x32_bf16 v[30:33], v[42:45], v[122:125], v[30:33]
	s_waitcnt lgkmcnt(0)
	v_mfma_f32_16x16x32_bf16 v[30:33], v[38:41], v[126:129], v[30:33]
	ds_read_b128 v[122:125], v191 offset:61376
	s_waitcnt vmcnt(7)
	ds_write_b128 v211, v[98:101]
	s_waitcnt vmcnt(6)
	ds_write_b128 v211, v[102:105] offset:8704
	s_waitcnt vmcnt(5)
	ds_write_b128 v211, v[106:109] offset:17408
	s_waitcnt vmcnt(4)
	ds_write_b128 v211, v[110:113] offset:26112
	s_waitcnt vmcnt(3)
	ds_write_b128 v211, v[114:117] offset:34816
	s_waitcnt vmcnt(2)
	ds_write_b128 v211, v[118:121] offset:43520
	s_waitcnt vmcnt(1)
	ds_write_b128 v211, v[130:133] offset:52224
	s_waitcnt vmcnt(0)
	ds_write_b128 v211, v[134:137] offset:60928
	v_mov_b32_e32 v98, v226
	s_waitcnt lgkmcnt(0)
	s_barrier
	ds_read_b128 v[130:133], v192
	s_waitcnt lgkmcnt(0)
	v_mfma_f32_16x16x32_bf16 v[66:69], v[62:65], v[130:133], v[66:69]
	ds_read_b128 v[130:133], v192 offset:64
	v_lshlrev_b32_e32 v98, 4, v98
	v_ashrrev_i32_e32 v99, 31, v98
	s_waitcnt lgkmcnt(0)
	v_mfma_f32_16x16x32_bf16 v[66:69], v[58:61], v[130:133], v[66:69]
	ds_read_b128 v[130:133], v192 offset:128
	v_lshl_add_u64 v[126:127], s[4:5], 0, v[98:99]
	v_add_co_u32_e32 v98, vcc, s33, v126
	s_waitcnt lgkmcnt(0)
	v_mfma_f32_16x16x32_bf16 v[66:69], v[54:57], v[130:133], v[66:69]
	ds_read_b128 v[130:133], v192 offset:192
	v_addc_co_u32_e32 v99, vcc, 0, v127, vcc
	s_waitcnt lgkmcnt(0)
	v_mfma_f32_16x16x32_bf16 v[66:69], v[50:53], v[130:133], v[66:69]
	ds_read_b128 v[130:133], v192 offset:256
	v_add_co_u32_e32 v102, vcc, s17, v126
	s_waitcnt lgkmcnt(0)
	v_mfma_f32_16x16x32_bf16 v[66:69], v[46:49], v[130:133], v[66:69]
	ds_read_b128 v[130:133], v192 offset:320
	v_addc_co_u32_e32 v103, vcc, 0, v127, vcc
	s_waitcnt lgkmcnt(0)
	v_mfma_f32_16x16x32_bf16 v[66:69], v[42:45], v[130:133], v[66:69]
	ds_read_b128 v[130:133], v192 offset:384
	v_add_co_u32_e32 v106, vcc, s18, v126
	s_waitcnt lgkmcnt(0)
	v_mfma_f32_16x16x32_bf16 v[66:69], v[38:41], v[130:133], v[66:69]
	ds_read_b128 v[130:133], v192 offset:448
	v_addc_co_u32_e32 v107, vcc, 0, v127, vcc
	s_waitcnt lgkmcnt(0)
	v_mfma_f32_16x16x32_bf16 v[66:69], v[34:37], v[130:133], v[66:69]
	ds_read_b128 v[130:133], v192 offset:8704
	v_add_co_u32_e32 v110, vcc, s20, v126
	s_waitcnt lgkmcnt(0)
	v_mfma_f32_16x16x32_bf16 v[70:73], v[62:65], v[130:133], v[70:73]
	ds_read_b128 v[130:133], v192 offset:8768
	v_addc_co_u32_e32 v111, vcc, 0, v127, vcc
	s_waitcnt lgkmcnt(0)
	v_mfma_f32_16x16x32_bf16 v[70:73], v[58:61], v[130:133], v[70:73]
	ds_read_b128 v[130:133], v192 offset:8832
	v_add_co_u32_e32 v114, vcc, s21, v126
	s_waitcnt lgkmcnt(0)
	v_mfma_f32_16x16x32_bf16 v[70:73], v[54:57], v[130:133], v[70:73]
	ds_read_b128 v[130:133], v192 offset:8896
	global_load_dwordx4 v[98:101], v[98:99], off
	v_addc_co_u32_e32 v115, vcc, 0, v127, vcc
	s_waitcnt lgkmcnt(0)
	v_mfma_f32_16x16x32_bf16 v[70:73], v[50:53], v[130:133], v[70:73]
	ds_read_b128 v[130:133], v192 offset:8960
	global_load_dwordx4 v[102:105], v[102:103], off
	v_add_co_u32_e32 v118, vcc, s22, v126
	s_waitcnt lgkmcnt(0)
	v_mfma_f32_16x16x32_bf16 v[70:73], v[46:49], v[130:133], v[70:73]
	ds_read_b128 v[130:133], v192 offset:9024
	global_load_dwordx4 v[106:109], v[106:107], off
	v_addc_co_u32_e32 v119, vcc, 0, v127, vcc
	s_waitcnt lgkmcnt(0)
	v_mfma_f32_16x16x32_bf16 v[70:73], v[42:45], v[130:133], v[70:73]
	ds_read_b128 v[130:133], v192 offset:9088
	global_load_dwordx4 v[110:113], v[110:111], off
	s_add_u32 s4, s0, s16
	s_waitcnt lgkmcnt(0)
	v_mfma_f32_16x16x32_bf16 v[70:73], v[38:41], v[130:133], v[70:73]
	ds_read_b128 v[130:133], v192 offset:9152
	global_load_dwordx4 v[114:117], v[114:115], off
	s_addc_u32 s5, s1, 0
	s_waitcnt lgkmcnt(0)
	v_mfma_f32_16x16x32_bf16 v[70:73], v[34:37], v[130:133], v[70:73]
	ds_read_b128 v[130:133], v192 offset:17408
	global_load_dwordx4 v[118:121], v[118:119], off
	s_lshl_b64 s[4:5], s[4:5], 9
	s_waitcnt lgkmcnt(0)
	v_mfma_f32_16x16x32_bf16 v[74:77], v[62:65], v[130:133], v[74:77]
	ds_read_b128 v[130:133], v192 offset:17472
	s_add_u32 s4, s78, s4
	s_addc_u32 s5, s79, s5
	s_waitcnt lgkmcnt(0)
	v_mfma_f32_16x16x32_bf16 v[74:77], v[58:61], v[130:133], v[74:77]
	ds_read_b128 v[130:133], v192 offset:17536
	ds_read_b128 v[134:137], v192 offset:17600
	ds_read_b128 v[138:141], v192 offset:17664
	ds_read_b128 v[142:145], v192 offset:17728
	s_waitcnt lgkmcnt(3)
	v_mfma_f32_16x16x32_bf16 v[74:77], v[54:57], v[130:133], v[74:77]
	ds_read_b128 v[130:133], v192 offset:17792
	s_waitcnt lgkmcnt(3)
	v_mfma_f32_16x16x32_bf16 v[74:77], v[50:53], v[134:137], v[74:77]
	ds_read_b128 v[134:137], v192 offset:17856
	s_waitcnt lgkmcnt(3)
	v_mfma_f32_16x16x32_bf16 v[74:77], v[46:49], v[138:141], v[74:77]
	ds_read_b128 v[138:141], v192 offset:26112
	s_waitcnt lgkmcnt(3)
	v_mfma_f32_16x16x32_bf16 v[74:77], v[42:45], v[142:145], v[74:77]
	ds_read_b128 v[142:145], v192 offset:26176
	s_waitcnt lgkmcnt(3)
; #define LAS __attribute__((address_space(3)))
; #define MFMA16(a, b, c) __builtin_amdgcn_mfma_f32_16x16x32_bf16((a), (b), (c), 0, 0, 0)
; __device__ void ret_out_phase(LAS unsigned char* lds, const bf16_t* PROJ, const bf16_t* ST, bf16_t* MIX, const float* lgf, const float* lgb, const float* ogain) {
;     ...
;             for (int i = 0; i < 8; ++i) *(LAS u32x4*)(buf + ((tid >> 5) + 16 * i) * RP + (tid & 31) * 16) = stg[i];
;     ...
;                 for (int ccl = 0; ccl < 8; ++ccl)
; #pragma unroll
;                     for (int ks = 0; ks < 8; ++ks) { const bf16x8 bfrag = *(const LAS bf16x8*)(buf + (16 * ccl + fr) * RP + (32 * ks + 8 * g) * 2); o[(s & 1) * 8 + ccl] = MFMA16(qf[ks], bfrag, o[(s & 1) * 8 + ccl]); }
	v_mfma_f32_16x16x32_bf16 v[74:77], v[38:41], v[130:133], v[74:77]
	ds_read_b128 v[130:133], v192 offset:26240
	s_waitcnt lgkmcnt(3)
	v_mfma_f32_16x16x32_bf16 v[74:77], v[34:37], v[134:137], v[74:77]
	ds_read_b128 v[134:137], v192 offset:26304
	s_waitcnt lgkmcnt(3)
	v_mfma_f32_16x16x32_bf16 v[78:81], v[62:65], v[138:141], v[78:81]
	ds_read_b128 v[138:141], v192 offset:26368
	s_waitcnt lgkmcnt(3)
	v_mfma_f32_16x16x32_bf16 v[78:81], v[58:61], v[142:145], v[78:81]
	ds_read_b128 v[142:145], v192 offset:26432
	s_waitcnt lgkmcnt(3)
	v_mfma_f32_16x16x32_bf16 v[78:81], v[54:57], v[130:133], v[78:81]
	ds_read_b128 v[130:133], v192 offset:26496
	s_waitcnt lgkmcnt(3)
	v_mfma_f32_16x16x32_bf16 v[78:81], v[50:53], v[134:137], v[78:81]
	ds_read_b128 v[134:137], v192 offset:26560
	s_waitcnt lgkmcnt(3)
	v_mfma_f32_16x16x32_bf16 v[78:81], v[46:49], v[138:141], v[78:81]
	ds_read_b128 v[138:141], v192 offset:34816
	s_waitcnt lgkmcnt(3)
	v_mfma_f32_16x16x32_bf16 v[78:81], v[42:45], v[142:145], v[78:81]
	ds_read_b128 v[142:145], v192 offset:34880
	s_waitcnt lgkmcnt(3)
	v_mfma_f32_16x16x32_bf16 v[78:81], v[38:41], v[130:133], v[78:81]
	ds_read_b128 v[130:133], v192 offset:34944
	s_waitcnt lgkmcnt(3)
	v_mfma_f32_16x16x32_bf16 v[78:81], v[34:37], v[134:137], v[78:81]
	ds_read_b128 v[134:137], v192 offset:35008
	s_waitcnt lgkmcnt(3)
	v_mfma_f32_16x16x32_bf16 v[82:85], v[62:65], v[138:141], v[82:85]
	ds_read_b128 v[138:141], v192 offset:35072
	s_waitcnt lgkmcnt(3)
	v_mfma_f32_16x16x32_bf16 v[82:85], v[58:61], v[142:145], v[82:85]
	ds_read_b128 v[142:145], v192 offset:35136
	s_waitcnt lgkmcnt(3)
	v_mfma_f32_16x16x32_bf16 v[82:85], v[54:57], v[130:133], v[82:85]
	ds_read_b128 v[130:133], v192 offset:35200
	s_waitcnt lgkmcnt(3)
	v_mfma_f32_16x16x32_bf16 v[82:85], v[50:53], v[134:137], v[82:85]
	ds_read_b128 v[134:137], v192 offset:35264
	s_waitcnt lgkmcnt(3)
	v_mfma_f32_16x16x32_bf16 v[82:85], v[46:49], v[138:141], v[82:85]
	ds_read_b128 v[138:141], v192 offset:43520
	s_waitcnt lgkmcnt(3)
	v_mfma_f32_16x16x32_bf16 v[82:85], v[42:45], v[142:145], v[82:85]
	ds_read_b128 v[142:145], v192 offset:43584
	s_waitcnt lgkmcnt(3)
	v_mfma_f32_16x16x32_bf16 v[82:85], v[38:41], v[130:133], v[82:85]
	ds_read_b128 v[130:133], v192 offset:43648
	s_waitcnt lgkmcnt(3)
	v_mfma_f32_16x16x32_bf16 v[82:85], v[34:37], v[134:137], v[82:85]
	ds_read_b128 v[134:137], v192 offset:43712
	s_waitcnt lgkmcnt(3)
	v_mfma_f32_16x16x32_bf16 v[86:89], v[62:65], v[138:141], v[86:89]
	ds_read_b128 v[138:141], v192 offset:43776
	s_waitcnt lgkmcnt(3)
	v_mfma_f32_16x16x32_bf16 v[86:89], v[58:61], v[142:145], v[86:89]
	ds_read_b128 v[142:145], v192 offset:43840
	s_waitcnt lgkmcnt(3)
	v_mfma_f32_16x16x32_bf16 v[86:89], v[54:57], v[130:133], v[86:89]
	ds_read_b128 v[130:133], v192 offset:43904
	s_waitcnt lgkmcnt(3)
	v_mfma_f32_16x16x32_bf16 v[86:89], v[50:53], v[134:137], v[86:89]
	ds_read_b128 v[134:137], v192 offset:43968
	s_waitcnt lgkmcnt(3)
	v_mfma_f32_16x16x32_bf16 v[86:89], v[46:49], v[138:141], v[86:89]
	s_waitcnt lgkmcnt(2)
	v_mfma_f32_16x16x32_bf16 v[86:89], v[42:45], v[142:145], v[86:89]
	s_waitcnt lgkmcnt(1)
	v_mfma_f32_16x16x32_bf16 v[86:89], v[38:41], v[130:133], v[86:89]
	s_waitcnt lgkmcnt(0)
	v_mfma_f32_16x16x32_bf16 v[86:89], v[34:37], v[134:137], v[86:89]
	ds_read_b128 v[130:133], v192 offset:52224
	v_mfma_f32_16x16x32_bf16 v[30:33], v[34:37], v[122:125], v[30:33]
	v_add_co_u32_e32 v122, vcc, s23, v126
	s_nop 1
	v_addc_co_u32_e32 v123, vcc, 0, v127, vcc
	v_add_co_u32_e32 v126, vcc, s24, v126
	global_load_dwordx4 v[122:125], v[122:123], off
	s_nop 0
	v_addc_co_u32_e32 v127, vcc, 0, v127, vcc
	s_waitcnt lgkmcnt(0)
	v_mfma_f32_16x16x32_bf16 v[90:93], v[62:65], v[130:133], v[90:93]
	ds_read_b128 v[130:133], v192 offset:52288
	global_load_dwordx4 v[126:129], v[126:127], off
	s_waitcnt lgkmcnt(0)
	v_mfma_f32_16x16x32_bf16 v[90:93], v[58:61], v[130:133], v[90:93]
	ds_read_b128 v[130:133], v192 offset:52352
	ds_read_b128 v[134:137], v192 offset:52416
	ds_read_b128 v[138:141], v192 offset:52480
	ds_read_b128 v[142:145], v192 offset:52544
	s_waitcnt lgkmcnt(3)
	v_mfma_f32_16x16x32_bf16 v[90:93], v[54:57], v[130:133], v[90:93]
	ds_read_b128 v[130:133], v192 offset:52608
	s_waitcnt lgkmcnt(3)
	v_mfma_f32_16x16x32_bf16 v[90:93], v[50:53], v[134:137], v[90:93]
	ds_read_b128 v[134:137], v192 offset:52672
	s_waitcnt lgkmcnt(3)
	v_mfma_f32_16x16x32_bf16 v[90:93], v[46:49], v[138:141], v[90:93]
	ds_read_b128 v[138:141], v192 offset:60928
	s_waitcnt lgkmcnt(3)
	v_mfma_f32_16x16x32_bf16 v[90:93], v[42:45], v[142:145], v[90:93]
	ds_read_b128 v[142:145], v192 offset:60992
	s_waitcnt lgkmcnt(3)
	v_mfma_f32_16x16x32_bf16 v[90:93], v[38:41], v[130:133], v[90:93]
	ds_read_b128 v[130:133], v192 offset:61056
	s_waitcnt lgkmcnt(3)
	v_mfma_f32_16x16x32_bf16 v[90:93], v[34:37], v[134:137], v[90:93]
	ds_read_b128 v[134:137], v192 offset:61120
	s_waitcnt lgkmcnt(3)
	v_mfma_f32_16x16x32_bf16 v[94:97], v[62:65], v[138:141], v[94:97]
	ds_read_b128 v[138:141], v192 offset:61184
	s_waitcnt lgkmcnt(3)
	v_mfma_f32_16x16x32_bf16 v[94:97], v[58:61], v[142:145], v[94:97]
	ds_read_b128 v[142:145], v192 offset:61248
	s_waitcnt lgkmcnt(3)
	v_mfma_f32_16x16x32_bf16 v[94:97], v[54:57], v[130:133], v[94:97]
	ds_read_b128 v[130:133], v192 offset:61312
	s_waitcnt lgkmcnt(3)
	v_mfma_f32_16x16x32_bf16 v[94:97], v[50:53], v[134:137], v[94:97]
	s_waitcnt lgkmcnt(2)
	v_mfma_f32_16x16x32_bf16 v[94:97], v[46:49], v[138:141], v[94:97]
	s_waitcnt lgkmcnt(1)
	v_mfma_f32_16x16x32_bf16 v[94:97], v[42:45], v[142:145], v[94:97]
	s_waitcnt lgkmcnt(0)
	v_mfma_f32_16x16x32_bf16 v[94:97], v[38:41], v[130:133], v[94:97]
	ds_read_b128 v[130:133], v192 offset:61376
	s_waitcnt vmcnt(7)
	ds_write_b128 v210, v[98:101]
	s_waitcnt vmcnt(6)
	ds_write_b128 v210, v[102:105] offset:8704
	s_waitcnt vmcnt(5)
	ds_write_b128 v210, v[106:109] offset:17408
	s_waitcnt vmcnt(4)
	ds_write_b128 v210, v[110:113] offset:26112
	s_waitcnt vmcnt(3)
	ds_write_b128 v210, v[114:117] offset:34816
	s_waitcnt vmcnt(2)
	ds_write_b128 v210, v[118:121] offset:43520
	s_waitcnt vmcnt(1)
	ds_write_b128 v210, v[122:125] offset:52224
	s_waitcnt vmcnt(0)
	ds_write_b128 v210, v[126:129] offset:60928
	v_mov_b32_e32 v98, v226
	s_waitcnt lgkmcnt(8)
	v_mfma_f32_16x16x32_bf16 v[94:97], v[34:37], v[130:133], v[94:97]
	s_waitcnt lgkmcnt(0)
	s_barrier
; #define LAS __attribute__((address_space(3)))
; #define MFMA16(a, b, c) __builtin_amdgcn_mfma_f32_16x16x32_bf16((a), (b), (c), 0, 0, 0)
; #define RET_ISSUE(s_, it_) do { const bf16_t* bp_; int pt_; RET_SRC(s_, it_, bp_, pt_); const int tv_ = otid(); const char* sb_ = (const char*)bp_ + (size_t)(((tv_ >> 5) * pt_ + (tv_ & 31) * 8) * 2); const size_t step_ = (size_t)pt_ * 32; \
;         _Pragma("unroll") for (int i_ = 0; i_ < 8; ++i_) stg[i_] = *(const u32x4*)(sb_ + i_ * step_); } while (0)
; __device__ void ret_out_phase(LAS unsigned char* lds, const bf16_t* PROJ, const bf16_t* ST, bf16_t* MIX, const float* lgf, const float* lgb, const float* ogain) {
;     ...
;             if (s < 7) { RET_ISSUE(s + 1, ri); }
;     ...
;             } else if (!(s & 1)) {
;                 const int kt2 = (s - 4) >> 1;
; #pragma unroll
;                 for (int kt = 0; kt < 8; ++kt) { st[kt] = (f32x4){0.f, 0.f, 0.f, 0.f};
; #pragma unroll
;                     for (int ks = 0; ks < 8; ++ks) { const bf16x8 af = *(const LAS bf16x8*)(buf + (16 * kt + fr) * RP + (32 * ks + 8 * g) * 2); st[kt] = MFMA16(af, qf[ks], st[kt]); } }
	ds_read_b128 v[130:133], v191
	ds_read_b128 v[134:137], v191 offset:64
	s_waitcnt lgkmcnt(1)
	v_mfma_f32_16x16x32_bf16 v[130:133], v[130:133], v[62:65], 0
	ds_read_b128 v[138:141], v191 offset:26176
	ds_read_b128 v[142:145], v191 offset:43584
	ds_read_b128 v[212:215], v191 offset:60992
	s_waitcnt lgkmcnt(3)
	v_mfma_f32_16x16x32_bf16 v[130:133], v[134:137], v[58:61], v[130:133]
	ds_read_b128 v[134:137], v191 offset:128
	v_lshlrev_b32_e32 v98, 4, v98
	v_ashrrev_i32_e32 v99, 31, v98
	s_waitcnt lgkmcnt(0)
	v_mfma_f32_16x16x32_bf16 v[130:133], v[134:137], v[54:57], v[130:133]
	ds_read_b128 v[134:137], v191 offset:192
	v_lshl_add_u64 v[126:127], s[4:5], 0, v[98:99]
	v_add_co_u32_e32 v98, vcc, s33, v126
	s_waitcnt lgkmcnt(0)
	v_mfma_f32_16x16x32_bf16 v[130:133], v[134:137], v[50:53], v[130:133]
	ds_read_b128 v[134:137], v191 offset:256
	v_addc_co_u32_e32 v99, vcc, 0, v127, vcc
	s_waitcnt lgkmcnt(0)
	v_mfma_f32_16x16x32_bf16 v[130:133], v[134:137], v[46:49], v[130:133]
	ds_read_b128 v[134:137], v191 offset:320
	v_add_co_u32_e32 v102, vcc, s17, v126
	s_waitcnt lgkmcnt(0)
	v_mfma_f32_16x16x32_bf16 v[130:133], v[134:137], v[42:45], v[130:133]
	ds_read_b128 v[134:137], v191 offset:384
	v_addc_co_u32_e32 v103, vcc, 0, v127, vcc
	s_waitcnt lgkmcnt(0)
	v_mfma_f32_16x16x32_bf16 v[130:133], v[134:137], v[38:41], v[130:133]
	ds_read_b128 v[134:137], v191 offset:448
	v_add_co_u32_e32 v106, vcc, s18, v126
	s_waitcnt lgkmcnt(0)
	v_mfma_f32_16x16x32_bf16 v[154:157], v[134:137], v[34:37], v[130:133]
	s_nop 3
	ds_read_b128 v[130:133], v191 offset:8704
	ds_read_b128 v[134:137], v191 offset:8768
	v_addc_co_u32_e32 v107, vcc, 0, v127, vcc
	s_waitcnt lgkmcnt(1)
	v_mfma_f32_16x16x32_bf16 v[130:133], v[130:133], v[62:65], 0
	v_add_co_u32_e32 v110, vcc, s20, v126
	global_load_dwordx4 v[98:101], v[98:99], off
	s_waitcnt lgkmcnt(0)
	v_mfma_f32_16x16x32_bf16 v[130:133], v[134:137], v[58:61], v[130:133]
	ds_read_b128 v[134:137], v191 offset:8832
	v_addc_co_u32_e32 v111, vcc, 0, v127, vcc
	s_waitcnt lgkmcnt(0)
	v_mfma_f32_16x16x32_bf16 v[130:133], v[134:137], v[54:57], v[130:133]
	ds_read_b128 v[134:137], v191 offset:8896
	v_add_co_u32_e32 v114, vcc, s21, v126
	s_waitcnt lgkmcnt(0)
	v_mfma_f32_16x16x32_bf16 v[130:133], v[134:137], v[50:53], v[130:133]
	ds_read_b128 v[134:137], v191 offset:8960
	v_addc_co_u32_e32 v115, vcc, 0, v127, vcc
	s_waitcnt lgkmcnt(0)
	v_mfma_f32_16x16x32_bf16 v[130:133], v[134:137], v[46:49], v[130:133]
	ds_read_b128 v[134:137], v191 offset:9024
	v_add_co_u32_e32 v118, vcc, s22, v126
	s_waitcnt lgkmcnt(0)
	v_mfma_f32_16x16x32_bf16 v[130:133], v[134:137], v[42:45], v[130:133]
	ds_read_b128 v[134:137], v191 offset:9088
	v_addc_co_u32_e32 v119, vcc, 0, v127, vcc
	s_waitcnt lgkmcnt(0)
	v_mfma_f32_16x16x32_bf16 v[130:133], v[134:137], v[38:41], v[130:133]
	ds_read_b128 v[134:137], v191 offset:9152
	v_add_co_u32_e32 v122, vcc, s23, v126
	s_waitcnt lgkmcnt(0)
	v_mfma_f32_16x16x32_bf16 v[158:161], v[134:137], v[34:37], v[130:133]
	s_nop 3
	ds_read_b128 v[130:133], v191 offset:17408
	ds_read_b128 v[134:137], v191 offset:17472
	v_addc_co_u32_e32 v123, vcc, 0, v127, vcc
	s_waitcnt lgkmcnt(1)
	v_mfma_f32_16x16x32_bf16 v[130:133], v[130:133], v[62:65], 0
	v_add_co_u32_e32 v126, vcc, s24, v126
	global_load_dwordx4 v[102:105], v[102:103], off
	s_waitcnt lgkmcnt(0)
	v_mfma_f32_16x16x32_bf16 v[130:133], v[134:137], v[58:61], v[130:133]
	ds_read_b128 v[134:137], v191 offset:17536
	v_addc_co_u32_e32 v127, vcc, 0, v127, vcc
	s_waitcnt lgkmcnt(0)
	v_mfma_f32_16x16x32_bf16 v[130:133], v[134:137], v[54:57], v[130:133]
	ds_read_b128 v[134:137], v191 offset:17600
	global_load_dwordx4 v[106:109], v[106:107], off
	v_cmp_gt_i32_e32 vcc, 1, v173
	s_waitcnt lgkmcnt(0)
	v_mfma_f32_16x16x32_bf16 v[130:133], v[134:137], v[50:53], v[130:133]
	ds_read_b128 v[134:137], v191 offset:17664
	global_load_dwordx4 v[110:113], v[110:111], off
	s_waitcnt lgkmcnt(0)
	v_mfma_f32_16x16x32_bf16 v[130:133], v[134:137], v[46:49], v[130:133]
	ds_read_b128 v[134:137], v191 offset:17728
	global_load_dwordx4 v[114:117], v[114:115], off
	s_nop 0
	global_load_dwordx4 v[118:121], v[118:119], off
	s_waitcnt lgkmcnt(0)
	v_mfma_f32_16x16x32_bf16 v[130:133], v[134:137], v[42:45], v[130:133]
	ds_read_b128 v[134:137], v191 offset:17792
	global_load_dwordx4 v[122:125], v[122:123], off
	s_nop 0
	global_load_dwordx4 v[126:129], v[126:127], off
	s_waitcnt lgkmcnt(0)
	v_mfma_f32_16x16x32_bf16 v[130:133], v[134:137], v[38:41], v[130:133]
	ds_read_b128 v[134:137], v191 offset:17856
	s_waitcnt lgkmcnt(0)
	v_mfma_f32_16x16x32_bf16 v[130:133], v[134:137], v[34:37], v[130:133]
	ds_read_b128 v[134:137], v191 offset:26112
	s_waitcnt lgkmcnt(0)
	v_mfma_f32_16x16x32_bf16 v[134:137], v[134:137], v[62:65], 0
	v_mfma_f32_16x16x32_bf16 v[134:137], v[138:141], v[58:61], v[134:137]
	ds_read_b128 v[138:141], v191 offset:26240
	ds_read_b128 v[146:149], v191 offset:26304
	s_waitcnt lgkmcnt(1)
	v_mfma_f32_16x16x32_bf16 v[134:137], v[138:141], v[54:57], v[134:137]
	ds_read_b128 v[138:141], v191 offset:26368
	s_waitcnt lgkmcnt(1)
; #define LAS __attribute__((address_space(3)))
; #define MFMA16(a, b, c) __builtin_amdgcn_mfma_f32_16x16x32_bf16((a), (b), (c), 0, 0, 0)
; __device__ void ret_out_phase(LAS unsigned char* lds, const bf16_t* PROJ, const bf16_t* ST, bf16_t* MIX, const float* lgf, const float* lgb, const float* ogain) {
;     ...
;                 for (int kt = 0; kt < 8; ++kt) { st[kt] = (f32x4){0.f, 0.f, 0.f, 0.f};
; #pragma unroll
;                     for (int ks = 0; ks < 8; ++ks) { const bf16x8 af = *(const LAS bf16x8*)(buf + (16 * kt + fr) * RP + (32 * ks + 8 * g) * 2); st[kt] = MFMA16(af, qf[ks], st[kt]); } }
;                 const int ql = half * 128 + 16 * wave + fr;
; #pragma unroll
;                 for (int kt = 0; kt < 8; ++kt)
; #pragma unroll
;                     for (int j = 0; j < 4; ++j) { const int kl = kt2 * 128 + 16 * kt + 4 * g + j; const int d = ql - kl;
;                         const float w = d > 0 ? __expf(lf * (float)d) : (d < 0 ? __expf(lb * (float)(-d)) : 2.0f); st[kt][j] *= w; }
	v_mfma_f32_16x16x32_bf16 v[134:137], v[146:149], v[50:53], v[134:137]
	ds_read_b128 v[146:149], v191 offset:26432
	s_waitcnt lgkmcnt(1)
	v_mfma_f32_16x16x32_bf16 v[134:137], v[138:141], v[46:49], v[134:137]
	ds_read_b128 v[138:141], v191 offset:26496
	s_waitcnt lgkmcnt(1)
	v_mfma_f32_16x16x32_bf16 v[134:137], v[146:149], v[42:45], v[134:137]
	ds_read_b128 v[146:149], v191 offset:26560
	s_waitcnt lgkmcnt(1)
	v_mfma_f32_16x16x32_bf16 v[134:137], v[138:141], v[38:41], v[134:137]
	s_waitcnt lgkmcnt(0)
	v_mfma_f32_16x16x32_bf16 v[150:153], v[146:149], v[34:37], v[134:137]
	s_nop 4
	ds_read_b128 v[134:137], v191 offset:34816
	ds_read_b128 v[138:141], v191 offset:34880
	s_waitcnt lgkmcnt(1)
	v_mfma_f32_16x16x32_bf16 v[134:137], v[134:137], v[62:65], 0
	s_waitcnt lgkmcnt(0)
	v_mfma_f32_16x16x32_bf16 v[134:137], v[138:141], v[58:61], v[134:137]
	ds_read_b128 v[138:141], v191 offset:34944
	ds_read_b128 v[146:149], v191 offset:35008
	s_waitcnt lgkmcnt(1)
	v_mfma_f32_16x16x32_bf16 v[134:137], v[138:141], v[54:57], v[134:137]
	ds_read_b128 v[138:141], v191 offset:35072
	s_waitcnt lgkmcnt(1)
	v_mfma_f32_16x16x32_bf16 v[134:137], v[146:149], v[50:53], v[134:137]
	ds_read_b128 v[146:149], v191 offset:35136
	s_waitcnt lgkmcnt(1)
	v_mfma_f32_16x16x32_bf16 v[134:137], v[138:141], v[46:49], v[134:137]
	ds_read_b128 v[138:141], v191 offset:35200
	s_waitcnt lgkmcnt(1)
	v_mfma_f32_16x16x32_bf16 v[134:137], v[146:149], v[42:45], v[134:137]
	ds_read_b128 v[146:149], v191 offset:35264
	s_waitcnt lgkmcnt(1)
	v_mfma_f32_16x16x32_bf16 v[134:137], v[138:141], v[38:41], v[134:137]
	s_waitcnt lgkmcnt(0)
	v_mfma_f32_16x16x32_bf16 v[134:137], v[146:149], v[34:37], v[134:137]
	ds_read_b128 v[138:141], v191 offset:43520
	s_waitcnt lgkmcnt(0)
	v_mfma_f32_16x16x32_bf16 v[138:141], v[138:141], v[62:65], 0
	v_mfma_f32_16x16x32_bf16 v[138:141], v[142:145], v[58:61], v[138:141]
	ds_read_b128 v[142:145], v191 offset:43648
	s_waitcnt lgkmcnt(0)
	v_mfma_f32_16x16x32_bf16 v[138:141], v[142:145], v[54:57], v[138:141]
	ds_read_b128 v[142:145], v191 offset:43712
	s_waitcnt lgkmcnt(0)
	v_mfma_f32_16x16x32_bf16 v[138:141], v[142:145], v[50:53], v[138:141]
	ds_read_b128 v[142:145], v191 offset:43776
	s_waitcnt lgkmcnt(0)
	v_mfma_f32_16x16x32_bf16 v[138:141], v[142:145], v[46:49], v[138:141]
	ds_read_b128 v[142:145], v191 offset:43840
	s_waitcnt lgkmcnt(0)
	v_mfma_f32_16x16x32_bf16 v[138:141], v[142:145], v[42:45], v[138:141]
	ds_read_b128 v[142:145], v191 offset:43904
	s_waitcnt lgkmcnt(0)
	v_mfma_f32_16x16x32_bf16 v[138:141], v[142:145], v[38:41], v[138:141]
	ds_read_b128 v[142:145], v191 offset:43968
	s_waitcnt lgkmcnt(0)
	v_mfma_f32_16x16x32_bf16 v[146:149], v[142:145], v[34:37], v[138:141]
	s_nop 4
	ds_read_b128 v[138:141], v191 offset:52224
	ds_read_b128 v[142:145], v191 offset:52288
	s_waitcnt lgkmcnt(1)
	v_mfma_f32_16x16x32_bf16 v[138:141], v[138:141], v[62:65], 0
	s_waitcnt lgkmcnt(0)
	v_mfma_f32_16x16x32_bf16 v[138:141], v[142:145], v[58:61], v[138:141]
	ds_read_b128 v[142:145], v191 offset:52352
	s_waitcnt lgkmcnt(0)
	v_mfma_f32_16x16x32_bf16 v[138:141], v[142:145], v[54:57], v[138:141]
	ds_read_b128 v[142:145], v191 offset:52416
	s_waitcnt lgkmcnt(0)
	v_mfma_f32_16x16x32_bf16 v[138:141], v[142:145], v[50:53], v[138:141]
	ds_read_b128 v[142:145], v191 offset:52480
	s_waitcnt lgkmcnt(0)
	v_mfma_f32_16x16x32_bf16 v[138:141], v[142:145], v[46:49], v[138:141]
	ds_read_b128 v[142:145], v191 offset:52544
	s_waitcnt lgkmcnt(0)
	v_mfma_f32_16x16x32_bf16 v[138:141], v[142:145], v[42:45], v[138:141]
	ds_read_b128 v[142:145], v191 offset:52608
	s_waitcnt lgkmcnt(0)
	v_mfma_f32_16x16x32_bf16 v[138:141], v[142:145], v[38:41], v[138:141]
	ds_read_b128 v[142:145], v191 offset:52672
	s_waitcnt lgkmcnt(0)
	v_mfma_f32_16x16x32_bf16 v[138:141], v[142:145], v[34:37], v[138:141]
	ds_read_b128 v[142:145], v191 offset:60928
	s_waitcnt lgkmcnt(0)
	v_mfma_f32_16x16x32_bf16 v[142:145], v[142:145], v[62:65], 0
	v_mfma_f32_16x16x32_bf16 v[142:145], v[212:215], v[58:61], v[142:145]
	ds_read_b128 v[212:215], v191 offset:61056
	s_waitcnt lgkmcnt(0)
	v_mfma_f32_16x16x32_bf16 v[142:145], v[212:215], v[54:57], v[142:145]
	ds_read_b128 v[212:215], v191 offset:61120
	s_waitcnt lgkmcnt(0)
	v_mfma_f32_16x16x32_bf16 v[142:145], v[212:215], v[50:53], v[142:145]
	ds_read_b128 v[212:215], v191 offset:61184
	s_waitcnt lgkmcnt(0)
	v_mfma_f32_16x16x32_bf16 v[142:145], v[212:215], v[46:49], v[142:145]
	ds_read_b128 v[212:215], v191 offset:61248
	s_waitcnt lgkmcnt(0)
	v_mfma_f32_16x16x32_bf16 v[142:145], v[212:215], v[42:45], v[142:145]
	ds_read_b128 v[212:215], v191 offset:61312
	s_waitcnt lgkmcnt(0)
	v_mfma_f32_16x16x32_bf16 v[142:145], v[212:215], v[38:41], v[142:145]
	ds_read_b128 v[212:215], v191 offset:61376
	s_waitcnt lgkmcnt(0)
	v_mfma_f32_16x16x32_bf16 v[142:145], v[212:215], v[34:37], v[142:145]
	s_and_saveexec_b64 s[4:5], vcc
	s_xor_b64 s[4:5], exec, s[4:5]
	s_cbranch_execz .LBB0_37
	v_sub_u32_e32 v173, 0, v173
	v_cvt_f32_u32_e32 v173, v173
	v_cmp_ne_u32_e32 vcc, v0, v190
	v_mul_f32_e32 v173, v185, v173
	v_mul_f32_e32 v173, 0x3fb8aa3b, v173
	v_exp_f32_e32 v173, v173
	s_nop 0
	v_cndmask_b32_e32 v177, 2.0, v173, vcc

; #define LAS __attribute__((address_space(3)))
; #define MFMA16(a, b, c) __builtin_amdgcn_mfma_f32_16x16x32_bf16((a), (b), (c), 0, 0, 0)
; __device__ void ret_out_phase(LAS unsigned char* lds, const bf16_t* PROJ, const bf16_t* ST, bf16_t* MIX, const float* lgf, const float* lgb, const float* ogain) {
;     ...
;                 if (s & 1) {
; #pragma unroll
;                     for (int j = 0; j < 4; ++j) { const int il = half * 128 + 16 * wave + 4 * g + j;
;                         const float sc = s == 1 ? __expf(lf * (float)(il + 1) - lb * (float)(256 - il)) : __expf(lb * (float)(256 - il));
; #pragma unroll
;                         for (int cc = 0; cc < 16; ++cc) o[cc][j] *= sc; }
;                 }
;     ...
;                 for (int kt = 0; kt < 8; ++kt)
; #pragma unroll
;                     for (int j = 0; j < 4; ++j) { const int kl = kt2 * 128 + 16 * kt + 4 * g + j; const int d = ql - kl;
;                         const float w = d > 0 ? __expf(lf * (float)d) : (d < 0 ? __expf(lb * (float)(-d)) : 2.0f); st[kt][j] *= w; }
;             } else {
; #pragma unroll
;                 for (int kk = 0; kk < 4; ++kk) { const bf16x8 pa = pack8(st[2 * kk], st[2 * kk + 1]);
;                     LAS unsigned char* vb = buf + (32 * kk + 4 * g + q4) * RP + 8 * p4;
; #pragma unroll
;                     for (int cc = 0; cc < 16; ++cc) { const bf16x8 bfrag = tr_pair(vb + 32 * cc, vb + 16 * RP + 32 * cc); o[cc] = MFMA16(pa, bfrag, o[cc]); } }
.LBB0_163:
	s_or_b64 exec, exec, s[4:5]
	v_sub_u32_e32 v167, 0xff, v167
	v_cvt_f32_i32_e32 v167, v167
	v_mul_f32_e32 v169, 0x3fb8aa3b, v169
	v_exp_f32_e32 v188, v169
	v_mul_f32_e32 v171, 0x3fb8aa3b, v171
	v_mul_f32_e32 v167, v185, v167
	v_mul_f32_e32 v167, 0x3fb8aa3b, v167
	v_exp_f32_e32 v189, v167
	v_mul_f32_e32 v167, 0x3fb8aa3b, v187
	v_exp_f32_e32 v186, v171
	v_exp_f32_e32 v187, v167
	v_mul_f32_e32 v167, v152, v243
	v_mul_f32_e32 v169, v153, v244
	v_mul_f32_e32 v160, v160, v232
	v_mul_f32_e32 v161, v161, v235
	v_mul_f32_e32 v158, v158, v217
	v_mul_f32_e32 v159, v159, v220
	v_mul_f32_e32 v156, v156, v213
	v_mul_f32_e32 v157, v157, v215
	v_mul_f32_e32 v171, v154, v177
	v_mul_f32_e32 v177, v155, v179
	v_pk_mul_f32 v[152:153], v[188:189], v[14:15]
	v_mov_b32_e32 v14, v226
	s_waitcnt vmcnt(7)
	ds_write_b128 v211, v[98:101]
	s_waitcnt vmcnt(6)
	ds_write_b128 v211, v[102:105] offset:8704
	s_waitcnt vmcnt(5)
	ds_write_b128 v211, v[106:109] offset:17408
	s_waitcnt vmcnt(4)
	ds_write_b128 v211, v[110:113] offset:26112
	s_waitcnt vmcnt(3)
	ds_write_b128 v211, v[114:117] offset:34816
	s_waitcnt vmcnt(2)
	ds_write_b128 v211, v[118:121] offset:43520
	s_waitcnt vmcnt(1)
	ds_write_b128 v211, v[122:125] offset:52224
	s_waitcnt vmcnt(0)
	ds_write_b128 v211, v[126:129] offset:60928
	s_waitcnt lgkmcnt(0)
	s_barrier
	v_cvt_pk_bf16_f32 v98, v171, v177
	v_cvt_pk_bf16_f32 v99, v156, v157
	v_cvt_pk_bf16_f32 v100, v158, v159
	v_cvt_pk_bf16_f32 v101, v160, v161
	ds_read_b64_tr_b16 v[104:105], v225 offset:8704
	ds_read_b64_tr_b16 v[102:103], v225
	ds_read_b64_tr_b16 v[106:107], v225 offset:32
	ds_read_b64_tr_b16 v[110:111], v225 offset:64
	ds_read_b64_tr_b16 v[114:115], v225 offset:96
	ds_read_b64_tr_b16 v[108:109], v225 offset:8736
	ds_read_b64_tr_b16 v[112:113], v225 offset:8768
	ds_read_b64_tr_b16 v[116:117], v225 offset:8800
	v_pk_mul_f32 v[4:5], v[186:187], v[4:5]
	v_pk_mul_f32 v[2:3], v[188:189], v[2:3]
	v_pk_mul_f32 v[8:9], v[186:187], v[8:9]
	v_pk_mul_f32 v[6:7], v[188:189], v[6:7]
	v_pk_mul_f32 v[12:13], v[186:187], v[12:13]
	v_pk_mul_f32 v[10:11], v[188:189], v[10:11]
	s_waitcnt lgkmcnt(2)
	v_mfma_f32_16x16x32_bf16 v[2:5], v[98:101], v[106:109], v[2:5]
	v_mul_f32_e64 v20, v186, v20
	v_mul_f32_e64 v21, v187, v21
	v_pk_mul_f32 v[18:19], v[188:189], v[18:19]
	v_pk_mul_f32 v[24:25], v[186:187], v[24:25]
	s_waitcnt lgkmcnt(1)
	v_mfma_f32_16x16x32_bf16 v[6:9], v[98:101], v[110:113], v[6:9]
	v_mul_f32_e64 v22, v188, v22
	v_mul_f32_e64 v23, v189, v23
	v_pk_mul_f32 v[28:29], v[186:187], v[28:29]
	v_pk_mul_f32 v[26:27], v[188:189], v[26:27]
	s_waitcnt lgkmcnt(0)
	v_mfma_f32_16x16x32_bf16 v[10:13], v[98:101], v[114:117], v[10:13]
	ds_read_b64_tr_b16 v[108:109], v225 offset:8832
	ds_read_b64_tr_b16 v[106:107], v225 offset:128
	ds_read_b64_tr_b16 v[110:111], v225 offset:160
	ds_read_b64_tr_b16 v[114:115], v225 offset:192
	ds_read_b64_tr_b16 v[118:119], v225 offset:224
	ds_read_b64_tr_b16 v[112:113], v225 offset:8864
	ds_read_b64_tr_b16 v[116:117], v225 offset:8896
	ds_read_b64_tr_b16 v[120:121], v225 offset:8928
	v_pk_mul_f32 v[32:33], v[186:187], v[32:33]
	v_pk_mul_f32 v[30:31], v[188:189], v[30:31]
	v_pk_mul_f32 v[154:155], v[186:187], v[16:17]
	s_waitcnt lgkmcnt(6)
	v_mfma_f32_16x16x32_bf16 v[16:19], v[98:101], v[106:109], v[18:21]
	v_mul_f32_e64 v68, v186, v68
	v_mul_f32_e64 v69, v187, v69
	v_pk_mul_f32 v[66:67], v[188:189], v[66:67]
	v_pk_mul_f32 v[72:73], v[186:187], v[72:73]
	s_waitcnt lgkmcnt(2)
	v_mfma_f32_16x16x32_bf16 v[20:23], v[98:101], v[110:113], v[22:25]
	v_mul_f32_e64 v70, v188, v70
	v_mul_f32_e64 v71, v189, v71
	v_pk_mul_f32 v[76:77], v[186:187], v[76:77]
	v_pk_mul_f32 v[74:75], v[188:189], v[74:75]
	s_waitcnt lgkmcnt(1)
	v_mfma_f32_16x16x32_bf16 v[24:27], v[98:101], v[114:117], v[26:29]
	v_mul_f32_e64 v80, v186, v80
	v_mul_f32_e64 v81, v187, v81
	v_pk_mul_f32 v[78:79], v[188:189], v[78:79]
	v_pk_mul_f32 v[84:85], v[186:187], v[84:85]
	s_waitcnt lgkmcnt(0)
	v_mfma_f32_16x16x32_bf16 v[28:31], v[98:101], v[118:121], v[30:33]
	ds_read_b64_tr_b16 v[108:109], v225 offset:8960
	ds_read_b64_tr_b16 v[106:107], v225 offset:256
	ds_read_b64_tr_b16 v[110:111], v225 offset:288
	ds_read_b64_tr_b16 v[114:115], v225 offset:320
	ds_read_b64_tr_b16 v[118:119], v225 offset:352
	ds_read_b64_tr_b16 v[112:113], v225 offset:8992
	ds_read_b64_tr_b16 v[116:117], v225 offset:9024
	ds_read_b64_tr_b16 v[120:121], v225 offset:9056
	v_pk_mul_f32 v[82:83], v[188:189], v[82:83]
	v_mul_f32_e32 v15, v150, v224
	s_waitcnt lgkmcnt(6)
	v_mfma_f32_16x16x32_bf16 v[66:69], v[98:101], v[106:109], v[66:69]
	v_mul_f32_e32 v122, v151, v223
	v_mul_f32_e32 v32, v132, v212
	v_mul_f32_e32 v33, v133, v183
	s_waitcnt lgkmcnt(2)
	v_mfma_f32_16x16x32_bf16 v[70:73], v[98:101], v[110:113], v[70:73]
	v_mul_f32_e64 v88, v186, v88
	v_mul_f32_e64 v89, v187, v89
	v_pk_mul_f32 v[86:87], v[188:189], v[86:87]
	v_pk_mul_f32 v[92:93], v[186:187], v[92:93]
	s_waitcnt lgkmcnt(1)
	v_mfma_f32_16x16x32_bf16 v[74:77], v[98:101], v[114:117], v[74:77]
	v_mul_f32_e64 v90, v188, v90
	v_mul_f32_e64 v91, v189, v91
	v_pk_mul_f32 v[96:97], v[186:187], v[96:97]
	v_pk_mul_f32 v[94:95], v[188:189], v[94:95]
	s_waitcnt lgkmcnt(0)
	v_mfma_f32_16x16x32_bf16 v[78:81], v[98:101], v[118:121], v[78:81]
	ds_read_b64_tr_b16 v[108:109], v225 offset:9088
	ds_read_b64_tr_b16 v[106:107], v225 offset:384
	ds_read_b64_tr_b16 v[110:111], v225 offset:416
	ds_read_b64_tr_b16 v[114:115], v225 offset:448
	ds_read_b64_tr_b16 v[118:119], v225 offset:480
	ds_read_b64_tr_b16 v[112:113], v225 offset:9120
	ds_read_b64_tr_b16 v[116:117], v225 offset:9152
	ds_read_b64_tr_b16 v[120:121], v225 offset:9184
	s_bitset1_b32 s0, 7
	s_add_u32 s4, s0, s15
	s_waitcnt lgkmcnt(6)
; #define LAS __attribute__((address_space(3)))
; #define MFMA16(a, b, c) __builtin_amdgcn_mfma_f32_16x16x32_bf16((a), (b), (c), 0, 0, 0)
; __device__ void ret_out_phase(LAS unsigned char* lds, const bf16_t* PROJ, const bf16_t* ST, bf16_t* MIX, const float* lgf, const float* lgb, const float* ogain) {
;     ...
;             } else {
; #pragma unroll
;                 for (int kk = 0; kk < 4; ++kk) { const bf16x8 pa = pack8(st[2 * kk], st[2 * kk + 1]);
;                     LAS unsigned char* vb = buf + (32 * kk + 4 * g + q4) * RP + 8 * p4;
; #pragma unroll
;                     for (int cc = 0; cc < 16; ++cc) { const bf16x8 bfrag = tr_pair(vb + 32 * cc, vb + 16 * RP + 32 * cc); o[cc] = MFMA16(pa, bfrag, o[cc]); } }
	v_mfma_f32_16x16x32_bf16 v[82:85], v[98:101], v[106:109], v[82:85]
	v_mul_f32_e32 v106, v130, v173
	v_mul_f32_e32 v107, v131, v175
	s_addc_u32 s5, s1, 0
	v_mfma_f32_16x16x32_bf16 v[102:105], v[98:101], v[102:105], v[152:155]
	s_lshl_b64 s[4:5], s[4:5], 9
	s_add_u32 s4, s78, s4
	v_lshlrev_b32_e32 v14, 4, v14
	s_waitcnt lgkmcnt(2)
	v_mfma_f32_16x16x32_bf16 v[86:89], v[98:101], v[110:113], v[86:89]
	s_addc_u32 s5, s79, s5
	s_mov_b32 s15, 0x9006000
	s_mov_b32 s17, 0x9008000
	s_waitcnt lgkmcnt(1)
	v_mfma_f32_16x16x32_bf16 v[90:93], v[98:101], v[114:117], v[90:93]
	s_mov_b32 s18, 0x900a000
	s_mov_b32 s20, 0x900c000
	s_mov_b32 s21, 0x900e000
	s_waitcnt lgkmcnt(0)
	v_mfma_f32_16x16x32_bf16 v[94:97], v[98:101], v[118:121], v[94:97]
	v_cvt_pk_bf16_f32 v98, v106, v107
	v_cvt_pk_bf16_f32 v99, v32, v33
	v_cvt_pk_bf16_f32 v100, v15, v122
	v_cvt_pk_bf16_f32 v101, v167, v169
	ds_read_b64_tr_b16 v[108:109], v225 offset:26112
	ds_read_b64_tr_b16 v[106:107], v225 offset:17408
	ds_read_b64_tr_b16 v[110:111], v225 offset:17440
	ds_read_b64_tr_b16 v[114:115], v225 offset:17472
	ds_read_b64_tr_b16 v[118:119], v225 offset:17504
	ds_read_b64_tr_b16 v[112:113], v225 offset:26144
	ds_read_b64_tr_b16 v[116:117], v225 offset:26176
	ds_read_b64_tr_b16 v[120:121], v225 offset:26208
	s_waitcnt lgkmcnt(6)
	v_mfma_f32_16x16x32_bf16 v[102:105], v[98:101], v[106:109], v[102:105]
	v_mul_f32_e32 v15, v148, v236
	v_mul_f32_e32 v32, v149, v238
	v_mul_f32_e32 v33, v146, v221
	s_waitcnt lgkmcnt(2)
	v_mfma_f32_16x16x32_bf16 v[2:5], v[98:101], v[110:113], v[2:5]
	s_add_u32 s0, s0, s16
	s_addc_u32 s1, s1, 0
	s_lshl_b64 s[0:1], s[0:1], 9
	s_waitcnt lgkmcnt(1)
	v_mfma_f32_16x16x32_bf16 v[6:9], v[98:101], v[114:117], v[6:9]
	s_add_u32 s0, s78, s0
	s_addc_u32 s1, s79, s1
	s_waitcnt lgkmcnt(0)
	v_mfma_f32_16x16x32_bf16 v[10:13], v[98:101], v[118:121], v[10:13]
	ds_read_b64_tr_b16 v[108:109], v225 offset:26240
	ds_read_b64_tr_b16 v[106:107], v225 offset:17536
	ds_read_b64_tr_b16 v[110:111], v225 offset:17568
	ds_read_b64_tr_b16 v[114:115], v225 offset:17600
	ds_read_b64_tr_b16 v[118:119], v225 offset:17632
	ds_read_b64_tr_b16 v[112:113], v225 offset:26272
	ds_read_b64_tr_b16 v[116:117], v225 offset:26304
	ds_read_b64_tr_b16 v[120:121], v225 offset:26336
	s_waitcnt lgkmcnt(6)
	v_mfma_f32_16x16x32_bf16 v[16:19], v[98:101], v[106:109], v[16:19]
	s_waitcnt lgkmcnt(2)
	v_mfma_f32_16x16x32_bf16 v[20:23], v[98:101], v[110:113], v[20:23]
	s_waitcnt lgkmcnt(1)
	v_mfma_f32_16x16x32_bf16 v[24:27], v[98:101], v[114:117], v[24:27]
	s_waitcnt lgkmcnt(0)
	v_mfma_f32_16x16x32_bf16 v[28:31], v[98:101], v[118:121], v[28:31]
	ds_read_b64_tr_b16 v[108:109], v225 offset:26368
	ds_read_b64_tr_b16 v[106:107], v225 offset:17664
	ds_read_b64_tr_b16 v[110:111], v225 offset:17696
	ds_read_b64_tr_b16 v[114:115], v225 offset:17728
	ds_read_b64_tr_b16 v[118:119], v225 offset:17760
	ds_read_b64_tr_b16 v[112:113], v225 offset:26400
	ds_read_b64_tr_b16 v[116:117], v225 offset:26432
	ds_read_b64_tr_b16 v[120:121], v225 offset:26464
	s_waitcnt lgkmcnt(6)
	v_mfma_f32_16x16x32_bf16 v[66:69], v[98:101], v[106:109], v[66:69]
	s_waitcnt lgkmcnt(2)
	v_mfma_f32_16x16x32_bf16 v[70:73], v[98:101], v[110:113], v[70:73]
	s_waitcnt lgkmcnt(1)
	v_mfma_f32_16x16x32_bf16 v[74:77], v[98:101], v[114:117], v[74:77]
	s_waitcnt lgkmcnt(0)
	v_mfma_f32_16x16x32_bf16 v[78:81], v[98:101], v[118:121], v[78:81]
	ds_read_b64_tr_b16 v[108:109], v225 offset:26496
	ds_read_b64_tr_b16 v[106:107], v225 offset:17792
	ds_read_b64_tr_b16 v[110:111], v225 offset:17824
	ds_read_b64_tr_b16 v[114:115], v225 offset:17856
	ds_read_b64_tr_b16 v[118:119], v225 offset:17888
	ds_read_b64_tr_b16 v[112:113], v225 offset:26528
	ds_read_b64_tr_b16 v[116:117], v225 offset:26560
	ds_read_b64_tr_b16 v[120:121], v225 offset:26592
	s_waitcnt lgkmcnt(6)
	v_mfma_f32_16x16x32_bf16 v[82:85], v[98:101], v[106:109], v[82:85]
	v_mul_f32_e32 v106, v147, v233
	v_mul_f32_e32 v107, v136, v216
	v_mul_f32_e32 v108, v137, v218
	s_waitcnt lgkmcnt(2)
	v_mfma_f32_16x16x32_bf16 v[86:89], v[98:101], v[110:113], v[86:89]
	v_mul_f32_e32 v109, v134, v181
	v_mul_f32_e32 v110, v135, v214
	s_waitcnt lgkmcnt(1)
	v_mfma_f32_16x16x32_bf16 v[90:93], v[98:101], v[114:117], v[90:93]
	s_waitcnt lgkmcnt(0)
	v_mfma_f32_16x16x32_bf16 v[94:97], v[98:101], v[118:121], v[94:97]
	v_cvt_pk_bf16_f32 v98, v109, v110
	v_cvt_pk_bf16_f32 v99, v107, v108
	v_cvt_pk_bf16_f32 v100, v33, v106
	v_cvt_pk_bf16_f32 v101, v15, v32
	ds_read_b64_tr_b16 v[108:109], v225 offset:43520
	ds_read_b64_tr_b16 v[106:107], v225 offset:34816
	ds_read_b64_tr_b16 v[110:111], v225 offset:34848
	ds_read_b64_tr_b16 v[114:115], v225 offset:34880
	ds_read_b64_tr_b16 v[118:119], v225 offset:34912
	ds_read_b64_tr_b16 v[112:113], v225 offset:43552
	ds_read_b64_tr_b16 v[116:117], v225 offset:43584
	ds_read_b64_tr_b16 v[120:121], v225 offset:43616
	s_waitcnt lgkmcnt(6)
	v_mfma_f32_16x16x32_bf16 v[102:105], v[98:101], v[106:109], v[102:105]
	v_mul_f32_e32 v15, v144, v242
	v_mul_f32_e32 v32, v142, v239
	v_mul_f32_e32 v33, v143, v240
	s_waitcnt lgkmcnt(2)
	v_mfma_f32_16x16x32_bf16 v[106:109], v[98:101], v[110:113], v[2:5]
	s_waitcnt lgkmcnt(1)
	v_mfma_f32_16x16x32_bf16 v[110:113], v[98:101], v[114:117], v[6:9]
	s_waitcnt lgkmcnt(0)
	v_mfma_f32_16x16x32_bf16 v[118:121], v[98:101], v[118:121], v[10:13]
	ds_read_b64_tr_b16 v[4:5], v225 offset:43648
	ds_read_b64_tr_b16 v[2:3], v225 offset:34944
	ds_read_b64_tr_b16 v[6:7], v225 offset:34976
	ds_read_b64_tr_b16 v[10:11], v225 offset:35008
	ds_read_b64_tr_b16 v[114:115], v225 offset:35040
	ds_read_b64_tr_b16 v[8:9], v225 offset:43680
	ds_read_b64_tr_b16 v[12:13], v225 offset:43712
	ds_read_b64_tr_b16 v[116:117], v225 offset:43744
	s_waitcnt lgkmcnt(6)
; #define LAS __attribute__((address_space(3)))
; #define MFMA16(a, b, c) __builtin_amdgcn_mfma_f32_16x16x32_bf16((a), (b), (c), 0, 0, 0)
; #define RET_ISSUE(s_, it_) do { const bf16_t* bp_; int pt_; RET_SRC(s_, it_, bp_, pt_); const int tv_ = otid(); const char* sb_ = (const char*)bp_ + (size_t)(((tv_ >> 5) * pt_ + (tv_ & 31) * 8) * 2); const size_t step_ = (size_t)pt_ * 32; \
;         _Pragma("unroll") for (int i_ = 0; i_ < 8; ++i_) stg[i_] = *(const u32x4*)(sb_ + i_ * step_); } while (0)
; __device__ void ret_out_phase(LAS unsigned char* lds, const bf16_t* PROJ, const bf16_t* ST, bf16_t* MIX, const float* lgf, const float* lgb, const float* ogain) {
;     ...
;             for (int i = 0; i < 8; ++i) *(LAS u32x4*)(buf + ((tid >> 5) + 16 * i) * RP + (tid & 31) * 16) = stg[i];
;             __syncthreads();
;             if (s < 7) { RET_ISSUE(s + 1, ri); }
;             else if (item + (int)gridDim.x < 768) { const RetItem rn = ret_decode(item + gridDim.x); RET_ISSUE(0, rn); }
;     ...
;             } else {
; #pragma unroll
;                 for (int kk = 0; kk < 4; ++kk) { const bf16x8 pa = pack8(st[2 * kk], st[2 * kk + 1]);
;                     LAS unsigned char* vb = buf + (32 * kk + 4 * g + q4) * RP + 8 * p4;
; #pragma unroll
;                     for (int cc = 0; cc < 16; ++cc) { const bf16x8 bfrag = tr_pair(vb + 32 * cc, vb + 16 * RP + 32 * cc); o[cc] = MFMA16(pa, bfrag, o[cc]); } }
	v_mfma_f32_16x16x32_bf16 v[16:19], v[98:101], v[2:5], v[16:19]
	s_waitcnt lgkmcnt(2)
	v_mfma_f32_16x16x32_bf16 v[20:23], v[98:101], v[6:9], v[20:23]
	s_waitcnt lgkmcnt(1)
	v_mfma_f32_16x16x32_bf16 v[24:27], v[98:101], v[10:13], v[24:27]
	s_waitcnt lgkmcnt(0)
	v_mfma_f32_16x16x32_bf16 v[28:31], v[98:101], v[114:117], v[28:31]
	ds_read_b64_tr_b16 v[4:5], v225 offset:43776
	ds_read_b64_tr_b16 v[2:3], v225 offset:35072
	ds_read_b64_tr_b16 v[6:7], v225 offset:35104
	ds_read_b64_tr_b16 v[10:11], v225 offset:35136
	ds_read_b64_tr_b16 v[114:115], v225 offset:35168
	ds_read_b64_tr_b16 v[8:9], v225 offset:43808
	ds_read_b64_tr_b16 v[12:13], v225 offset:43840
	ds_read_b64_tr_b16 v[116:117], v225 offset:43872
	s_waitcnt lgkmcnt(6)
	v_mfma_f32_16x16x32_bf16 v[66:69], v[98:101], v[2:5], v[66:69]
	s_waitcnt lgkmcnt(2)
	v_mfma_f32_16x16x32_bf16 v[70:73], v[98:101], v[6:9], v[70:73]
	s_waitcnt lgkmcnt(1)
	v_mfma_f32_16x16x32_bf16 v[130:133], v[98:101], v[10:13], v[74:77]
	ds_read_b64_tr_b16 v[4:5], v225 offset:43904
	ds_read_b64_tr_b16 v[2:3], v225 offset:35200
	ds_read_b64_tr_b16 v[6:7], v225 offset:35232
	ds_read_b64_tr_b16 v[10:11], v225 offset:35264
	ds_read_b64_tr_b16 v[74:75], v225 offset:35296
	ds_read_b64_tr_b16 v[8:9], v225 offset:43936
	ds_read_b64_tr_b16 v[12:13], v225 offset:43968
	ds_read_b64_tr_b16 v[76:77], v225 offset:44000
	s_waitcnt lgkmcnt(8)
	v_mfma_f32_16x16x32_bf16 v[134:137], v[98:101], v[114:117], v[78:81]
	s_nop 2
	v_mul_f32_e32 v78, v140, v234
	v_mul_f32_e32 v79, v141, v237
	s_waitcnt lgkmcnt(2)
	v_mfma_f32_16x16x32_bf16 v[140:143], v[98:101], v[6:9], v[86:89]
	v_mul_f32_e32 v6, v138, v219
	v_mul_f32_e32 v7, v139, v222
	v_mul_f32_e32 v9, v145, v241
	v_mfma_f32_16x16x32_bf16 v[146:149], v[98:101], v[2:5], v[82:85]
	v_cvt_pk_bf16_f32 v6, v6, v7
	v_cvt_pk_bf16_f32 v7, v78, v79
	v_cvt_pk_bf16_f32 v8, v32, v33
	s_waitcnt lgkmcnt(0)
	v_mfma_f32_16x16x32_bf16 v[2:5], v[98:101], v[74:77], v[94:97]
	v_cvt_pk_bf16_f32 v9, v15, v9
	ds_read_b64_tr_b16 v[76:77], v225 offset:60928
	ds_read_b64_tr_b16 v[74:75], v225 offset:52224
	ds_read_b64_tr_b16 v[78:79], v225 offset:52256
	ds_read_b64_tr_b16 v[82:83], v225 offset:52288
	ds_read_b64_tr_b16 v[86:87], v225 offset:52320
	ds_read_b64_tr_b16 v[80:81], v225 offset:60960
	ds_read_b64_tr_b16 v[84:85], v225 offset:60992
	ds_read_b64_tr_b16 v[88:89], v225 offset:61024
	v_ashrrev_i32_e32 v15, 31, v14
	v_lshl_add_u64 v[138:139], s[4:5], 0, v[14:15]
	v_add_co_u32_e32 v14, vcc, s33, v138
	s_mov_b32 s4, 0x9002000
	s_nop 0
	v_addc_co_u32_e32 v15, vcc, 0, v139, vcc
	v_mfma_f32_16x16x32_bf16 v[10:13], v[98:101], v[10:13], v[90:93]
	s_mov_b32 s5, 0x9004000
	s_waitcnt lgkmcnt(6)
	v_mfma_f32_16x16x32_bf16 v[122:125], v[6:9], v[74:77], v[102:105]
	s_waitcnt lgkmcnt(2)
	v_mfma_f32_16x16x32_bf16 v[126:129], v[6:9], v[78:81], v[106:109]
	ds_read_b64_tr_b16 v[76:77], v225 offset:61056
	ds_read_b64_tr_b16 v[74:75], v225 offset:52352
	ds_read_b64_tr_b16 v[78:79], v225 offset:52384
	ds_read_b64_tr_b16 v[90:91], v225 offset:52416
	ds_read_b64_tr_b16 v[94:95], v225 offset:52448
	ds_read_b64_tr_b16 v[80:81], v225 offset:61088
	ds_read_b64_tr_b16 v[92:93], v225 offset:61120
	ds_read_b64_tr_b16 v[96:97], v225 offset:61152
	s_waitcnt lgkmcnt(9)
	v_mfma_f32_16x16x32_bf16 v[114:117], v[6:9], v[82:85], v[110:113]
	s_waitcnt lgkmcnt(8)
	v_mfma_f32_16x16x32_bf16 v[82:85], v[6:9], v[86:89], v[118:121]
	s_waitcnt lgkmcnt(6)
	v_mfma_f32_16x16x32_bf16 v[86:89], v[6:9], v[74:77], v[16:19]
	s_nop 2
	v_add_co_u32_e32 v18, vcc, s4, v138
	s_waitcnt lgkmcnt(2)
	v_mfma_f32_16x16x32_bf16 v[110:113], v[6:9], v[78:81], v[20:23]
	v_addc_co_u32_e32 v19, vcc, 0, v139, vcc
	global_load_dwordx4 v[14:17], v[14:15], off
	s_nop 0
	global_load_dwordx4 v[118:121], v[18:19], off
	v_add_co_u32_e32 v18, vcc, s5, v138
	s_waitcnt lgkmcnt(1)
	v_mfma_f32_16x16x32_bf16 v[98:101], v[6:9], v[90:93], v[24:27]
	v_addc_co_u32_e32 v19, vcc, 0, v139, vcc
	v_add_co_u32_e32 v22, vcc, s15, v138
	s_waitcnt lgkmcnt(0)
	v_mfma_f32_16x16x32_bf16 v[74:77], v[6:9], v[94:97], v[28:31]
	v_addc_co_u32_e32 v23, vcc, 0, v139, vcc
	global_load_dwordx4 v[18:21], v[18:19], off
	s_nop 0
	global_load_dwordx4 v[22:25], v[22:23], off
	ds_read_b64_tr_b16 v[28:29], v225 offset:61184
	ds_read_b64_tr_b16 v[26:27], v225 offset:52480
	ds_read_b64_tr_b16 v[30:31], v225 offset:52512
	ds_read_b64_tr_b16 v[90:91], v225 offset:52544
	ds_read_b64_tr_b16 v[106:107], v225 offset:52576
	ds_read_b64_tr_b16 v[32:33], v225 offset:61216
	ds_read_b64_tr_b16 v[92:93], v225 offset:61248
	ds_read_b64_tr_b16 v[108:109], v225 offset:61280
	s_waitcnt lgkmcnt(6)
	v_mfma_f32_16x16x32_bf16 v[78:81], v[6:9], v[26:29], v[66:69]
	v_add_co_u32_e32 v26, vcc, s17, v138
	s_nop 1
	v_addc_co_u32_e32 v27, vcc, 0, v139, vcc
	s_waitcnt lgkmcnt(2)
	v_mfma_f32_16x16x32_bf16 v[102:105], v[6:9], v[30:33], v[70:73]
	v_add_co_u32_e32 v30, vcc, s18, v138
	s_nop 1
	v_addc_co_u32_e32 v31, vcc, 0, v139, vcc
	v_add_co_u32_e32 v144, vcc, s20, v138
	global_load_dwordx4 v[26:29], v[26:27], off
	s_nop 0
	global_load_dwordx4 v[30:33], v[30:31], off
	s_waitcnt lgkmcnt(1)
	v_mfma_f32_16x16x32_bf16 v[94:97], v[6:9], v[90:93], v[130:133]
	v_addc_co_u32_e32 v145, vcc, 0, v139, vcc
	v_add_co_u32_e32 v138, vcc, s21, v138
	s_waitcnt lgkmcnt(0)
	v_mfma_f32_16x16x32_bf16 v[70:73], v[6:9], v[106:109], v[134:137]
	ds_read_b64_tr_b16 v[68:69], v225 offset:61312
	ds_read_b64_tr_b16 v[66:67], v225 offset:52608
	ds_read_b64_tr_b16 v[90:91], v225 offset:52640
	ds_read_b64_tr_b16 v[106:107], v225 offset:52672
	ds_read_b64_tr_b16 v[130:131], v225 offset:52704
	ds_read_b64_tr_b16 v[92:93], v225 offset:61344
	ds_read_b64_tr_b16 v[108:109], v225 offset:61376
	ds_read_b64_tr_b16 v[132:133], v225 offset:61408
	v_addc_co_u32_e32 v139, vcc, 0, v139, vcc
	s_waitcnt lgkmcnt(2)
	v_mfma_f32_16x16x32_bf16 v[90:93], v[6:9], v[90:93], v[140:143]
	global_load_dwordx4 v[134:137], v[144:145], off
	s_nop 1
	global_load_dwordx4 v[138:141], v[138:139], off
	s_waitcnt vmcnt(7)
	ds_write_b128 v210, v[14:17]
	s_waitcnt vmcnt(6)
	ds_write_b128 v210, v[118:121] offset:8704
	s_waitcnt vmcnt(5)
	ds_write_b128 v210, v[18:21] offset:17408
	s_waitcnt vmcnt(4)
	ds_write_b128 v210, v[22:25] offset:26112
	s_waitcnt vmcnt(3)
	ds_write_b128 v210, v[26:29] offset:34816
	s_waitcnt vmcnt(2)
	ds_write_b128 v210, v[30:33] offset:43520
	s_waitcnt vmcnt(1)
	ds_write_b128 v210, v[134:137] offset:52224
	s_waitcnt vmcnt(0)
	ds_write_b128 v210, v[138:141] offset:60928
	v_mov_b32_e32 v18, v226
	s_waitcnt lgkmcnt(9)
	v_mfma_f32_16x16x32_bf16 v[106:109], v[6:9], v[106:109], v[10:13]
	s_waitcnt lgkmcnt(0)
	s_barrier
; #define LAS __attribute__((address_space(3)))
; #define MFMA16(a, b, c) __builtin_amdgcn_mfma_f32_16x16x32_bf16((a), (b), (c), 0, 0, 0)
; __device__ void ret_out_phase(LAS unsigned char* lds, const bf16_t* PROJ, const bf16_t* ST, bf16_t* MIX, const float* lgf, const float* lgb, const float* ogain) {
;     ...
;             } else if (!(s & 1)) {
;                 const int kt2 = (s - 4) >> 1;
; #pragma unroll
;                 for (int kt = 0; kt < 8; ++kt) { st[kt] = (f32x4){0.f, 0.f, 0.f, 0.f};
; #pragma unroll
;                     for (int ks = 0; ks < 8; ++ks) { const bf16x8 af = *(const LAS bf16x8*)(buf + (16 * kt + fr) * RP + (32 * ks + 8 * g) * 2); st[kt] = MFMA16(af, qf[ks], st[kt]); } }
	s_nop 0
	ds_read_b128 v[10:13], v191
	v_mfma_f32_16x16x32_bf16 v[118:121], v[6:9], v[130:133], v[2:5]
	ds_read_b128 v[14:17], v191 offset:52416
	s_nop 1
	ds_read_b128 v[2:5], v191 offset:64
	v_mfma_f32_16x16x32_bf16 v[66:69], v[6:9], v[66:69], v[146:149]
	s_waitcnt lgkmcnt(2)
	v_mfma_f32_16x16x32_bf16 v[6:9], v[10:13], v[62:65], 0
	ds_read_b128 v[10:13], v191 offset:128
	s_waitcnt lgkmcnt(1)
	v_mfma_f32_16x16x32_bf16 v[2:5], v[2:5], v[58:61], v[6:9]
	s_nop 4
	ds_read_b128 v[6:9], v191 offset:192
	s_waitcnt lgkmcnt(1)
	v_mfma_f32_16x16x32_bf16 v[2:5], v[10:13], v[54:57], v[2:5]
	ds_read_b128 v[10:13], v191 offset:256
	s_waitcnt lgkmcnt(1)
	v_mfma_f32_16x16x32_bf16 v[2:5], v[6:9], v[50:53], v[2:5]
	ds_read_b128 v[6:9], v191 offset:320
	s_waitcnt lgkmcnt(1)
	v_mfma_f32_16x16x32_bf16 v[2:5], v[10:13], v[46:49], v[2:5]
	ds_read_b128 v[10:13], v191 offset:384
	s_waitcnt lgkmcnt(1)
	v_mfma_f32_16x16x32_bf16 v[2:5], v[6:9], v[42:45], v[2:5]
	ds_read_b128 v[6:9], v191 offset:448
	s_waitcnt lgkmcnt(1)
	v_mfma_f32_16x16x32_bf16 v[2:5], v[10:13], v[38:41], v[2:5]
	ds_read_b128 v[10:13], v191 offset:8704
	s_waitcnt lgkmcnt(1)
	v_mfma_f32_16x16x32_bf16 v[130:133], v[6:9], v[34:37], v[2:5]
	s_nop 4
	ds_read_b128 v[2:5], v191 offset:8768
	s_waitcnt lgkmcnt(1)
	v_mfma_f32_16x16x32_bf16 v[6:9], v[10:13], v[62:65], 0
	ds_read_b128 v[10:13], v191 offset:8832
	s_waitcnt lgkmcnt(1)
	v_mfma_f32_16x16x32_bf16 v[2:5], v[2:5], v[58:61], v[6:9]
	s_nop 4
	ds_read_b128 v[6:9], v191 offset:8896
	s_waitcnt lgkmcnt(1)
	v_mfma_f32_16x16x32_bf16 v[2:5], v[10:13], v[54:57], v[2:5]
	ds_read_b128 v[10:13], v191 offset:8960
	s_waitcnt lgkmcnt(1)
	v_mfma_f32_16x16x32_bf16 v[2:5], v[6:9], v[50:53], v[2:5]
	ds_read_b128 v[6:9], v191 offset:9024
	s_waitcnt lgkmcnt(1)
	v_mfma_f32_16x16x32_bf16 v[2:5], v[10:13], v[46:49], v[2:5]
	ds_read_b128 v[10:13], v191 offset:9088
	s_waitcnt lgkmcnt(1)
	v_mfma_f32_16x16x32_bf16 v[2:5], v[6:9], v[42:45], v[2:5]
	ds_read_b128 v[6:9], v191 offset:9152
	s_waitcnt lgkmcnt(1)
	v_mfma_f32_16x16x32_bf16 v[2:5], v[10:13], v[38:41], v[2:5]
	ds_read_b128 v[10:13], v191 offset:17408
	s_waitcnt lgkmcnt(1)
	v_mfma_f32_16x16x32_bf16 v[134:137], v[6:9], v[34:37], v[2:5]
	s_nop 4
	ds_read_b128 v[2:5], v191 offset:17472
	s_waitcnt lgkmcnt(1)
	v_mfma_f32_16x16x32_bf16 v[6:9], v[10:13], v[62:65], 0
	ds_read_b128 v[10:13], v191 offset:17536
	s_waitcnt lgkmcnt(1)
	v_mfma_f32_16x16x32_bf16 v[2:5], v[2:5], v[58:61], v[6:9]
	s_nop 4
	ds_read_b128 v[6:9], v191 offset:17600
	s_waitcnt lgkmcnt(1)
	v_mfma_f32_16x16x32_bf16 v[2:5], v[10:13], v[54:57], v[2:5]
	ds_read_b128 v[10:13], v191 offset:17664
	s_waitcnt lgkmcnt(1)
	v_mfma_f32_16x16x32_bf16 v[2:5], v[6:9], v[50:53], v[2:5]
	ds_read_b128 v[6:9], v191 offset:17728
	s_waitcnt lgkmcnt(1)
	v_mfma_f32_16x16x32_bf16 v[2:5], v[10:13], v[46:49], v[2:5]
	ds_read_b128 v[10:13], v191 offset:17792
	s_waitcnt lgkmcnt(1)
	v_mfma_f32_16x16x32_bf16 v[2:5], v[6:9], v[42:45], v[2:5]
	ds_read_b128 v[6:9], v191 offset:17856
	s_waitcnt lgkmcnt(1)
	v_mfma_f32_16x16x32_bf16 v[2:5], v[10:13], v[38:41], v[2:5]
	ds_read_b128 v[10:13], v191 offset:26112
	s_waitcnt lgkmcnt(1)
	v_mfma_f32_16x16x32_bf16 v[138:141], v[6:9], v[34:37], v[2:5]
	s_nop 4
	ds_read_b128 v[2:5], v191 offset:26176
	s_waitcnt lgkmcnt(1)
	v_mfma_f32_16x16x32_bf16 v[6:9], v[10:13], v[62:65], 0
	ds_read_b128 v[10:13], v191 offset:26240
	s_waitcnt lgkmcnt(1)
	v_mfma_f32_16x16x32_bf16 v[2:5], v[2:5], v[58:61], v[6:9]
	s_nop 4
	ds_read_b128 v[6:9], v191 offset:26304
	s_waitcnt lgkmcnt(1)
	v_mfma_f32_16x16x32_bf16 v[2:5], v[10:13], v[54:57], v[2:5]
	ds_read_b128 v[10:13], v191 offset:26368
	s_waitcnt lgkmcnt(1)
	v_mfma_f32_16x16x32_bf16 v[2:5], v[6:9], v[50:53], v[2:5]
	ds_read_b128 v[6:9], v191 offset:26432
	s_waitcnt lgkmcnt(1)
	v_mfma_f32_16x16x32_bf16 v[2:5], v[10:13], v[46:49], v[2:5]
	ds_read_b128 v[10:13], v191 offset:26496
	s_waitcnt lgkmcnt(1)
	v_mfma_f32_16x16x32_bf16 v[2:5], v[6:9], v[42:45], v[2:5]
	ds_read_b128 v[6:9], v191 offset:26560
	s_waitcnt lgkmcnt(1)
	v_mfma_f32_16x16x32_bf16 v[2:5], v[10:13], v[38:41], v[2:5]
	ds_read_b128 v[10:13], v191 offset:34816
	s_waitcnt lgkmcnt(1)
	v_mfma_f32_16x16x32_bf16 v[142:145], v[6:9], v[34:37], v[2:5]
	s_nop 4
	ds_read_b128 v[2:5], v191 offset:34880
	s_waitcnt lgkmcnt(1)
	v_mfma_f32_16x16x32_bf16 v[6:9], v[10:13], v[62:65], 0
	ds_read_b128 v[10:13], v191 offset:34944
	s_waitcnt lgkmcnt(1)
	v_mfma_f32_16x16x32_bf16 v[2:5], v[2:5], v[58:61], v[6:9]
	s_nop 4
	ds_read_b128 v[6:9], v191 offset:35008
	s_waitcnt lgkmcnt(1)
	v_mfma_f32_16x16x32_bf16 v[2:5], v[10:13], v[54:57], v[2:5]
	ds_read_b128 v[10:13], v191 offset:35072
	s_waitcnt lgkmcnt(1)
	v_mfma_f32_16x16x32_bf16 v[2:5], v[6:9], v[50:53], v[2:5]
	ds_read_b128 v[6:9], v191 offset:35136
	s_waitcnt lgkmcnt(1)
	v_mfma_f32_16x16x32_bf16 v[2:5], v[10:13], v[46:49], v[2:5]
	ds_read_b128 v[10:13], v191 offset:35200
	s_waitcnt lgkmcnt(1)
; #define LAS __attribute__((address_space(3)))
; #define MFMA16(a, b, c) __builtin_amdgcn_mfma_f32_16x16x32_bf16((a), (b), (c), 0, 0, 0)
; __device__ void ret_out_phase(LAS unsigned char* lds, const bf16_t* PROJ, const bf16_t* ST, bf16_t* MIX, const float* lgf, const float* lgb, const float* ogain) {
;     ...
;             } else if (!(s & 1)) {
;                 const int kt2 = (s - 4) >> 1;
; #pragma unroll
;                 for (int kt = 0; kt < 8; ++kt) { st[kt] = (f32x4){0.f, 0.f, 0.f, 0.f};
; #pragma unroll
;                     for (int ks = 0; ks < 8; ++ks) { const bf16x8 af = *(const LAS bf16x8*)(buf + (16 * kt + fr) * RP + (32 * ks + 8 * g) * 2); st[kt] = MFMA16(af, qf[ks], st[kt]); } }
;                 const int ql = half * 128 + 16 * wave + fr;
; #pragma unroll
;                 for (int kt = 0; kt < 8; ++kt)
; #pragma unroll
;                     for (int j = 0; j < 4; ++j) { const int kl = kt2 * 128 + 16 * kt + 4 * g + j; const int d = ql - kl;
;                         const float w = d > 0 ? __expf(lf * (float)d) : (d < 0 ? __expf(lb * (float)(-d)) : 2.0f); st[kt][j] *= w; }
	v_mfma_f32_16x16x32_bf16 v[2:5], v[6:9], v[42:45], v[2:5]
	ds_read_b128 v[6:9], v191 offset:35264
	s_waitcnt lgkmcnt(1)
	v_mfma_f32_16x16x32_bf16 v[2:5], v[10:13], v[38:41], v[2:5]
	ds_read_b128 v[10:13], v191 offset:43520
	s_waitcnt lgkmcnt(1)
	v_mfma_f32_16x16x32_bf16 v[146:149], v[6:9], v[34:37], v[2:5]
	s_nop 4
	ds_read_b128 v[2:5], v191 offset:43584
	s_waitcnt lgkmcnt(1)
	v_mfma_f32_16x16x32_bf16 v[6:9], v[10:13], v[62:65], 0
	ds_read_b128 v[10:13], v191 offset:43648
	s_waitcnt lgkmcnt(1)
	v_mfma_f32_16x16x32_bf16 v[2:5], v[2:5], v[58:61], v[6:9]
	s_nop 4
	ds_read_b128 v[6:9], v191 offset:43712
	s_waitcnt lgkmcnt(1)
	v_mfma_f32_16x16x32_bf16 v[2:5], v[10:13], v[54:57], v[2:5]
	ds_read_b128 v[10:13], v191 offset:43776
	s_waitcnt lgkmcnt(1)
	v_mfma_f32_16x16x32_bf16 v[2:5], v[6:9], v[50:53], v[2:5]
	ds_read_b128 v[6:9], v191 offset:43840
	s_waitcnt lgkmcnt(1)
	v_mfma_f32_16x16x32_bf16 v[2:5], v[10:13], v[46:49], v[2:5]
	ds_read_b128 v[10:13], v191 offset:43904
	s_waitcnt lgkmcnt(1)
	v_mfma_f32_16x16x32_bf16 v[2:5], v[6:9], v[42:45], v[2:5]
	ds_read_b128 v[6:9], v191 offset:43968
	s_waitcnt lgkmcnt(1)
	v_mfma_f32_16x16x32_bf16 v[2:5], v[10:13], v[38:41], v[2:5]
	ds_read_b128 v[10:13], v191 offset:52224
	s_waitcnt lgkmcnt(1)
	v_mfma_f32_16x16x32_bf16 v[150:153], v[6:9], v[34:37], v[2:5]
	ds_read_b128 v[6:9], v191 offset:52352
	s_nop 3
	ds_read_b128 v[2:5], v191 offset:52288
	s_waitcnt lgkmcnt(2)
	v_mfma_f32_16x16x32_bf16 v[10:13], v[10:13], v[62:65], 0
	s_waitcnt lgkmcnt(0)
	v_mfma_f32_16x16x32_bf16 v[2:5], v[2:5], v[58:61], v[10:13]
	s_nop 5
	v_lshlrev_b32_e32 v10, 4, v18
	v_ashrrev_i32_e32 v11, 31, v10
	v_mfma_f32_16x16x32_bf16 v[2:5], v[6:9], v[54:57], v[2:5]
	ds_read_b128 v[6:9], v191 offset:52480
	v_lshl_add_u64 v[158:159], s[0:1], 0, v[10:11]
	ds_read_b128 v[10:13], v191 offset:52544
	v_mfma_f32_16x16x32_bf16 v[2:5], v[14:17], v[50:53], v[2:5]
	ds_read_b128 v[14:17], v191 offset:52608
	ds_read_b128 v[18:21], v191 offset:52672
	v_add_co_u32_e32 v22, vcc, s33, v158
	s_waitcnt lgkmcnt(3)
	v_mfma_f32_16x16x32_bf16 v[2:5], v[6:9], v[46:49], v[2:5]
	v_addc_co_u32_e32 v23, vcc, 0, v159, vcc
	v_add_co_u32_e32 v6, vcc, s4, v158
	s_waitcnt lgkmcnt(2)
	v_mfma_f32_16x16x32_bf16 v[10:13], v[10:13], v[42:45], v[2:5]
	v_addc_co_u32_e32 v7, vcc, 0, v159, vcc
	s_nop 2
	global_load_dwordx4 v[2:5], v[22:23], off
	s_nop 0
	global_load_dwordx4 v[6:9], v[6:7], off
	s_waitcnt lgkmcnt(1)
	v_mfma_f32_16x16x32_bf16 v[10:13], v[14:17], v[38:41], v[10:13]
	ds_read_b128 v[14:17], v191 offset:60928
	ds_read_b128 v[26:29], v191 offset:61056
	v_add_co_u32_e32 v30, vcc, s5, v158
	s_waitcnt lgkmcnt(2)
	v_mfma_f32_16x16x32_bf16 v[154:157], v[18:21], v[34:37], v[10:13]
	ds_read_b128 v[18:21], v191 offset:60992
	v_addc_co_u32_e32 v31, vcc, 0, v159, vcc
	s_waitcnt lgkmcnt(2)
	v_mfma_f32_16x16x32_bf16 v[22:25], v[14:17], v[62:65], 0
	v_add_co_u32_e32 v32, vcc, s15, v158
	s_nop 1
	v_addc_co_u32_e32 v33, vcc, 0, v159, vcc
	global_load_dwordx4 v[10:13], v[30:31], off
	global_load_dwordx4 v[14:17], v[32:33], off
	s_waitcnt lgkmcnt(0)
	v_mfma_f32_16x16x32_bf16 v[18:21], v[18:21], v[58:61], v[22:25]
	v_add_co_u32_e32 v58, vcc, s17, v158
	s_nop 1
	ds_read_b128 v[22:25], v191 offset:61120
	v_mfma_f32_16x16x32_bf16 v[18:21], v[26:29], v[54:57], v[18:21]
	ds_read_b128 v[26:29], v191 offset:61184
	v_addc_co_u32_e32 v59, vcc, 0, v159, vcc
	s_waitcnt lgkmcnt(1)
	v_mfma_f32_16x16x32_bf16 v[30:33], v[22:25], v[50:53], v[18:21]
	ds_read_b128 v[50:53], v191 offset:61248
	v_add_co_u32_e32 v54, vcc, s18, v158
	s_waitcnt lgkmcnt(1)
	v_mfma_f32_16x16x32_bf16 v[26:29], v[26:29], v[46:49], v[30:33]
	v_addc_co_u32_e32 v55, vcc, 0, v159, vcc
	global_load_dwordx4 v[18:21], v[58:59], off
	global_load_dwordx4 v[22:25], v[54:55], off
	s_nop 0
	ds_read_b128 v[30:33], v191 offset:61312
	s_waitcnt lgkmcnt(1)
	v_mfma_f32_16x16x32_bf16 v[26:29], v[50:53], v[42:45], v[26:29]
	v_add_co_u32_e32 v46, vcc, s20, v158
	ds_read_b128 v[42:45], v191 offset:61376
	s_nop 0
	v_addc_co_u32_e32 v47, vcc, 0, v159, vcc
	v_add_co_u32_e32 v48, vcc, s21, v158
	s_waitcnt lgkmcnt(1)
	v_mfma_f32_16x16x32_bf16 v[38:41], v[30:33], v[38:41], v[26:29]
	v_addc_co_u32_e32 v49, vcc, 0, v159, vcc
	s_nop 1
	global_load_dwordx4 v[26:29], v[46:47], off
	global_load_dwordx4 v[30:33], v[48:49], off
	s_waitcnt lgkmcnt(0)
	v_mfma_f32_16x16x32_bf16 v[34:37], v[42:45], v[34:37], v[38:41]
	s_nop 2
	v_or_b32_e32 v38, 0x80, v190
	v_sub_u32_e32 v39, v0, v38
	v_cmp_gt_i32_e32 vcc, 1, v39
	s_and_saveexec_b64 s[0:1], vcc
	s_xor_b64 s[0:1], exec, s[0:1]
	s_cbranch_execz .LBB0_165
	v_sub_u32_e32 v38, 0, v39
	v_cvt_f32_u32_e32 v38, v38
	v_or_b32_e32 v39, 0x80, v190
	v_cmp_ne_u32_e32 vcc, v0, v39
	v_mul_f32_e32 v38, v185, v38
	v_mul_f32_e32 v38, 0x3fb8aa3b, v38
	v_exp_f32_e32 v38, v38
	s_nop 0
	v_cndmask_b32_e32 v38, 2.0, v38, vcc

; #define LAS __attribute__((address_space(3)))
; #define RET_ISSUE(s_, it_) do { const bf16_t* bp_; int pt_; RET_SRC(s_, it_, bp_, pt_); const int tv_ = otid(); const char* sb_ = (const char*)bp_ + (size_t)(((tv_ >> 5) * pt_ + (tv_ & 31) * 8) * 2); const size_t step_ = (size_t)pt_ * 32; \
;         _Pragma("unroll") for (int i_ = 0; i_ < 8; ++i_) stg[i_] = *(const u32x4*)(sb_ + i_ * step_); } while (0)
; __device__ void ret_out_phase(LAS unsigned char* lds, const bf16_t* PROJ, const bf16_t* ST, bf16_t* MIX, const float* lgf, const float* lgb, const float* ogain) {
;     ...
;         for (int s = 0; s < 8; ++s) {
;             LAS unsigned char* buf = lds + (s & 1) * BUFB;
; #pragma unroll
;             for (int i = 0; i < 8; ++i) *(LAS u32x4*)(buf + ((tid >> 5) + 16 * i) * RP + (tid & 31) * 16) = stg[i];
;             __syncthreads();
;             if (s < 7) { RET_ISSUE(s + 1, ri); }
;             else if (item + (int)gridDim.x < 768) { const RetItem rn = ret_decode(item + gridDim.x); RET_ISSUE(0, rn); }
.LBB0_291:
	s_or_b64 exec, exec, s[0:1]
	s_waitcnt vmcnt(7)
	ds_write_b128 v211, v[2:5]
	s_waitcnt vmcnt(6)
	ds_write_b128 v211, v[6:9] offset:8704
	s_waitcnt vmcnt(5)
	ds_write_b128 v211, v[10:13] offset:17408
	s_waitcnt vmcnt(4)
	ds_write_b128 v211, v[14:17] offset:26112
	s_waitcnt vmcnt(3)
	ds_write_b128 v211, v[18:21] offset:34816
	s_waitcnt vmcnt(2)
	ds_write_b128 v211, v[22:25] offset:43520
	s_waitcnt vmcnt(1)
	ds_write_b128 v211, v[26:29] offset:52224
	s_waitcnt vmcnt(0)
	ds_write_b128 v211, v[30:33] offset:60928
	s_waitcnt lgkmcnt(0)
	s_barrier
	s_load_dword s0, s[68:69], 0x10
	s_waitcnt lgkmcnt(0)
	s_lshr_b32 s0, s0, 16
	s_cmp_lg_u32 s0, 0
	s_cselect_b64 s[0:1], -1, 0
	s_cmp_lg_u64 s[0:1], 0
	s_addc_u32 s0, s14, s10
	s_cmpk_gt_i32 s0, 0x2ff
	s_cbranch_scc1 .LBB0_34
	s_ashr_i32 s1, s0, 1
	s_and_b32 s1, s1, -8
	s_and_b32 s0, s0, 7
	s_or_b32 s0, s1, s0
	s_ashr_i32 s1, s0, 31
	v_mov_b32_e32 v0, v226
	s_lshl_b64 s[0:1], s[0:1], 17
	s_add_u32 s0, s84, s0
	v_lshlrev_b32_e32 v2, 4, v0
	s_addc_u32 s1, s85, s1
	v_ashrrev_i32_e32 v3, 31, v2
	v_lshl_add_u64 v[26:27], s[0:1], 0, v[2:3]
	s_movk_i32 s0, 0x2000
	v_add_co_u32_e32 v6, vcc, s0, v26
	s_movk_i32 s0, 0x4000
	s_nop 0
	v_addc_co_u32_e32 v7, vcc, 0, v27, vcc
	v_add_co_u32_e32 v10, vcc, s0, v26
	s_movk_i32 s0, 0x6000
	s_nop 0
	v_addc_co_u32_e32 v11, vcc, 0, v27, vcc
	v_add_co_u32_e32 v14, vcc, s0, v26
	global_load_dwordx4 v[2:5], v[26:27], off
	s_nop 0
	global_load_dwordx4 v[6:9], v[6:7], off
	v_addc_co_u32_e32 v15, vcc, 0, v27, vcc
	v_add_co_u32_e32 v18, vcc, 0x8000, v26
	global_load_dwordx4 v[10:13], v[10:11], off
	s_nop 0
	global_load_dwordx4 v[14:17], v[14:15], off
	v_addc_co_u32_e32 v19, vcc, 0, v27, vcc
	v_add_co_u32_e32 v22, vcc, 0xa000, v26
	s_nop 1
	v_addc_co_u32_e32 v23, vcc, 0, v27, vcc
	v_add_co_u32_e32 v28, vcc, 0xc000, v26
	global_load_dwordx4 v[18:21], v[18:19], off
	s_nop 0
	global_load_dwordx4 v[22:25], v[22:23], off
	v_addc_co_u32_e32 v29, vcc, 0, v27, vcc
	v_add_co_u32_e32 v30, vcc, 0xe000, v26
	s_nop 1
	v_addc_co_u32_e32 v31, vcc, 0, v27, vcc
	global_load_dwordx4 v[26:29], v[28:29], off
	s_nop 0
	global_load_dwordx4 v[30:33], v[30:31], off
	s_branch .LBB0_34
